# UP epilogue: thread->(row,chunk) remap, a 32-lane LDS group reads 8 rows x 4 chunks of the C tile (conflict-free) instead of 2 rows x 16 chunks
# baseline (speedup 1.0000x reference)
.LBB0_338:
	s_lshr_b32 s8, s13, 2
	s_and_b32 s10, s16, 56
	s_and_b32 s8, s8, 0x1ffffc0
	s_or_b32 s10, s10, s3
	s_or_b32 s8, s10, s8
	s_lshl_b32 s8, s8, 7
	s_lshl_b64 s[24:25], s[8:9], 11
	v_lshl_add_u64 v[78:79], v[68:69], 0, s[24:25]
	v_add_co_u32_e32 v80, vcc, s18, v78
	s_and_b32 s10, s14, 0xf80
	s_nop 0
	v_addc_co_u32_e32 v81, vcc, 0, v79, vcc
	s_lshl_b32 s26, s10, 11
	s_mov_b32 s27, s9
	v_add_co_u32_e32 v82, vcc, s19, v78
	v_lshl_add_u64 v[76:77], v[70:71], 0, s[26:27]
	s_nop 0
	v_addc_co_u32_e32 v83, vcc, 0, v79, vcc
	v_add_co_u32_e32 v84, vcc, s18, v76
	global_load_dwordx4 v[2:5], v[78:79], off
	global_load_dwordx4 v[6:9], v[80:81], off
	v_addc_co_u32_e32 v85, vcc, 0, v77, vcc
	v_add_co_u32_e32 v86, vcc, s19, v76
	global_load_dwordx4 v[10:13], v[82:83], off
	global_load_dwordx4 v[14:17], v[76:77], off
	v_addc_co_u32_e32 v87, vcc, 0, v77, vcc
	global_load_dwordx4 v[18:21], v[84:85], off
	global_load_dwordx4 v[22:25], v[86:87], off
	v_add_co_u32_e32 v88, vcc, s20, v76
	s_nop 1
	v_addc_co_u32_e32 v89, vcc, 0, v77, vcc
	global_load_dwordx4 v[26:29], v[88:89], off
	v_add_co_u32_e32 v90, vcc, s20, v78
	s_nop 1
	v_addc_co_u32_e32 v91, vcc, 0, v79, vcc
	global_load_dwordx4 v[30:33], v[90:91], off
	global_load_dwordx4 v[148:151], v[76:77], off offset:128
	global_load_dwordx4 v[152:155], v[84:85], off offset:128
	global_load_dwordx4 v[156:159], v[86:87], off offset:128
	global_load_dwordx4 v[160:163], v[88:89], off offset:128
	global_load_dwordx4 v[164:167], v[78:79], off offset:128
	global_load_dwordx4 v[168:171], v[80:81], off offset:128
	global_load_dwordx4 v[172:175], v[82:83], off offset:128
	global_load_dwordx4 v[176:179], v[90:91], off offset:128
	s_waitcnt vmcnt(12)
	ds_write_b128 v1, v[14:17] offset:36864
	s_waitcnt vmcnt(11)
	ds_write_b128 v1, v[18:21] offset:41472
	s_waitcnt vmcnt(10)
	ds_write_b128 v1, v[22:25] offset:46080
	s_waitcnt vmcnt(9)
	ds_write_b128 v1, v[26:29] offset:50688
	ds_write_b128 v1, v[2:5]
	ds_write_b128 v1, v[6:9] offset:4608
	ds_write_b128 v1, v[10:13] offset:9216
	s_waitcnt vmcnt(8)
	ds_write_b128 v1, v[30:33] offset:13824
	s_waitcnt lgkmcnt(0)
	s_barrier
	global_load_dwordx4 v[180:183], v[80:81], off offset:256
	global_load_dwordx4 v[184:187], v[82:83], off offset:256
	global_load_dwordx4 v[188:191], v[78:79], off offset:256
	global_load_dwordx4 v[192:195], v[76:77], off offset:256
	global_load_dwordx4 v[196:199], v[90:91], off offset:256
	global_load_dwordx4 v[200:203], v[84:85], off offset:256
	global_load_dwordx4 v[204:207], v[86:87], off offset:256
	global_load_dwordx4 v[208:211], v[88:89], off offset:256
	ds_read_b128 v[18:21], v72
	ds_read_b128 v[34:37], v73 offset:36864
	ds_read_b128 v[212:215], v72 offset:32
	ds_read_b128 v[216:219], v73 offset:36896
	ds_read_b128 v[50:53], v73 offset:41472
	ds_read_b128 v[220:223], v73 offset:41504
	ds_read_b128 v[54:57], v72 offset:4608
	ds_read_b128 v[224:227], v72 offset:4640
	s_waitcnt lgkmcnt(6)
	v_mfma_f32_32x32x16_bf16 v[2:17], v[18:21], v[34:37], 0
	s_waitcnt lgkmcnt(3)
	v_mfma_f32_32x32x16_bf16 v[18:33], v[18:21], v[50:53], 0
	s_waitcnt lgkmcnt(1)
	v_mfma_f32_32x32x16_bf16 v[34:49], v[54:57], v[34:37], 0
	v_mfma_f32_32x32x16_bf16 v[50:65], v[54:57], v[50:53], 0
	v_mfma_f32_32x32x16_bf16 v[2:17], v[212:215], v[216:219], v[2:17]
	v_mfma_f32_32x32x16_bf16 v[18:33], v[212:215], v[220:223], v[18:33]
	s_waitcnt lgkmcnt(0)
	v_mfma_f32_32x32x16_bf16 v[34:49], v[224:227], v[216:219], v[34:49]
	v_mfma_f32_32x32x16_bf16 v[50:65], v[224:227], v[220:223], v[50:65]
	ds_read_b128 v[212:215], v72 offset:64
	ds_read_b128 v[216:219], v73 offset:36928
	ds_read_b128 v[220:223], v72 offset:96
	ds_read_b128 v[224:227], v73 offset:36960
	ds_read_b128 v[228:231], v73 offset:41536
	ds_read_b128 v[232:235], v73 offset:41568
	s_waitcnt lgkmcnt(4)
	v_mfma_f32_32x32x16_bf16 v[2:17], v[212:215], v[216:219], v[2:17]
	s_waitcnt lgkmcnt(1)
	v_mfma_f32_32x32x16_bf16 v[18:33], v[212:215], v[228:231], v[18:33]
	ds_read_b128 v[212:215], v72 offset:4672
	ds_read_b128 v[236:239], v72 offset:4704
	s_waitcnt vmcnt(11)
	ds_write_b128 v1, v[164:167] offset:18432
	s_waitcnt vmcnt(10)
	ds_write_b128 v1, v[168:171] offset:23040
	s_waitcnt vmcnt(9)
	ds_write_b128 v1, v[172:175] offset:27648
	s_waitcnt vmcnt(8)
	ds_write_b128 v1, v[176:179] offset:32256
	ds_write_b128 v1, v[148:151] offset:55296
	ds_write_b128 v1, v[152:155] offset:59904
	ds_write_b128 v1, v[156:159] offset:64512
	ds_write_b128 v92, v[160:163] offset:32256
	global_load_dwordx4 v[148:151], v[80:81], off offset:384
	global_load_dwordx4 v[152:155], v[82:83], off offset:384
	global_load_dwordx4 v[156:159], v[78:79], off offset:384
	global_load_dwordx4 v[160:163], v[76:77], off offset:384
	global_load_dwordx4 v[164:167], v[90:91], off offset:384
	global_load_dwordx4 v[168:171], v[84:85], off offset:384
	global_load_dwordx4 v[172:175], v[86:87], off offset:384
	global_load_dwordx4 v[176:179], v[88:89], off offset:384
	s_waitcnt lgkmcnt(0)
	s_barrier
	v_mfma_f32_32x32x16_bf16 v[34:49], v[212:215], v[216:219], v[34:49]
	v_mfma_f32_32x32x16_bf16 v[50:65], v[212:215], v[228:231], v[50:65]
	v_mfma_f32_32x32x16_bf16 v[2:17], v[220:223], v[224:227], v[2:17]
	v_mfma_f32_32x32x16_bf16 v[18:33], v[220:223], v[232:235], v[18:33]
	v_mfma_f32_32x32x16_bf16 v[34:49], v[236:239], v[224:227], v[34:49]
	v_mfma_f32_32x32x16_bf16 v[50:65], v[236:239], v[232:235], v[50:65]
	ds_read_b128 v[212:215], v72 offset:18432
	ds_read_b128 v[216:219], v73 offset:55296
	ds_read_b128 v[220:223], v72 offset:18464
	ds_read_b128 v[224:227], v73 offset:55328
	ds_read_b128 v[228:231], v73 offset:59904
	ds_read_b128 v[232:235], v73 offset:59936
	s_waitcnt lgkmcnt(4)
	v_mfma_f32_32x32x16_bf16 v[2:17], v[212:215], v[216:219], v[2:17]
	s_waitcnt lgkmcnt(1)
	v_mfma_f32_32x32x16_bf16 v[18:33], v[212:215], v[228:231], v[18:33]
	ds_read_b128 v[212:215], v72 offset:23040
	ds_read_b128 v[236:239], v72 offset:23072
	s_waitcnt lgkmcnt(1)
	v_mfma_f32_32x32x16_bf16 v[34:49], v[212:215], v[216:219], v[34:49]
	v_mfma_f32_32x32x16_bf16 v[50:65], v[212:215], v[228:231], v[50:65]
	v_mfma_f32_32x32x16_bf16 v[2:17], v[220:223], v[224:227], v[2:17]
	v_mfma_f32_32x32x16_bf16 v[18:33], v[220:223], v[232:235], v[18:33]
	s_waitcnt lgkmcnt(0)
	v_mfma_f32_32x32x16_bf16 v[34:49], v[236:239], v[224:227], v[34:49]
	ds_read_b128 v[212:215], v72 offset:18496
	ds_read_b128 v[216:219], v73 offset:55360
	ds_read_b128 v[220:223], v72 offset:18528
	ds_read_b128 v[224:227], v73 offset:55392
	v_mfma_f32_32x32x16_bf16 v[50:65], v[236:239], v[232:235], v[50:65]
	ds_read_b128 v[228:231], v73 offset:59968
	ds_read_b128 v[232:235], v73 offset:60000
	s_waitcnt lgkmcnt(4)
	v_mfma_f32_32x32x16_bf16 v[2:17], v[212:215], v[216:219], v[2:17]
	s_waitcnt lgkmcnt(1)
	v_mfma_f32_32x32x16_bf16 v[18:33], v[212:215], v[228:231], v[18:33]
	ds_read_b128 v[212:215], v72 offset:23104
	ds_read_b128 v[236:239], v72 offset:23136
	s_waitcnt vmcnt(13)
	ds_write_b128 v1, v[188:191]
	ds_write_b128 v1, v[180:183] offset:4608
	ds_write_b128 v1, v[184:187] offset:9216
	s_waitcnt vmcnt(11)
	ds_write_b128 v1, v[196:199] offset:13824
	ds_write_b128 v1, v[192:195] offset:36864
	s_waitcnt vmcnt(10)
	ds_write_b128 v1, v[200:203] offset:41472
	s_waitcnt vmcnt(9)
	ds_write_b128 v1, v[204:207] offset:46080
	s_waitcnt vmcnt(8)
	ds_write_b128 v1, v[208:211] offset:50688
	global_load_dwordx4 v[180:183], v[80:81], off offset:512
	global_load_dwordx4 v[184:187], v[82:83], off offset:512
	global_load_dwordx4 v[188:191], v[78:79], off offset:512
	global_load_dwordx4 v[192:195], v[76:77], off offset:512
	global_load_dwordx4 v[196:199], v[90:91], off offset:512
	global_load_dwordx4 v[200:203], v[84:85], off offset:512
	global_load_dwordx4 v[204:207], v[86:87], off offset:512
	global_load_dwordx4 v[208:211], v[88:89], off offset:512
	s_waitcnt lgkmcnt(0)
	s_barrier
	v_mfma_f32_32x32x16_bf16 v[34:49], v[212:215], v[216:219], v[34:49]
	v_mfma_f32_32x32x16_bf16 v[50:65], v[212:215], v[228:231], v[50:65]
	v_mfma_f32_32x32x16_bf16 v[2:17], v[220:223], v[224:227], v[2:17]
	v_mfma_f32_32x32x16_bf16 v[18:33], v[220:223], v[232:235], v[18:33]
	v_mfma_f32_32x32x16_bf16 v[34:49], v[236:239], v[224:227], v[34:49]
	v_mfma_f32_32x32x16_bf16 v[50:65], v[236:239], v[232:235], v[50:65]
	ds_read_b128 v[212:215], v72
	ds_read_b128 v[216:219], v73 offset:36864
	ds_read_b128 v[220:223], v72 offset:32
	ds_read_b128 v[224:227], v73 offset:36896
	ds_read_b128 v[228:231], v73 offset:41472
	ds_read_b128 v[232:235], v73 offset:41504
	s_waitcnt lgkmcnt(4)
	v_mfma_f32_32x32x16_bf16 v[2:17], v[212:215], v[216:219], v[2:17]
	s_waitcnt lgkmcnt(1)
	v_mfma_f32_32x32x16_bf16 v[18:33], v[212:215], v[228:231], v[18:33]
	ds_read_b128 v[212:215], v72 offset:4608
	ds_read_b128 v[236:239], v72 offset:4640
	s_waitcnt lgkmcnt(1)
	v_mfma_f32_32x32x16_bf16 v[34:49], v[212:215], v[216:219], v[34:49]
	v_mfma_f32_32x32x16_bf16 v[50:65], v[212:215], v[228:231], v[50:65]
	v_mfma_f32_32x32x16_bf16 v[2:17], v[220:223], v[224:227], v[2:17]
	v_mfma_f32_32x32x16_bf16 v[18:33], v[220:223], v[232:235], v[18:33]
	s_waitcnt lgkmcnt(0)
	v_mfma_f32_32x32x16_bf16 v[34:49], v[236:239], v[224:227], v[34:49]
	ds_read_b128 v[212:215], v72 offset:64
	ds_read_b128 v[216:219], v73 offset:36928
	ds_read_b128 v[220:223], v72 offset:96
	ds_read_b128 v[224:227], v73 offset:36960
	v_mfma_f32_32x32x16_bf16 v[50:65], v[236:239], v[232:235], v[50:65]
	ds_read_b128 v[228:231], v73 offset:41536
	ds_read_b128 v[232:235], v73 offset:41568
	s_waitcnt lgkmcnt(4)
	v_mfma_f32_32x32x16_bf16 v[2:17], v[212:215], v[216:219], v[2:17]
	s_waitcnt lgkmcnt(1)
	v_mfma_f32_32x32x16_bf16 v[18:33], v[212:215], v[228:231], v[18:33]
	ds_read_b128 v[212:215], v72 offset:4672
	ds_read_b128 v[236:239], v72 offset:4704
	s_waitcnt vmcnt(13)
	ds_write_b128 v1, v[156:159] offset:18432
	ds_write_b128 v1, v[148:151] offset:23040
	ds_write_b128 v1, v[152:155] offset:27648
	s_waitcnt vmcnt(11)
	ds_write_b128 v1, v[164:167] offset:32256
	ds_write_b128 v1, v[160:163] offset:55296
	s_waitcnt vmcnt(10)
	ds_write_b128 v1, v[168:171] offset:59904
	s_waitcnt vmcnt(9)
	ds_write_b128 v1, v[172:175] offset:64512
	s_waitcnt vmcnt(8)
	ds_write_b128 v92, v[176:179] offset:32256
	global_load_dwordx4 v[148:151], v[80:81], off offset:640
	global_load_dwordx4 v[152:155], v[82:83], off offset:640
	global_load_dwordx4 v[156:159], v[78:79], off offset:640
	global_load_dwordx4 v[160:163], v[76:77], off offset:640
	global_load_dwordx4 v[164:167], v[90:91], off offset:640
	global_load_dwordx4 v[168:171], v[84:85], off offset:640
	global_load_dwordx4 v[172:175], v[86:87], off offset:640
	global_load_dwordx4 v[176:179], v[88:89], off offset:640
	s_waitcnt lgkmcnt(0)
	s_barrier
	v_mfma_f32_32x32x16_bf16 v[34:49], v[212:215], v[216:219], v[34:49]
	v_mfma_f32_32x32x16_bf16 v[50:65], v[212:215], v[228:231], v[50:65]
	v_mfma_f32_32x32x16_bf16 v[2:17], v[220:223], v[224:227], v[2:17]
	v_mfma_f32_32x32x16_bf16 v[18:33], v[220:223], v[232:235], v[18:33]
	v_mfma_f32_32x32x16_bf16 v[34:49], v[236:239], v[224:227], v[34:49]
	v_mfma_f32_32x32x16_bf16 v[50:65], v[236:239], v[232:235], v[50:65]
	ds_read_b128 v[212:215], v72 offset:18432
	ds_read_b128 v[216:219], v73 offset:55296
	ds_read_b128 v[220:223], v72 offset:18464
	ds_read_b128 v[224:227], v73 offset:55328
	ds_read_b128 v[228:231], v73 offset:59904
	ds_read_b128 v[232:235], v73 offset:59936
	s_waitcnt lgkmcnt(4)
	v_mfma_f32_32x32x16_bf16 v[2:17], v[212:215], v[216:219], v[2:17]
	s_waitcnt lgkmcnt(1)
	v_mfma_f32_32x32x16_bf16 v[18:33], v[212:215], v[228:231], v[18:33]
	ds_read_b128 v[212:215], v72 offset:23040
	ds_read_b128 v[236:239], v72 offset:23072
	s_waitcnt lgkmcnt(1)
	v_mfma_f32_32x32x16_bf16 v[34:49], v[212:215], v[216:219], v[34:49]
	v_mfma_f32_32x32x16_bf16 v[50:65], v[212:215], v[228:231], v[50:65]
	v_mfma_f32_32x32x16_bf16 v[2:17], v[220:223], v[224:227], v[2:17]
	v_mfma_f32_32x32x16_bf16 v[18:33], v[220:223], v[232:235], v[18:33]
	s_waitcnt lgkmcnt(0)
	v_mfma_f32_32x32x16_bf16 v[34:49], v[236:239], v[224:227], v[34:49]
	ds_read_b128 v[212:215], v72 offset:18496
	ds_read_b128 v[216:219], v73 offset:55360
	ds_read_b128 v[220:223], v72 offset:18528
	ds_read_b128 v[224:227], v73 offset:55392
	v_mfma_f32_32x32x16_bf16 v[50:65], v[236:239], v[232:235], v[50:65]
	ds_read_b128 v[228:231], v73 offset:59968
	ds_read_b128 v[232:235], v73 offset:60000
	s_waitcnt lgkmcnt(4)
	v_mfma_f32_32x32x16_bf16 v[2:17], v[212:215], v[216:219], v[2:17]
	s_waitcnt lgkmcnt(1)
	v_mfma_f32_32x32x16_bf16 v[18:33], v[212:215], v[228:231], v[18:33]
	ds_read_b128 v[212:215], v72 offset:23104
	ds_read_b128 v[236:239], v72 offset:23136
	s_waitcnt vmcnt(13)
	ds_write_b128 v1, v[188:191]
	ds_write_b128 v1, v[180:183] offset:4608
	ds_write_b128 v1, v[184:187] offset:9216
	s_waitcnt vmcnt(11)
	ds_write_b128 v1, v[196:199] offset:13824
	ds_write_b128 v1, v[192:195] offset:36864
	s_waitcnt vmcnt(10)
	ds_write_b128 v1, v[200:203] offset:41472
	s_waitcnt vmcnt(9)
	ds_write_b128 v1, v[204:207] offset:46080
	s_waitcnt vmcnt(8)
	ds_write_b128 v1, v[208:211] offset:50688
	global_load_dwordx4 v[180:183], v[80:81], off offset:768
	global_load_dwordx4 v[184:187], v[82:83], off offset:768
	global_load_dwordx4 v[188:191], v[78:79], off offset:768
	global_load_dwordx4 v[192:195], v[76:77], off offset:768
	global_load_dwordx4 v[196:199], v[90:91], off offset:768
	global_load_dwordx4 v[200:203], v[84:85], off offset:768
	global_load_dwordx4 v[204:207], v[86:87], off offset:768
	global_load_dwordx4 v[208:211], v[88:89], off offset:768
	s_waitcnt lgkmcnt(0)
	s_barrier
	v_mfma_f32_32x32x16_bf16 v[34:49], v[212:215], v[216:219], v[34:49]
	v_mfma_f32_32x32x16_bf16 v[50:65], v[212:215], v[228:231], v[50:65]
	v_mfma_f32_32x32x16_bf16 v[2:17], v[220:223], v[224:227], v[2:17]
	v_mfma_f32_32x32x16_bf16 v[18:33], v[220:223], v[232:235], v[18:33]
	v_mfma_f32_32x32x16_bf16 v[34:49], v[236:239], v[224:227], v[34:49]
	v_mfma_f32_32x32x16_bf16 v[50:65], v[236:239], v[232:235], v[50:65]
	ds_read_b128 v[212:215], v72
	ds_read_b128 v[216:219], v73 offset:36864
	ds_read_b128 v[220:223], v72 offset:32
	ds_read_b128 v[224:227], v73 offset:36896
	ds_read_b128 v[228:231], v73 offset:41472
	ds_read_b128 v[232:235], v73 offset:41504
	s_waitcnt lgkmcnt(4)
	v_mfma_f32_32x32x16_bf16 v[2:17], v[212:215], v[216:219], v[2:17]
	s_waitcnt lgkmcnt(1)
	v_mfma_f32_32x32x16_bf16 v[18:33], v[212:215], v[228:231], v[18:33]
	ds_read_b128 v[212:215], v72 offset:4608
	ds_read_b128 v[236:239], v72 offset:4640
	s_waitcnt lgkmcnt(1)
	v_mfma_f32_32x32x16_bf16 v[34:49], v[212:215], v[216:219], v[34:49]
	v_mfma_f32_32x32x16_bf16 v[50:65], v[212:215], v[228:231], v[50:65]
	v_mfma_f32_32x32x16_bf16 v[2:17], v[220:223], v[224:227], v[2:17]
	v_mfma_f32_32x32x16_bf16 v[18:33], v[220:223], v[232:235], v[18:33]
	s_waitcnt lgkmcnt(0)
	v_mfma_f32_32x32x16_bf16 v[34:49], v[236:239], v[224:227], v[34:49]
	ds_read_b128 v[212:215], v72 offset:64
	ds_read_b128 v[216:219], v73 offset:36928
	ds_read_b128 v[220:223], v72 offset:96
	ds_read_b128 v[224:227], v73 offset:36960
	v_mfma_f32_32x32x16_bf16 v[50:65], v[236:239], v[232:235], v[50:65]
	ds_read_b128 v[228:231], v73 offset:41536
	ds_read_b128 v[232:235], v73 offset:41568
	s_waitcnt lgkmcnt(4)
	v_mfma_f32_32x32x16_bf16 v[2:17], v[212:215], v[216:219], v[2:17]
	s_waitcnt lgkmcnt(1)
	v_mfma_f32_32x32x16_bf16 v[18:33], v[212:215], v[228:231], v[18:33]
	ds_read_b128 v[212:215], v72 offset:4672
	ds_read_b128 v[236:239], v72 offset:4704
	s_waitcnt vmcnt(13)
	ds_write_b128 v1, v[156:159] offset:18432
	ds_write_b128 v1, v[148:151] offset:23040
	ds_write_b128 v1, v[152:155] offset:27648
	s_waitcnt vmcnt(11)
	ds_write_b128 v1, v[164:167] offset:32256
	ds_write_b128 v1, v[160:163] offset:55296
	s_waitcnt vmcnt(10)
	ds_write_b128 v1, v[168:171] offset:59904
	s_waitcnt vmcnt(9)
	ds_write_b128 v1, v[172:175] offset:64512
	s_waitcnt vmcnt(8)
	ds_write_b128 v92, v[176:179] offset:32256
	global_load_dwordx4 v[148:151], v[80:81], off offset:896
	global_load_dwordx4 v[152:155], v[82:83], off offset:896
	global_load_dwordx4 v[156:159], v[78:79], off offset:896
	global_load_dwordx4 v[160:163], v[76:77], off offset:896
	global_load_dwordx4 v[164:167], v[90:91], off offset:896
	global_load_dwordx4 v[168:171], v[84:85], off offset:896
	global_load_dwordx4 v[172:175], v[86:87], off offset:896
	global_load_dwordx4 v[176:179], v[88:89], off offset:896
	s_waitcnt lgkmcnt(0)
	s_barrier
	v_mfma_f32_32x32x16_bf16 v[34:49], v[212:215], v[216:219], v[34:49]
	v_mfma_f32_32x32x16_bf16 v[50:65], v[212:215], v[228:231], v[50:65]
	v_mfma_f32_32x32x16_bf16 v[2:17], v[220:223], v[224:227], v[2:17]
	v_mfma_f32_32x32x16_bf16 v[18:33], v[220:223], v[232:235], v[18:33]
	v_mfma_f32_32x32x16_bf16 v[34:49], v[236:239], v[224:227], v[34:49]
	v_mfma_f32_32x32x16_bf16 v[50:65], v[236:239], v[232:235], v[50:65]
	ds_read_b128 v[212:215], v72 offset:18432
	ds_read_b128 v[216:219], v73 offset:55296
	ds_read_b128 v[220:223], v72 offset:18464
	ds_read_b128 v[224:227], v73 offset:55328
	ds_read_b128 v[228:231], v73 offset:59904
	ds_read_b128 v[232:235], v73 offset:59936
	s_waitcnt lgkmcnt(4)
	v_mfma_f32_32x32x16_bf16 v[2:17], v[212:215], v[216:219], v[2:17]
	s_waitcnt lgkmcnt(1)
	v_mfma_f32_32x32x16_bf16 v[18:33], v[212:215], v[228:231], v[18:33]
	ds_read_b128 v[212:215], v72 offset:23040
	ds_read_b128 v[236:239], v72 offset:23072
	s_waitcnt lgkmcnt(1)
	v_mfma_f32_32x32x16_bf16 v[34:49], v[212:215], v[216:219], v[34:49]
	v_mfma_f32_32x32x16_bf16 v[50:65], v[212:215], v[228:231], v[50:65]
	v_mfma_f32_32x32x16_bf16 v[2:17], v[220:223], v[224:227], v[2:17]
	v_mfma_f32_32x32x16_bf16 v[18:33], v[220:223], v[232:235], v[18:33]
	s_waitcnt lgkmcnt(0)
	v_mfma_f32_32x32x16_bf16 v[34:49], v[236:239], v[224:227], v[34:49]
	ds_read_b128 v[212:215], v72 offset:18496
	ds_read_b128 v[216:219], v73 offset:55360
	ds_read_b128 v[220:223], v72 offset:18528
	ds_read_b128 v[224:227], v73 offset:55392
	v_mfma_f32_32x32x16_bf16 v[50:65], v[236:239], v[232:235], v[50:65]
	ds_read_b128 v[228:231], v73 offset:59968
	ds_read_b128 v[232:235], v73 offset:60000
	s_waitcnt lgkmcnt(4)
	v_mfma_f32_32x32x16_bf16 v[2:17], v[212:215], v[216:219], v[2:17]
	s_waitcnt lgkmcnt(1)
	v_mfma_f32_32x32x16_bf16 v[18:33], v[212:215], v[228:231], v[18:33]
	ds_read_b128 v[212:215], v72 offset:23104
	ds_read_b128 v[236:239], v72 offset:23136
	s_waitcnt vmcnt(13)
	ds_write_b128 v1, v[188:191]
	ds_write_b128 v1, v[180:183] offset:4608
	ds_write_b128 v1, v[184:187] offset:9216
	s_waitcnt vmcnt(11)
	ds_write_b128 v1, v[196:199] offset:13824
	ds_write_b128 v1, v[192:195] offset:36864
	s_waitcnt vmcnt(10)
	ds_write_b128 v1, v[200:203] offset:41472
	s_waitcnt vmcnt(9)
	ds_write_b128 v1, v[204:207] offset:46080
	s_waitcnt vmcnt(8)
	ds_write_b128 v1, v[208:211] offset:50688
	global_load_dwordx4 v[180:183], v[80:81], off offset:1024
	global_load_dwordx4 v[184:187], v[82:83], off offset:1024
	global_load_dwordx4 v[188:191], v[78:79], off offset:1024
	global_load_dwordx4 v[192:195], v[76:77], off offset:1024
	global_load_dwordx4 v[196:199], v[90:91], off offset:1024
	global_load_dwordx4 v[200:203], v[84:85], off offset:1024
	global_load_dwordx4 v[204:207], v[86:87], off offset:1024
	global_load_dwordx4 v[208:211], v[88:89], off offset:1024
	s_waitcnt lgkmcnt(0)
	s_barrier
	v_mfma_f32_32x32x16_bf16 v[34:49], v[212:215], v[216:219], v[34:49]
	v_mfma_f32_32x32x16_bf16 v[50:65], v[212:215], v[228:231], v[50:65]
	v_mfma_f32_32x32x16_bf16 v[2:17], v[220:223], v[224:227], v[2:17]
	v_mfma_f32_32x32x16_bf16 v[18:33], v[220:223], v[232:235], v[18:33]
	v_mfma_f32_32x32x16_bf16 v[34:49], v[236:239], v[224:227], v[34:49]
	v_mfma_f32_32x32x16_bf16 v[50:65], v[236:239], v[232:235], v[50:65]
	ds_read_b128 v[212:215], v72
	ds_read_b128 v[216:219], v73 offset:36864
	ds_read_b128 v[220:223], v72 offset:32
	ds_read_b128 v[224:227], v73 offset:36896
	ds_read_b128 v[228:231], v73 offset:41472
	ds_read_b128 v[232:235], v73 offset:41504
	s_waitcnt lgkmcnt(4)
	v_mfma_f32_32x32x16_bf16 v[2:17], v[212:215], v[216:219], v[2:17]
	s_waitcnt lgkmcnt(1)
	v_mfma_f32_32x32x16_bf16 v[18:33], v[212:215], v[228:231], v[18:33]
	ds_read_b128 v[212:215], v72 offset:4608
	ds_read_b128 v[236:239], v72 offset:4640
	s_waitcnt lgkmcnt(1)
	v_mfma_f32_32x32x16_bf16 v[34:49], v[212:215], v[216:219], v[34:49]
	v_mfma_f32_32x32x16_bf16 v[50:65], v[212:215], v[228:231], v[50:65]
	v_mfma_f32_32x32x16_bf16 v[2:17], v[220:223], v[224:227], v[2:17]
	v_mfma_f32_32x32x16_bf16 v[18:33], v[220:223], v[232:235], v[18:33]
	s_waitcnt lgkmcnt(0)
	v_mfma_f32_32x32x16_bf16 v[34:49], v[236:239], v[224:227], v[34:49]
	ds_read_b128 v[212:215], v72 offset:64
	ds_read_b128 v[216:219], v73 offset:36928
	ds_read_b128 v[220:223], v72 offset:96
	ds_read_b128 v[224:227], v73 offset:36960
	v_mfma_f32_32x32x16_bf16 v[50:65], v[236:239], v[232:235], v[50:65]
	ds_read_b128 v[228:231], v73 offset:41536
	ds_read_b128 v[232:235], v73 offset:41568
	s_waitcnt lgkmcnt(4)
	v_mfma_f32_32x32x16_bf16 v[2:17], v[212:215], v[216:219], v[2:17]
	s_waitcnt lgkmcnt(1)
	v_mfma_f32_32x32x16_bf16 v[18:33], v[212:215], v[228:231], v[18:33]
	ds_read_b128 v[212:215], v72 offset:4672
	ds_read_b128 v[236:239], v72 offset:4704
	s_waitcnt vmcnt(13)
	ds_write_b128 v1, v[156:159] offset:18432
	ds_write_b128 v1, v[148:151] offset:23040
	ds_write_b128 v1, v[152:155] offset:27648
	s_waitcnt vmcnt(11)
	ds_write_b128 v1, v[164:167] offset:32256
	ds_write_b128 v1, v[160:163] offset:55296
	s_waitcnt vmcnt(10)
	ds_write_b128 v1, v[168:171] offset:59904
	s_waitcnt vmcnt(9)
	ds_write_b128 v1, v[172:175] offset:64512
	s_waitcnt vmcnt(8)
	ds_write_b128 v92, v[176:179] offset:32256
	global_load_dwordx4 v[148:151], v[80:81], off offset:1152
	global_load_dwordx4 v[152:155], v[82:83], off offset:1152
	global_load_dwordx4 v[156:159], v[78:79], off offset:1152
	global_load_dwordx4 v[160:163], v[76:77], off offset:1152
	global_load_dwordx4 v[164:167], v[90:91], off offset:1152
	global_load_dwordx4 v[168:171], v[84:85], off offset:1152
	global_load_dwordx4 v[172:175], v[86:87], off offset:1152
	global_load_dwordx4 v[176:179], v[88:89], off offset:1152
	s_waitcnt lgkmcnt(0)
	s_barrier
	v_mfma_f32_32x32x16_bf16 v[34:49], v[212:215], v[216:219], v[34:49]
	v_mfma_f32_32x32x16_bf16 v[50:65], v[212:215], v[228:231], v[50:65]
	v_mfma_f32_32x32x16_bf16 v[2:17], v[220:223], v[224:227], v[2:17]
	v_mfma_f32_32x32x16_bf16 v[18:33], v[220:223], v[232:235], v[18:33]
	v_mfma_f32_32x32x16_bf16 v[34:49], v[236:239], v[224:227], v[34:49]
	v_mfma_f32_32x32x16_bf16 v[50:65], v[236:239], v[232:235], v[50:65]
	ds_read_b128 v[212:215], v72 offset:18432
	ds_read_b128 v[216:219], v73 offset:55296
	ds_read_b128 v[220:223], v72 offset:18464
	ds_read_b128 v[224:227], v73 offset:55328
	ds_read_b128 v[228:231], v73 offset:59904
	ds_read_b128 v[232:235], v73 offset:59936
	s_waitcnt lgkmcnt(4)
	v_mfma_f32_32x32x16_bf16 v[2:17], v[212:215], v[216:219], v[2:17]
	s_waitcnt lgkmcnt(1)
	v_mfma_f32_32x32x16_bf16 v[18:33], v[212:215], v[228:231], v[18:33]
	ds_read_b128 v[212:215], v72 offset:23040
	ds_read_b128 v[236:239], v72 offset:23072
	s_waitcnt lgkmcnt(1)
	v_mfma_f32_32x32x16_bf16 v[34:49], v[212:215], v[216:219], v[34:49]
	v_mfma_f32_32x32x16_bf16 v[50:65], v[212:215], v[228:231], v[50:65]
	v_mfma_f32_32x32x16_bf16 v[2:17], v[220:223], v[224:227], v[2:17]
	v_mfma_f32_32x32x16_bf16 v[18:33], v[220:223], v[232:235], v[18:33]
	s_waitcnt lgkmcnt(0)
	v_mfma_f32_32x32x16_bf16 v[34:49], v[236:239], v[224:227], v[34:49]
	ds_read_b128 v[212:215], v72 offset:18496
	ds_read_b128 v[216:219], v73 offset:55360
	ds_read_b128 v[220:223], v72 offset:18528
	ds_read_b128 v[224:227], v73 offset:55392
	v_mfma_f32_32x32x16_bf16 v[50:65], v[236:239], v[232:235], v[50:65]
	ds_read_b128 v[228:231], v73 offset:59968
	ds_read_b128 v[232:235], v73 offset:60000
	s_waitcnt lgkmcnt(4)
	v_mfma_f32_32x32x16_bf16 v[2:17], v[212:215], v[216:219], v[2:17]
	s_waitcnt lgkmcnt(1)
	v_mfma_f32_32x32x16_bf16 v[18:33], v[212:215], v[228:231], v[18:33]
	ds_read_b128 v[212:215], v72 offset:23104
	ds_read_b128 v[236:239], v72 offset:23136
	s_waitcnt vmcnt(13)
	ds_write_b128 v1, v[188:191]
	ds_write_b128 v1, v[180:183] offset:4608
	ds_write_b128 v1, v[184:187] offset:9216
	s_waitcnt vmcnt(11)
	ds_write_b128 v1, v[196:199] offset:13824
	ds_write_b128 v1, v[192:195] offset:36864
	s_waitcnt vmcnt(10)
	ds_write_b128 v1, v[200:203] offset:41472
	s_waitcnt vmcnt(9)
	ds_write_b128 v1, v[204:207] offset:46080
	s_waitcnt vmcnt(8)
	ds_write_b128 v1, v[208:211] offset:50688
	global_load_dwordx4 v[180:183], v[80:81], off offset:1280
	global_load_dwordx4 v[184:187], v[82:83], off offset:1280
	global_load_dwordx4 v[188:191], v[78:79], off offset:1280
	global_load_dwordx4 v[192:195], v[76:77], off offset:1280
	global_load_dwordx4 v[196:199], v[90:91], off offset:1280
	global_load_dwordx4 v[200:203], v[84:85], off offset:1280
	global_load_dwordx4 v[204:207], v[86:87], off offset:1280
	global_load_dwordx4 v[208:211], v[88:89], off offset:1280
	s_waitcnt lgkmcnt(0)
	s_barrier
	v_mfma_f32_32x32x16_bf16 v[34:49], v[212:215], v[216:219], v[34:49]
	v_mfma_f32_32x32x16_bf16 v[50:65], v[212:215], v[228:231], v[50:65]
	v_mfma_f32_32x32x16_bf16 v[2:17], v[220:223], v[224:227], v[2:17]
	v_mfma_f32_32x32x16_bf16 v[18:33], v[220:223], v[232:235], v[18:33]
	v_mfma_f32_32x32x16_bf16 v[34:49], v[236:239], v[224:227], v[34:49]
	v_mfma_f32_32x32x16_bf16 v[50:65], v[236:239], v[232:235], v[50:65]
	ds_read_b128 v[212:215], v72
	ds_read_b128 v[216:219], v73 offset:36864
	ds_read_b128 v[220:223], v72 offset:32
	ds_read_b128 v[224:227], v73 offset:36896
	ds_read_b128 v[228:231], v73 offset:41472
	ds_read_b128 v[232:235], v73 offset:41504
	s_waitcnt lgkmcnt(4)
	v_mfma_f32_32x32x16_bf16 v[2:17], v[212:215], v[216:219], v[2:17]
	s_waitcnt lgkmcnt(1)
	v_mfma_f32_32x32x16_bf16 v[18:33], v[212:215], v[228:231], v[18:33]
	ds_read_b128 v[212:215], v72 offset:4608
	ds_read_b128 v[236:239], v72 offset:4640
	s_waitcnt lgkmcnt(1)
	v_mfma_f32_32x32x16_bf16 v[34:49], v[212:215], v[216:219], v[34:49]
	v_mfma_f32_32x32x16_bf16 v[50:65], v[212:215], v[228:231], v[50:65]
	v_mfma_f32_32x32x16_bf16 v[2:17], v[220:223], v[224:227], v[2:17]
	v_mfma_f32_32x32x16_bf16 v[18:33], v[220:223], v[232:235], v[18:33]
	s_waitcnt lgkmcnt(0)
	v_mfma_f32_32x32x16_bf16 v[34:49], v[236:239], v[224:227], v[34:49]
	ds_read_b128 v[212:215], v72 offset:64
	ds_read_b128 v[216:219], v73 offset:36928
	ds_read_b128 v[220:223], v72 offset:96
	ds_read_b128 v[224:227], v73 offset:36960
	v_mfma_f32_32x32x16_bf16 v[50:65], v[236:239], v[232:235], v[50:65]
	ds_read_b128 v[228:231], v73 offset:41536
	ds_read_b128 v[232:235], v73 offset:41568
	s_waitcnt lgkmcnt(4)
	v_mfma_f32_32x32x16_bf16 v[2:17], v[212:215], v[216:219], v[2:17]
	s_waitcnt lgkmcnt(1)
	v_mfma_f32_32x32x16_bf16 v[18:33], v[212:215], v[228:231], v[18:33]
	ds_read_b128 v[212:215], v72 offset:4672
	ds_read_b128 v[236:239], v72 offset:4704
	s_waitcnt vmcnt(13)
	ds_write_b128 v1, v[156:159] offset:18432
	ds_write_b128 v1, v[148:151] offset:23040
	ds_write_b128 v1, v[152:155] offset:27648
	s_waitcnt vmcnt(11)
	ds_write_b128 v1, v[164:167] offset:32256
	ds_write_b128 v1, v[160:163] offset:55296
	s_waitcnt vmcnt(10)
	ds_write_b128 v1, v[168:171] offset:59904
	s_waitcnt vmcnt(9)
	ds_write_b128 v1, v[172:175] offset:64512
	s_waitcnt vmcnt(8)
	ds_write_b128 v92, v[176:179] offset:32256
	global_load_dwordx4 v[148:151], v[80:81], off offset:1408
	global_load_dwordx4 v[152:155], v[82:83], off offset:1408
	global_load_dwordx4 v[156:159], v[78:79], off offset:1408
	global_load_dwordx4 v[160:163], v[76:77], off offset:1408
	global_load_dwordx4 v[164:167], v[90:91], off offset:1408
	global_load_dwordx4 v[168:171], v[84:85], off offset:1408
	global_load_dwordx4 v[172:175], v[86:87], off offset:1408
	global_load_dwordx4 v[176:179], v[88:89], off offset:1408
	s_waitcnt lgkmcnt(0)
	s_barrier
	v_mfma_f32_32x32x16_bf16 v[34:49], v[212:215], v[216:219], v[34:49]
	v_mfma_f32_32x32x16_bf16 v[50:65], v[212:215], v[228:231], v[50:65]
	v_mfma_f32_32x32x16_bf16 v[2:17], v[220:223], v[224:227], v[2:17]
	v_mfma_f32_32x32x16_bf16 v[18:33], v[220:223], v[232:235], v[18:33]
	v_mfma_f32_32x32x16_bf16 v[34:49], v[236:239], v[224:227], v[34:49]
	v_mfma_f32_32x32x16_bf16 v[50:65], v[236:239], v[232:235], v[50:65]
	ds_read_b128 v[212:215], v72 offset:18432
	ds_read_b128 v[216:219], v73 offset:55296
	ds_read_b128 v[220:223], v72 offset:18464
	ds_read_b128 v[224:227], v73 offset:55328
	ds_read_b128 v[228:231], v73 offset:59904
	ds_read_b128 v[232:235], v73 offset:59936
	s_waitcnt lgkmcnt(4)
	v_mfma_f32_32x32x16_bf16 v[2:17], v[212:215], v[216:219], v[2:17]
	s_waitcnt lgkmcnt(1)
	v_mfma_f32_32x32x16_bf16 v[18:33], v[212:215], v[228:231], v[18:33]
	ds_read_b128 v[212:215], v72 offset:23040
	ds_read_b128 v[236:239], v72 offset:23072
	s_waitcnt lgkmcnt(1)
	v_mfma_f32_32x32x16_bf16 v[34:49], v[212:215], v[216:219], v[34:49]
	v_mfma_f32_32x32x16_bf16 v[50:65], v[212:215], v[228:231], v[50:65]
	v_mfma_f32_32x32x16_bf16 v[2:17], v[220:223], v[224:227], v[2:17]
	v_mfma_f32_32x32x16_bf16 v[18:33], v[220:223], v[232:235], v[18:33]
	s_waitcnt lgkmcnt(0)
	v_mfma_f32_32x32x16_bf16 v[34:49], v[236:239], v[224:227], v[34:49]
	ds_read_b128 v[212:215], v72 offset:18496
	ds_read_b128 v[216:219], v73 offset:55360
	ds_read_b128 v[220:223], v72 offset:18528
	ds_read_b128 v[224:227], v73 offset:55392
	v_mfma_f32_32x32x16_bf16 v[50:65], v[236:239], v[232:235], v[50:65]
	ds_read_b128 v[228:231], v73 offset:59968
	ds_read_b128 v[232:235], v73 offset:60000
	s_waitcnt lgkmcnt(4)
	v_mfma_f32_32x32x16_bf16 v[2:17], v[212:215], v[216:219], v[2:17]
	s_waitcnt lgkmcnt(1)
	v_mfma_f32_32x32x16_bf16 v[18:33], v[212:215], v[228:231], v[18:33]
	ds_read_b128 v[212:215], v72 offset:23104
	ds_read_b128 v[236:239], v72 offset:23136
	s_waitcnt vmcnt(13)
	ds_write_b128 v1, v[188:191]
	ds_write_b128 v1, v[180:183] offset:4608
	ds_write_b128 v1, v[184:187] offset:9216
	s_waitcnt vmcnt(11)
	ds_write_b128 v1, v[196:199] offset:13824
	ds_write_b128 v1, v[192:195] offset:36864
	s_waitcnt vmcnt(10)
	ds_write_b128 v1, v[200:203] offset:41472
	s_waitcnt vmcnt(9)
	ds_write_b128 v1, v[204:207] offset:46080
	s_waitcnt vmcnt(8)
	ds_write_b128 v1, v[208:211] offset:50688
	global_load_dwordx4 v[180:183], v[80:81], off offset:1536
	global_load_dwordx4 v[184:187], v[82:83], off offset:1536
	global_load_dwordx4 v[188:191], v[78:79], off offset:1536
	global_load_dwordx4 v[192:195], v[76:77], off offset:1536
	global_load_dwordx4 v[196:199], v[90:91], off offset:1536
	global_load_dwordx4 v[200:203], v[84:85], off offset:1536
	global_load_dwordx4 v[204:207], v[86:87], off offset:1536
	global_load_dwordx4 v[208:211], v[88:89], off offset:1536
	s_waitcnt lgkmcnt(0)
	s_barrier
	v_mfma_f32_32x32x16_bf16 v[34:49], v[212:215], v[216:219], v[34:49]
	v_mfma_f32_32x32x16_bf16 v[50:65], v[212:215], v[228:231], v[50:65]
	v_mfma_f32_32x32x16_bf16 v[2:17], v[220:223], v[224:227], v[2:17]
	v_mfma_f32_32x32x16_bf16 v[18:33], v[220:223], v[232:235], v[18:33]
	v_mfma_f32_32x32x16_bf16 v[34:49], v[236:239], v[224:227], v[34:49]
	v_mfma_f32_32x32x16_bf16 v[50:65], v[236:239], v[232:235], v[50:65]
	ds_read_b128 v[212:215], v72
	ds_read_b128 v[216:219], v73 offset:36864
	ds_read_b128 v[220:223], v72 offset:32
	ds_read_b128 v[224:227], v73 offset:36896
	ds_read_b128 v[228:231], v73 offset:41472
	ds_read_b128 v[232:235], v73 offset:41504
	s_waitcnt lgkmcnt(4)
	v_mfma_f32_32x32x16_bf16 v[2:17], v[212:215], v[216:219], v[2:17]
	s_waitcnt lgkmcnt(1)
	v_mfma_f32_32x32x16_bf16 v[18:33], v[212:215], v[228:231], v[18:33]
	ds_read_b128 v[212:215], v72 offset:4608
	ds_read_b128 v[236:239], v72 offset:4640
	s_waitcnt lgkmcnt(1)
	v_mfma_f32_32x32x16_bf16 v[34:49], v[212:215], v[216:219], v[34:49]
	v_mfma_f32_32x32x16_bf16 v[50:65], v[212:215], v[228:231], v[50:65]
	v_mfma_f32_32x32x16_bf16 v[2:17], v[220:223], v[224:227], v[2:17]
	v_mfma_f32_32x32x16_bf16 v[18:33], v[220:223], v[232:235], v[18:33]
	s_waitcnt lgkmcnt(0)
	v_mfma_f32_32x32x16_bf16 v[34:49], v[236:239], v[224:227], v[34:49]
	ds_read_b128 v[212:215], v72 offset:64
	ds_read_b128 v[216:219], v73 offset:36928
	ds_read_b128 v[220:223], v72 offset:96
	ds_read_b128 v[224:227], v73 offset:36960
	v_mfma_f32_32x32x16_bf16 v[50:65], v[236:239], v[232:235], v[50:65]
	ds_read_b128 v[228:231], v73 offset:41536
	ds_read_b128 v[232:235], v73 offset:41568
	s_waitcnt lgkmcnt(4)
	v_mfma_f32_32x32x16_bf16 v[2:17], v[212:215], v[216:219], v[2:17]
	s_waitcnt lgkmcnt(1)
	v_mfma_f32_32x32x16_bf16 v[18:33], v[212:215], v[228:231], v[18:33]
	ds_read_b128 v[212:215], v72 offset:4672
	ds_read_b128 v[236:239], v72 offset:4704
	s_waitcnt vmcnt(13)
	ds_write_b128 v1, v[156:159] offset:18432
	ds_write_b128 v1, v[148:151] offset:23040
	ds_write_b128 v1, v[152:155] offset:27648
	s_waitcnt vmcnt(11)
	ds_write_b128 v1, v[164:167] offset:32256
	ds_write_b128 v1, v[160:163] offset:55296
	s_waitcnt vmcnt(10)
	ds_write_b128 v1, v[168:171] offset:59904
	s_waitcnt vmcnt(9)
	ds_write_b128 v1, v[172:175] offset:64512
	s_waitcnt vmcnt(8)
	ds_write_b128 v92, v[176:179] offset:32256
	global_load_dwordx4 v[148:151], v[80:81], off offset:1664
	global_load_dwordx4 v[152:155], v[82:83], off offset:1664
	global_load_dwordx4 v[156:159], v[78:79], off offset:1664
	global_load_dwordx4 v[160:163], v[76:77], off offset:1664
	global_load_dwordx4 v[164:167], v[90:91], off offset:1664
	global_load_dwordx4 v[168:171], v[84:85], off offset:1664
	global_load_dwordx4 v[172:175], v[86:87], off offset:1664
	global_load_dwordx4 v[176:179], v[88:89], off offset:1664
	s_waitcnt lgkmcnt(0)
	s_barrier
	v_mfma_f32_32x32x16_bf16 v[34:49], v[212:215], v[216:219], v[34:49]
	v_mfma_f32_32x32x16_bf16 v[50:65], v[212:215], v[228:231], v[50:65]
	v_mfma_f32_32x32x16_bf16 v[2:17], v[220:223], v[224:227], v[2:17]
	v_mfma_f32_32x32x16_bf16 v[18:33], v[220:223], v[232:235], v[18:33]
	v_mfma_f32_32x32x16_bf16 v[34:49], v[236:239], v[224:227], v[34:49]
	v_mfma_f32_32x32x16_bf16 v[50:65], v[236:239], v[232:235], v[50:65]
	ds_read_b128 v[212:215], v72 offset:18432
	ds_read_b128 v[216:219], v73 offset:55296
	ds_read_b128 v[220:223], v72 offset:18464
	ds_read_b128 v[224:227], v73 offset:55328
	ds_read_b128 v[228:231], v73 offset:59904
	ds_read_b128 v[232:235], v73 offset:59936
	s_waitcnt lgkmcnt(4)
	v_mfma_f32_32x32x16_bf16 v[2:17], v[212:215], v[216:219], v[2:17]
	s_waitcnt lgkmcnt(1)
	v_mfma_f32_32x32x16_bf16 v[18:33], v[212:215], v[228:231], v[18:33]
	ds_read_b128 v[212:215], v72 offset:23040
	ds_read_b128 v[236:239], v72 offset:23072
	s_waitcnt lgkmcnt(1)
	v_mfma_f32_32x32x16_bf16 v[34:49], v[212:215], v[216:219], v[34:49]
	v_mfma_f32_32x32x16_bf16 v[50:65], v[212:215], v[228:231], v[50:65]
	v_mfma_f32_32x32x16_bf16 v[2:17], v[220:223], v[224:227], v[2:17]
	v_mfma_f32_32x32x16_bf16 v[18:33], v[220:223], v[232:235], v[18:33]
	s_waitcnt lgkmcnt(0)
	v_mfma_f32_32x32x16_bf16 v[34:49], v[236:239], v[224:227], v[34:49]
	ds_read_b128 v[212:215], v72 offset:18496
	ds_read_b128 v[216:219], v73 offset:55360
	ds_read_b128 v[220:223], v72 offset:18528
	ds_read_b128 v[224:227], v73 offset:55392
	v_mfma_f32_32x32x16_bf16 v[50:65], v[236:239], v[232:235], v[50:65]
	ds_read_b128 v[228:231], v73 offset:59968
	ds_read_b128 v[232:235], v73 offset:60000
	s_waitcnt lgkmcnt(4)
	v_mfma_f32_32x32x16_bf16 v[2:17], v[212:215], v[216:219], v[2:17]
	s_waitcnt lgkmcnt(1)
	v_mfma_f32_32x32x16_bf16 v[18:33], v[212:215], v[228:231], v[18:33]
	ds_read_b128 v[212:215], v72 offset:23104
	ds_read_b128 v[236:239], v72 offset:23136
	s_waitcnt vmcnt(13)
	ds_write_b128 v1, v[188:191]
	ds_write_b128 v1, v[180:183] offset:4608
	ds_write_b128 v1, v[184:187] offset:9216
	s_waitcnt vmcnt(11)
	ds_write_b128 v1, v[196:199] offset:13824
	ds_write_b128 v1, v[192:195] offset:36864
	s_waitcnt vmcnt(10)
	ds_write_b128 v1, v[200:203] offset:41472
	s_waitcnt vmcnt(9)
	ds_write_b128 v1, v[204:207] offset:46080
	s_waitcnt vmcnt(8)
	ds_write_b128 v1, v[208:211] offset:50688
	global_load_dwordx4 v[180:183], v[80:81], off offset:1792
	global_load_dwordx4 v[184:187], v[82:83], off offset:1792
	global_load_dwordx4 v[188:191], v[78:79], off offset:1792
	global_load_dwordx4 v[192:195], v[76:77], off offset:1792
	global_load_dwordx4 v[196:199], v[90:91], off offset:1792
	global_load_dwordx4 v[200:203], v[84:85], off offset:1792
	global_load_dwordx4 v[204:207], v[86:87], off offset:1792
	global_load_dwordx4 v[208:211], v[88:89], off offset:1792
	s_waitcnt lgkmcnt(0)
	s_barrier
	v_mfma_f32_32x32x16_bf16 v[34:49], v[212:215], v[216:219], v[34:49]
	v_mfma_f32_32x32x16_bf16 v[50:65], v[212:215], v[228:231], v[50:65]
	v_mfma_f32_32x32x16_bf16 v[2:17], v[220:223], v[224:227], v[2:17]
	v_mfma_f32_32x32x16_bf16 v[18:33], v[220:223], v[232:235], v[18:33]
	v_mfma_f32_32x32x16_bf16 v[34:49], v[236:239], v[224:227], v[34:49]
	v_mfma_f32_32x32x16_bf16 v[50:65], v[236:239], v[232:235], v[50:65]
	ds_read_b128 v[212:215], v72
	ds_read_b128 v[216:219], v73 offset:36864
	ds_read_b128 v[220:223], v72 offset:32
	ds_read_b128 v[224:227], v73 offset:36896
	ds_read_b128 v[228:231], v73 offset:41472
	ds_read_b128 v[232:235], v73 offset:41504
	s_waitcnt lgkmcnt(4)
	v_mfma_f32_32x32x16_bf16 v[2:17], v[212:215], v[216:219], v[2:17]
	s_waitcnt lgkmcnt(1)
	v_mfma_f32_32x32x16_bf16 v[18:33], v[212:215], v[228:231], v[18:33]
	ds_read_b128 v[212:215], v72 offset:4608
	ds_read_b128 v[236:239], v72 offset:4640
	s_waitcnt lgkmcnt(1)
	v_mfma_f32_32x32x16_bf16 v[34:49], v[212:215], v[216:219], v[34:49]
	v_mfma_f32_32x32x16_bf16 v[50:65], v[212:215], v[228:231], v[50:65]
	v_mfma_f32_32x32x16_bf16 v[2:17], v[220:223], v[224:227], v[2:17]
	v_mfma_f32_32x32x16_bf16 v[18:33], v[220:223], v[232:235], v[18:33]
	s_waitcnt lgkmcnt(0)
	v_mfma_f32_32x32x16_bf16 v[34:49], v[236:239], v[224:227], v[34:49]
	ds_read_b128 v[212:215], v72 offset:64
	ds_read_b128 v[216:219], v73 offset:36928
	ds_read_b128 v[220:223], v72 offset:96
	ds_read_b128 v[224:227], v73 offset:36960
	v_mfma_f32_32x32x16_bf16 v[50:65], v[236:239], v[232:235], v[50:65]
	ds_read_b128 v[228:231], v73 offset:41536
	ds_read_b128 v[232:235], v73 offset:41568
	s_waitcnt lgkmcnt(4)
	v_mfma_f32_32x32x16_bf16 v[2:17], v[212:215], v[216:219], v[2:17]
	s_waitcnt lgkmcnt(1)
	v_mfma_f32_32x32x16_bf16 v[18:33], v[212:215], v[228:231], v[18:33]
	ds_read_b128 v[212:215], v72 offset:4672
	ds_read_b128 v[236:239], v72 offset:4704
	s_waitcnt vmcnt(13)
	ds_write_b128 v1, v[156:159] offset:18432
	ds_write_b128 v1, v[148:151] offset:23040
	ds_write_b128 v1, v[152:155] offset:27648
	s_waitcnt vmcnt(11)
	ds_write_b128 v1, v[164:167] offset:32256
	ds_write_b128 v1, v[160:163] offset:55296
	s_waitcnt vmcnt(10)
	ds_write_b128 v1, v[168:171] offset:59904
	s_waitcnt vmcnt(9)
	ds_write_b128 v1, v[172:175] offset:64512
	s_waitcnt vmcnt(8)
	ds_write_b128 v92, v[176:179] offset:32256
	s_waitcnt lgkmcnt(0)
	s_barrier
	global_load_dwordx4 v[148:151], v[80:81], off offset:1920
	s_nop 0
	global_load_dwordx4 v[80:83], v[82:83], off offset:1920
	s_nop 0
	global_load_dwordx4 v[152:155], v[78:79], off offset:1920
	s_nop 0
	global_load_dwordx4 v[76:79], v[76:77], off offset:1920
	s_nop 0
	global_load_dwordx4 v[156:159], v[90:91], off offset:1920
	global_load_dwordx4 v[160:163], v[84:85], off offset:1920
	s_nop 0
	global_load_dwordx4 v[84:87], v[86:87], off offset:1920
	s_nop 0
	global_load_dwordx4 v[88:91], v[88:89], off offset:1920
	v_mfma_f32_32x32x16_bf16 v[34:49], v[212:215], v[216:219], v[34:49]
	v_mfma_f32_32x32x16_bf16 v[50:65], v[212:215], v[228:231], v[50:65]
	v_mfma_f32_32x32x16_bf16 v[2:17], v[220:223], v[224:227], v[2:17]
	v_mfma_f32_32x32x16_bf16 v[18:33], v[220:223], v[232:235], v[18:33]
	v_mfma_f32_32x32x16_bf16 v[34:49], v[236:239], v[224:227], v[34:49]
	v_mfma_f32_32x32x16_bf16 v[50:65], v[236:239], v[232:235], v[50:65]
	ds_read_b128 v[164:167], v72 offset:18432
	ds_read_b128 v[168:171], v73 offset:55296
	ds_read_b128 v[172:175], v72 offset:18464
	ds_read_b128 v[176:179], v73 offset:55328
	ds_read_b128 v[212:215], v73 offset:59904
	ds_read_b128 v[216:219], v73 offset:59936
	s_waitcnt lgkmcnt(4)
	v_mfma_f32_32x32x16_bf16 v[2:17], v[164:167], v[168:171], v[2:17]
	s_waitcnt lgkmcnt(1)
	v_mfma_f32_32x32x16_bf16 v[18:33], v[164:167], v[212:215], v[18:33]
	ds_read_b128 v[164:167], v72 offset:23040
	ds_read_b128 v[220:223], v72 offset:23072
	s_waitcnt lgkmcnt(1)
	v_mfma_f32_32x32x16_bf16 v[34:49], v[164:167], v[168:171], v[34:49]
	v_mfma_f32_32x32x16_bf16 v[50:65], v[164:167], v[212:215], v[50:65]
	v_mfma_f32_32x32x16_bf16 v[2:17], v[172:175], v[176:179], v[2:17]
	v_mfma_f32_32x32x16_bf16 v[18:33], v[172:175], v[216:219], v[18:33]
	s_waitcnt lgkmcnt(0)
	v_mfma_f32_32x32x16_bf16 v[34:49], v[220:223], v[176:179], v[34:49]
	ds_read_b128 v[164:167], v72 offset:18496
	ds_read_b128 v[168:171], v73 offset:55360
	ds_read_b128 v[172:175], v72 offset:18528
	ds_read_b128 v[176:179], v73 offset:55392
	v_mfma_f32_32x32x16_bf16 v[50:65], v[220:223], v[216:219], v[50:65]
	ds_read_b128 v[212:215], v73 offset:59968
	ds_read_b128 v[216:219], v73 offset:60000
	s_waitcnt lgkmcnt(4)
	v_mfma_f32_32x32x16_bf16 v[2:17], v[164:167], v[168:171], v[2:17]
	s_waitcnt lgkmcnt(1)
	v_mfma_f32_32x32x16_bf16 v[18:33], v[164:167], v[212:215], v[18:33]
	ds_read_b128 v[164:167], v72 offset:23104
	ds_read_b128 v[220:223], v72 offset:23136
	s_waitcnt vmcnt(13)
	ds_write_b128 v1, v[188:191]
	ds_write_b128 v1, v[180:183] offset:4608
	ds_write_b128 v1, v[184:187] offset:9216
	s_waitcnt vmcnt(11)
	ds_write_b128 v1, v[196:199] offset:13824
	ds_write_b128 v1, v[192:195] offset:36864
	s_waitcnt vmcnt(10)
	ds_write_b128 v1, v[200:203] offset:41472
	s_waitcnt vmcnt(9)
	ds_write_b128 v1, v[204:207] offset:46080
	s_waitcnt vmcnt(8)
	ds_write_b128 v1, v[208:211] offset:50688
	s_waitcnt lgkmcnt(0)
	s_barrier
	v_mfma_f32_32x32x16_bf16 v[34:49], v[164:167], v[168:171], v[34:49]
	v_mfma_f32_32x32x16_bf16 v[50:65], v[164:167], v[212:215], v[50:65]
	v_mfma_f32_32x32x16_bf16 v[2:17], v[172:175], v[176:179], v[2:17]
	v_mfma_f32_32x32x16_bf16 v[18:33], v[172:175], v[216:219], v[18:33]
	v_mfma_f32_32x32x16_bf16 v[34:49], v[220:223], v[176:179], v[34:49]
	v_mfma_f32_32x32x16_bf16 v[50:65], v[220:223], v[216:219], v[50:65]
	ds_read_b128 v[164:167], v72
	ds_read_b128 v[168:171], v73 offset:36864
	ds_read_b128 v[172:175], v72 offset:32
	ds_read_b128 v[176:179], v73 offset:36896
	ds_read_b128 v[180:183], v73 offset:41472
	ds_read_b128 v[184:187], v73 offset:41504
	s_waitcnt lgkmcnt(4)
	v_mfma_f32_32x32x16_bf16 v[2:17], v[164:167], v[168:171], v[2:17]
	s_waitcnt lgkmcnt(1)
	v_mfma_f32_32x32x16_bf16 v[18:33], v[164:167], v[180:183], v[18:33]
	ds_read_b128 v[164:167], v72 offset:4608
	ds_read_b128 v[188:191], v72 offset:4640
	s_waitcnt lgkmcnt(1)
	v_mfma_f32_32x32x16_bf16 v[34:49], v[164:167], v[168:171], v[34:49]
	v_mfma_f32_32x32x16_bf16 v[50:65], v[164:167], v[180:183], v[50:65]
	v_mfma_f32_32x32x16_bf16 v[2:17], v[172:175], v[176:179], v[2:17]
	v_mfma_f32_32x32x16_bf16 v[18:33], v[172:175], v[184:187], v[18:33]
	s_waitcnt lgkmcnt(0)
	v_mfma_f32_32x32x16_bf16 v[34:49], v[188:191], v[176:179], v[34:49]
	ds_read_b128 v[164:167], v72 offset:64
	ds_read_b128 v[168:171], v73 offset:36928
	ds_read_b128 v[172:175], v72 offset:96
	ds_read_b128 v[176:179], v73 offset:36960
	v_mfma_f32_32x32x16_bf16 v[50:65], v[188:191], v[184:187], v[50:65]
	ds_read_b128 v[180:183], v73 offset:41536
	ds_read_b128 v[184:187], v73 offset:41568
	s_waitcnt lgkmcnt(4)
	v_mfma_f32_32x32x16_bf16 v[2:17], v[164:167], v[168:171], v[2:17]
	s_waitcnt lgkmcnt(1)
	v_mfma_f32_32x32x16_bf16 v[18:33], v[164:167], v[180:183], v[18:33]
	ds_read_b128 v[164:167], v72 offset:4672
	ds_read_b128 v[188:191], v72 offset:4704
	s_waitcnt vmcnt(5)
	ds_write_b128 v1, v[152:155] offset:18432
	ds_write_b128 v1, v[148:151] offset:23040
	ds_write_b128 v1, v[80:83] offset:27648
	s_waitcnt vmcnt(3)
	ds_write_b128 v1, v[156:159] offset:32256
	ds_write_b128 v1, v[76:79] offset:55296
	s_waitcnt vmcnt(2)
	ds_write_b128 v1, v[160:163] offset:59904
	s_waitcnt vmcnt(1)
	ds_write_b128 v1, v[84:87] offset:64512
	s_waitcnt vmcnt(0)
	ds_write_b128 v92, v[88:91] offset:32256
	s_waitcnt lgkmcnt(0)
	s_barrier
	v_mfma_f32_32x32x16_bf16 v[34:49], v[164:167], v[168:171], v[34:49]
	v_mfma_f32_32x32x16_bf16 v[50:65], v[164:167], v[180:183], v[50:65]
	v_mfma_f32_32x32x16_bf16 v[2:17], v[172:175], v[176:179], v[2:17]
	v_mfma_f32_32x32x16_bf16 v[18:33], v[172:175], v[184:187], v[18:33]
	v_mfma_f32_32x32x16_bf16 v[34:49], v[188:191], v[176:179], v[34:49]
	v_mfma_f32_32x32x16_bf16 v[50:65], v[188:191], v[184:187], v[50:65]
	ds_read_b128 v[76:79], v72 offset:18432
	ds_read_b128 v[80:83], v73 offset:55296
	ds_read_b128 v[84:87], v72 offset:18464
	ds_read_b128 v[88:91], v73 offset:55328
	ds_read_b128 v[148:151], v73 offset:59904
	ds_read_b128 v[152:155], v73 offset:59936
	v_or_b32_e32 v66, s8, v93
	s_waitcnt lgkmcnt(4)
	v_mfma_f32_32x32x16_bf16 v[2:17], v[76:79], v[80:83], v[2:17]
	s_lshl_b32 s10, s10, 1
	s_mov_b32 s11, s9
	s_add_i32 s13, s13, s12
	s_add_i32 s14, s14, s15
	s_add_i32 s16, s16, s17
	s_cmpk_lt_u32 s13, 0x400
	s_waitcnt lgkmcnt(1)
	v_mfma_f32_32x32x16_bf16 v[18:33], v[76:79], v[148:151], v[18:33]
	ds_read_b128 v[76:79], v72 offset:23040
	ds_read_b128 v[156:159], v72 offset:23072
	s_waitcnt lgkmcnt(1)
	v_mfma_f32_32x32x16_bf16 v[34:49], v[76:79], v[80:83], v[34:49]
	v_mfma_f32_32x32x16_bf16 v[50:65], v[76:79], v[148:151], v[50:65]
	v_mfma_f32_32x32x16_bf16 v[2:17], v[84:87], v[88:91], v[2:17]
	v_mfma_f32_32x32x16_bf16 v[18:33], v[84:87], v[152:155], v[18:33]
	s_waitcnt lgkmcnt(0)
	v_mfma_f32_32x32x16_bf16 v[34:49], v[156:159], v[88:91], v[34:49]
	ds_read_b128 v[76:79], v72 offset:18496
	ds_read_b128 v[80:83], v73 offset:55360
	ds_read_b128 v[84:87], v72 offset:18528
	ds_read_b128 v[88:91], v73 offset:55392
	v_mfma_f32_32x32x16_bf16 v[50:65], v[156:159], v[152:155], v[50:65]
	ds_read_b128 v[148:151], v73 offset:59968
	ds_read_b128 v[152:155], v73 offset:60000
	s_waitcnt lgkmcnt(4)
	v_mfma_f32_32x32x16_bf16 v[2:17], v[76:79], v[80:83], v[2:17]
	s_waitcnt lgkmcnt(1)
	v_mfma_f32_32x32x16_bf16 v[18:33], v[76:79], v[148:151], v[18:33]
	ds_read_b128 v[76:79], v72 offset:23104
	ds_read_b128 v[156:159], v72 offset:23136
	s_waitcnt lgkmcnt(0)
	s_barrier
	v_mfma_f32_32x32x16_bf16 v[34:49], v[76:79], v[80:83], v[34:49]
	v_mfma_f32_32x32x16_bf16 v[50:65], v[76:79], v[148:151], v[50:65]
	v_mfma_f32_32x32x16_bf16 v[2:17], v[84:87], v[88:91], v[2:17]
	v_mfma_f32_32x32x16_bf16 v[18:33], v[84:87], v[152:155], v[18:33]
	v_mfma_f32_32x32x16_bf16 v[34:49], v[156:159], v[88:91], v[34:49]
	s_nop 10
	ds_write2_b32 v101, v2, v18 offset1:32
	v_mfma_f32_32x32x16_bf16 v[50:65], v[156:159], v[152:155], v[50:65]
	s_nop 11
	ds_write2_b32 v132, v34, v50 offset0:32 offset1:64
	ds_write2_b32 v101, v3, v19 offset0:129 offset1:161
	ds_write2_b32 v132, v35, v51 offset0:161 offset1:193
	ds_write2_b32 v133, v4, v20 offset0:2 offset1:34
	ds_write2_b32 v134, v36, v52 offset0:34 offset1:66
	ds_write2_b32 v133, v5, v21 offset0:131 offset1:163
	ds_write2_b32 v134, v37, v53 offset0:163 offset1:195
	ds_write2_b32 v135, v6, v22 offset0:8 offset1:40
	ds_write2_b32 v136, v38, v54 offset0:40 offset1:72
	ds_write2_b32 v135, v7, v23 offset0:137 offset1:169
	ds_write2_b32 v136, v39, v55 offset0:169 offset1:201
	ds_write2_b32 v137, v8, v24 offset0:10 offset1:42
	ds_write2_b32 v138, v40, v56 offset0:42 offset1:74
	ds_write2_b32 v137, v9, v25 offset0:139 offset1:171
	ds_write2_b32 v138, v41, v57 offset0:171 offset1:203
	ds_write2_b32 v139, v10, v26 offset0:16 offset1:48
	ds_write2_b32 v140, v42, v58 offset0:48 offset1:80
	ds_write2_b32 v139, v11, v27 offset0:145 offset1:177
	ds_write2_b32 v140, v43, v59 offset0:177 offset1:209
	ds_write2_b32 v141, v12, v28 offset0:18 offset1:50
	ds_write2_b32 v142, v44, v60 offset0:50 offset1:82
	ds_write2_b32 v141, v13, v29 offset0:147 offset1:179
	ds_write2_b32 v142, v45, v61 offset0:179 offset1:211
	ds_write2_b32 v143, v14, v30 offset0:24 offset1:56
	ds_write2_b32 v144, v46, v62 offset0:56 offset1:88
	ds_write2_b32 v143, v15, v31 offset0:153 offset1:185
	ds_write2_b32 v144, v47, v63 offset0:185 offset1:217
	ds_write2_b32 v145, v16, v32 offset0:26 offset1:58
	ds_write2_b32 v146, v48, v64 offset0:58 offset1:90
	ds_write2_b32 v145, v17, v33 offset0:155 offset1:187
	ds_write2_b32 v146, v49, v65 offset0:187 offset1:219
	v_lshl_add_u64 v[2:3], v[66:67], 2, s[6:7]
	s_waitcnt lgkmcnt(0)
	s_barrier
	v_and_b32_e32 v230, 0x3ff, v0
	v_and_b32_e32 v231, 63, v230
	v_lshrrev_b32_e32 v232, 6, v230
	v_and_b32_e32 v233, 7, v231
	v_and_b32_e32 v234, 1, v232
	v_lshl_add_u32 v233, v234, 3, v233
	v_lshrrev_b32_e32 v235, 3, v231
	v_lshrrev_b32_e32 v234, 1, v232
	v_lshl_add_u32 v235, v234, 3, v235
	v_lshrrev_b32_e32 v234, 4, v230
	v_sub_u32_e32 v236, v66, v234
	v_add_u32_e32 v236, v236, v233
	v_mul_u32_u24_e32 v237, 0x204, v233
	v_lshl_add_u32 v237, v235, 5, v237
	v_lshlrev_b32_e32 v238, 4, v235
	v_mov_b32_e32 v2, v236
	v_lshlrev_b32_e32 v3, 2, v2
	global_load_dword v5, v3, s[6:7]
	global_load_dword v6, v3, s[6:7] offset:64
	global_load_dword v7, v3, s[6:7] offset:128
	global_load_dword v8, v3, s[6:7] offset:192
	global_load_dword v9, v3, s[6:7] offset:256
	global_load_dword v10, v3, s[6:7] offset:320
	global_load_dword v11, v3, s[6:7] offset:384
	global_load_dword v12, v3, s[6:7] offset:448
	v_lshlrev_b32_e32 v4, 13, v2
	v_add3_u32 v4, v4, v238, s10
	s_movk_i32 s24, 0x7fff
	v_mov_b32_e32 v59, 1
	v_mov_b32_e32 v13, 0x358637bd
	ds_read2_b32 v[14:15], v237 offset0:0 offset1:1
	ds_read2_b32 v[16:17], v237 offset0:2 offset1:3
	ds_read2_b32 v[18:19], v237 offset0:4 offset1:5
	ds_read2_b32 v[20:21], v237 offset0:6 offset1:7
	v_add_u32_e32 v56, 0x2040, v237
	ds_read2_b32 v[22:23], v56 offset0:0 offset1:1
	ds_read2_b32 v[24:25], v56 offset0:2 offset1:3
	ds_read2_b32 v[26:27], v56 offset0:4 offset1:5
	ds_read2_b32 v[28:29], v56 offset0:6 offset1:7
	s_waitcnt vmcnt(7) lgkmcnt(4)
	v_fmamk_f32 v54, v5, 0x3a800000, v13
	v_rsq_f32_e32 v54, v54
	s_nop 0
	v_mul_f32_e32 v14, v14, v54
	v_mul_f32_e32 v15, v15, v54
	v_mul_f32_e32 v16, v16, v54
	v_mul_f32_e32 v17, v17, v54
	v_mul_f32_e32 v18, v18, v54
	v_mul_f32_e32 v19, v19, v54
	v_mul_f32_e32 v20, v20, v54
	v_mul_f32_e32 v21, v21, v54
	v_max_f32_e32 v14, 0, v14
	v_max_f32_e32 v15, 0, v15
	v_max_f32_e32 v16, 0, v16
	v_max_f32_e32 v17, 0, v17
	v_max_f32_e32 v18, 0, v18
	v_max_f32_e32 v19, 0, v19
	v_max_f32_e32 v20, 0, v20
	v_max_f32_e32 v21, 0, v21
	v_pk_mul_f32 v[14:15], v[14:15], v[14:15]
	v_pk_mul_f32 v[16:17], v[16:17], v[16:17]
	v_pk_mul_f32 v[18:19], v[18:19], v[18:19]
	v_pk_mul_f32 v[20:21], v[20:21], v[20:21]
	v_and_b32_sdwa v46, v14, v59 dst_sel:DWORD dst_unused:UNUSED_PAD src0_sel:WORD_1 src1_sel:DWORD
	v_and_b32_sdwa v47, v15, v59 dst_sel:DWORD dst_unused:UNUSED_PAD src0_sel:WORD_1 src1_sel:DWORD
	v_and_b32_sdwa v48, v16, v59 dst_sel:DWORD dst_unused:UNUSED_PAD src0_sel:WORD_1 src1_sel:DWORD
	v_and_b32_sdwa v49, v17, v59 dst_sel:DWORD dst_unused:UNUSED_PAD src0_sel:WORD_1 src1_sel:DWORD
	v_and_b32_sdwa v50, v18, v59 dst_sel:DWORD dst_unused:UNUSED_PAD src0_sel:WORD_1 src1_sel:DWORD
	v_and_b32_sdwa v51, v19, v59 dst_sel:DWORD dst_unused:UNUSED_PAD src0_sel:WORD_1 src1_sel:DWORD
	v_and_b32_sdwa v52, v20, v59 dst_sel:DWORD dst_unused:UNUSED_PAD src0_sel:WORD_1 src1_sel:DWORD
	v_and_b32_sdwa v53, v21, v59 dst_sel:DWORD dst_unused:UNUSED_PAD src0_sel:WORD_1 src1_sel:DWORD
	v_add3_u32 v14, v14, v46, s24
	v_add3_u32 v15, v15, v47, s24
	v_add3_u32 v16, v16, v48, s24
	v_add3_u32 v17, v17, v49, s24
	v_add3_u32 v18, v18, v50, s24
	v_add3_u32 v19, v19, v51, s24
	v_add3_u32 v20, v20, v52, s24
	v_add3_u32 v21, v21, v53, s24
	v_and_b32_e32 v15, 0xffff0000, v15
	v_and_b32_e32 v17, 0xffff0000, v17
	v_and_b32_e32 v19, 0xffff0000, v19
	v_and_b32_e32 v21, 0xffff0000, v21
	v_or_b32_sdwa v60, v15, v14 dst_sel:DWORD dst_unused:UNUSED_PAD src0_sel:DWORD src1_sel:WORD_1
	v_or_b32_sdwa v61, v17, v16 dst_sel:DWORD dst_unused:UNUSED_PAD src0_sel:DWORD src1_sel:WORD_1
	v_or_b32_sdwa v62, v19, v18 dst_sel:DWORD dst_unused:UNUSED_PAD src0_sel:DWORD src1_sel:WORD_1
	v_or_b32_sdwa v63, v21, v20 dst_sel:DWORD dst_unused:UNUSED_PAD src0_sel:DWORD src1_sel:WORD_1
	global_store_dwordx4 v4, v[60:63], s[56:57]
	v_add_u32_e32 v55, 0x4080, v237
	ds_read2_b32 v[30:31], v55 offset0:0 offset1:1
	ds_read2_b32 v[32:33], v55 offset0:2 offset1:3
	ds_read2_b32 v[34:35], v55 offset0:4 offset1:5
	ds_read2_b32 v[36:37], v55 offset0:6 offset1:7
	v_add_u32_e32 v56, 0x60c0, v237
	ds_read2_b32 v[38:39], v56 offset0:0 offset1:1
	ds_read2_b32 v[40:41], v56 offset0:2 offset1:3
	ds_read2_b32 v[42:43], v56 offset0:4 offset1:5
	ds_read2_b32 v[44:45], v56 offset0:6 offset1:7
	s_waitcnt vmcnt(7) lgkmcnt(8)
	v_fmamk_f32 v54, v6, 0x3a800000, v13
	v_rsq_f32_e32 v54, v54
	v_add_u32_e32 v58, 0x20000, v4
	v_mul_f32_e32 v22, v22, v54
	v_mul_f32_e32 v23, v23, v54
	v_mul_f32_e32 v24, v24, v54
	v_mul_f32_e32 v25, v25, v54
	v_mul_f32_e32 v26, v26, v54
	v_mul_f32_e32 v27, v27, v54
	v_mul_f32_e32 v28, v28, v54
	v_mul_f32_e32 v29, v29, v54
	v_max_f32_e32 v22, 0, v22
	v_max_f32_e32 v23, 0, v23
	v_max_f32_e32 v24, 0, v24
	v_max_f32_e32 v25, 0, v25
	v_max_f32_e32 v26, 0, v26
	v_max_f32_e32 v27, 0, v27
	v_max_f32_e32 v28, 0, v28
	v_max_f32_e32 v29, 0, v29
	v_pk_mul_f32 v[22:23], v[22:23], v[22:23]
	v_pk_mul_f32 v[24:25], v[24:25], v[24:25]
	v_pk_mul_f32 v[26:27], v[26:27], v[26:27]
	v_pk_mul_f32 v[28:29], v[28:29], v[28:29]
	v_and_b32_sdwa v46, v22, v59 dst_sel:DWORD dst_unused:UNUSED_PAD src0_sel:WORD_1 src1_sel:DWORD
	v_and_b32_sdwa v47, v23, v59 dst_sel:DWORD dst_unused:UNUSED_PAD src0_sel:WORD_1 src1_sel:DWORD
	v_and_b32_sdwa v48, v24, v59 dst_sel:DWORD dst_unused:UNUSED_PAD src0_sel:WORD_1 src1_sel:DWORD
	v_and_b32_sdwa v49, v25, v59 dst_sel:DWORD dst_unused:UNUSED_PAD src0_sel:WORD_1 src1_sel:DWORD
	v_and_b32_sdwa v50, v26, v59 dst_sel:DWORD dst_unused:UNUSED_PAD src0_sel:WORD_1 src1_sel:DWORD
	v_and_b32_sdwa v51, v27, v59 dst_sel:DWORD dst_unused:UNUSED_PAD src0_sel:WORD_1 src1_sel:DWORD
	v_and_b32_sdwa v52, v28, v59 dst_sel:DWORD dst_unused:UNUSED_PAD src0_sel:WORD_1 src1_sel:DWORD
	v_and_b32_sdwa v53, v29, v59 dst_sel:DWORD dst_unused:UNUSED_PAD src0_sel:WORD_1 src1_sel:DWORD
	v_add3_u32 v22, v22, v46, s24
	v_add3_u32 v23, v23, v47, s24
	v_add3_u32 v24, v24, v48, s24
	v_add3_u32 v25, v25, v49, s24
	v_add3_u32 v26, v26, v50, s24
	v_add3_u32 v27, v27, v51, s24
	v_add3_u32 v28, v28, v52, s24
	v_add3_u32 v29, v29, v53, s24
	v_and_b32_e32 v23, 0xffff0000, v23
	v_and_b32_e32 v25, 0xffff0000, v25
	v_and_b32_e32 v27, 0xffff0000, v27
	v_and_b32_e32 v29, 0xffff0000, v29
	v_or_b32_sdwa v76, v23, v22 dst_sel:DWORD dst_unused:UNUSED_PAD src0_sel:DWORD src1_sel:WORD_1
	v_or_b32_sdwa v77, v25, v24 dst_sel:DWORD dst_unused:UNUSED_PAD src0_sel:DWORD src1_sel:WORD_1
	v_or_b32_sdwa v78, v27, v26 dst_sel:DWORD dst_unused:UNUSED_PAD src0_sel:DWORD src1_sel:WORD_1
	v_or_b32_sdwa v79, v29, v28 dst_sel:DWORD dst_unused:UNUSED_PAD src0_sel:DWORD src1_sel:WORD_1
	global_store_dwordx4 v58, v[76:79], s[56:57]
	s_waitcnt vmcnt(7) lgkmcnt(4)
	v_fmamk_f32 v54, v7, 0x3a800000, v13
	v_rsq_f32_e32 v54, v54
	v_add_u32_e32 v57, 0x40000, v4
	v_mul_f32_e32 v30, v30, v54
	v_mul_f32_e32 v31, v31, v54
	v_mul_f32_e32 v32, v32, v54
	v_mul_f32_e32 v33, v33, v54
	v_mul_f32_e32 v34, v34, v54
	v_mul_f32_e32 v35, v35, v54
	v_mul_f32_e32 v36, v36, v54
	v_mul_f32_e32 v37, v37, v54
	v_max_f32_e32 v30, 0, v30
	v_max_f32_e32 v31, 0, v31
	v_max_f32_e32 v32, 0, v32
	v_max_f32_e32 v33, 0, v33
	v_max_f32_e32 v34, 0, v34
	v_max_f32_e32 v35, 0, v35
	v_max_f32_e32 v36, 0, v36
	v_max_f32_e32 v37, 0, v37
	v_pk_mul_f32 v[30:31], v[30:31], v[30:31]
	v_pk_mul_f32 v[32:33], v[32:33], v[32:33]
	v_pk_mul_f32 v[34:35], v[34:35], v[34:35]
	v_pk_mul_f32 v[36:37], v[36:37], v[36:37]
	v_and_b32_sdwa v46, v30, v59 dst_sel:DWORD dst_unused:UNUSED_PAD src0_sel:WORD_1 src1_sel:DWORD
	v_and_b32_sdwa v47, v31, v59 dst_sel:DWORD dst_unused:UNUSED_PAD src0_sel:WORD_1 src1_sel:DWORD
	v_and_b32_sdwa v48, v32, v59 dst_sel:DWORD dst_unused:UNUSED_PAD src0_sel:WORD_1 src1_sel:DWORD
	v_and_b32_sdwa v49, v33, v59 dst_sel:DWORD dst_unused:UNUSED_PAD src0_sel:WORD_1 src1_sel:DWORD
	v_and_b32_sdwa v50, v34, v59 dst_sel:DWORD dst_unused:UNUSED_PAD src0_sel:WORD_1 src1_sel:DWORD
	v_and_b32_sdwa v51, v35, v59 dst_sel:DWORD dst_unused:UNUSED_PAD src0_sel:WORD_1 src1_sel:DWORD
	v_and_b32_sdwa v52, v36, v59 dst_sel:DWORD dst_unused:UNUSED_PAD src0_sel:WORD_1 src1_sel:DWORD
	v_and_b32_sdwa v53, v37, v59 dst_sel:DWORD dst_unused:UNUSED_PAD src0_sel:WORD_1 src1_sel:DWORD
	v_add3_u32 v30, v30, v46, s24
	v_add3_u32 v31, v31, v47, s24
	v_add3_u32 v32, v32, v48, s24
	v_add3_u32 v33, v33, v49, s24
	v_add3_u32 v34, v34, v50, s24
	v_add3_u32 v35, v35, v51, s24
	v_add3_u32 v36, v36, v52, s24
	v_add3_u32 v37, v37, v53, s24
	v_and_b32_e32 v31, 0xffff0000, v31
	v_and_b32_e32 v33, 0xffff0000, v33
	v_and_b32_e32 v35, 0xffff0000, v35
	v_and_b32_e32 v37, 0xffff0000, v37
	v_or_b32_sdwa v60, v31, v30 dst_sel:DWORD dst_unused:UNUSED_PAD src0_sel:DWORD src1_sel:WORD_1
	v_or_b32_sdwa v61, v33, v32 dst_sel:DWORD dst_unused:UNUSED_PAD src0_sel:DWORD src1_sel:WORD_1
	v_or_b32_sdwa v62, v35, v34 dst_sel:DWORD dst_unused:UNUSED_PAD src0_sel:DWORD src1_sel:WORD_1
	v_or_b32_sdwa v63, v37, v36 dst_sel:DWORD dst_unused:UNUSED_PAD src0_sel:DWORD src1_sel:WORD_1
	global_store_dwordx4 v57, v[60:63], s[56:57]
	v_add_u32_e32 v55, 0x8100, v237
	ds_read2_b32 v[14:15], v55 offset0:0 offset1:1
	ds_read2_b32 v[16:17], v55 offset0:2 offset1:3
	ds_read2_b32 v[18:19], v55 offset0:4 offset1:5
	ds_read2_b32 v[20:21], v55 offset0:6 offset1:7
	v_add_u32_e32 v56, 0xa140, v237
	ds_read2_b32 v[22:23], v56 offset0:0 offset1:1
	ds_read2_b32 v[24:25], v56 offset0:2 offset1:3
	ds_read2_b32 v[26:27], v56 offset0:4 offset1:5
	ds_read2_b32 v[28:29], v56 offset0:6 offset1:7
	s_waitcnt vmcnt(7) lgkmcnt(8)
	v_fmamk_f32 v54, v8, 0x3a800000, v13
	v_rsq_f32_e32 v54, v54
	v_add_u32_e32 v58, 0x60000, v4
	v_mul_f32_e32 v38, v38, v54
	v_mul_f32_e32 v39, v39, v54
	v_mul_f32_e32 v40, v40, v54
	v_mul_f32_e32 v41, v41, v54
	v_mul_f32_e32 v42, v42, v54
	v_mul_f32_e32 v43, v43, v54
	v_mul_f32_e32 v44, v44, v54
	v_mul_f32_e32 v45, v45, v54
	v_max_f32_e32 v38, 0, v38
	v_max_f32_e32 v39, 0, v39
	v_max_f32_e32 v40, 0, v40
	v_max_f32_e32 v41, 0, v41
	v_max_f32_e32 v42, 0, v42
	v_max_f32_e32 v43, 0, v43
	v_max_f32_e32 v44, 0, v44
	v_max_f32_e32 v45, 0, v45
	v_pk_mul_f32 v[38:39], v[38:39], v[38:39]
	v_pk_mul_f32 v[40:41], v[40:41], v[40:41]
	v_pk_mul_f32 v[42:43], v[42:43], v[42:43]
	v_pk_mul_f32 v[44:45], v[44:45], v[44:45]
	v_and_b32_sdwa v46, v38, v59 dst_sel:DWORD dst_unused:UNUSED_PAD src0_sel:WORD_1 src1_sel:DWORD
	v_and_b32_sdwa v47, v39, v59 dst_sel:DWORD dst_unused:UNUSED_PAD src0_sel:WORD_1 src1_sel:DWORD
	v_and_b32_sdwa v48, v40, v59 dst_sel:DWORD dst_unused:UNUSED_PAD src0_sel:WORD_1 src1_sel:DWORD
	v_and_b32_sdwa v49, v41, v59 dst_sel:DWORD dst_unused:UNUSED_PAD src0_sel:WORD_1 src1_sel:DWORD
	v_and_b32_sdwa v50, v42, v59 dst_sel:DWORD dst_unused:UNUSED_PAD src0_sel:WORD_1 src1_sel:DWORD
	v_and_b32_sdwa v51, v43, v59 dst_sel:DWORD dst_unused:UNUSED_PAD src0_sel:WORD_1 src1_sel:DWORD
	v_and_b32_sdwa v52, v44, v59 dst_sel:DWORD dst_unused:UNUSED_PAD src0_sel:WORD_1 src1_sel:DWORD
	v_and_b32_sdwa v53, v45, v59 dst_sel:DWORD dst_unused:UNUSED_PAD src0_sel:WORD_1 src1_sel:DWORD
	v_add3_u32 v38, v38, v46, s24
	v_add3_u32 v39, v39, v47, s24
	v_add3_u32 v40, v40, v48, s24
	v_add3_u32 v41, v41, v49, s24
	v_add3_u32 v42, v42, v50, s24
	v_add3_u32 v43, v43, v51, s24
	v_add3_u32 v44, v44, v52, s24
	v_add3_u32 v45, v45, v53, s24
	v_and_b32_e32 v39, 0xffff0000, v39
	v_and_b32_e32 v41, 0xffff0000, v41
	v_and_b32_e32 v43, 0xffff0000, v43
	v_and_b32_e32 v45, 0xffff0000, v45
	v_or_b32_sdwa v76, v39, v38 dst_sel:DWORD dst_unused:UNUSED_PAD src0_sel:DWORD src1_sel:WORD_1
	v_or_b32_sdwa v77, v41, v40 dst_sel:DWORD dst_unused:UNUSED_PAD src0_sel:DWORD src1_sel:WORD_1
	v_or_b32_sdwa v78, v43, v42 dst_sel:DWORD dst_unused:UNUSED_PAD src0_sel:DWORD src1_sel:WORD_1
	v_or_b32_sdwa v79, v45, v44 dst_sel:DWORD dst_unused:UNUSED_PAD src0_sel:DWORD src1_sel:WORD_1
	global_store_dwordx4 v58, v[76:79], s[56:57]
	s_waitcnt vmcnt(7) lgkmcnt(4)
	v_fmamk_f32 v54, v9, 0x3a800000, v13
	v_rsq_f32_e32 v54, v54
	v_add_u32_e32 v57, 0x80000, v4
	v_mul_f32_e32 v14, v14, v54
	v_mul_f32_e32 v15, v15, v54
	v_mul_f32_e32 v16, v16, v54
	v_mul_f32_e32 v17, v17, v54
	v_mul_f32_e32 v18, v18, v54
	v_mul_f32_e32 v19, v19, v54
	v_mul_f32_e32 v20, v20, v54
	v_mul_f32_e32 v21, v21, v54
	v_max_f32_e32 v14, 0, v14
	v_max_f32_e32 v15, 0, v15
	v_max_f32_e32 v16, 0, v16
	v_max_f32_e32 v17, 0, v17
	v_max_f32_e32 v18, 0, v18
	v_max_f32_e32 v19, 0, v19
	v_max_f32_e32 v20, 0, v20
	v_max_f32_e32 v21, 0, v21
	v_pk_mul_f32 v[14:15], v[14:15], v[14:15]
	v_pk_mul_f32 v[16:17], v[16:17], v[16:17]
	v_pk_mul_f32 v[18:19], v[18:19], v[18:19]
	v_pk_mul_f32 v[20:21], v[20:21], v[20:21]
	v_and_b32_sdwa v46, v14, v59 dst_sel:DWORD dst_unused:UNUSED_PAD src0_sel:WORD_1 src1_sel:DWORD
	v_and_b32_sdwa v47, v15, v59 dst_sel:DWORD dst_unused:UNUSED_PAD src0_sel:WORD_1 src1_sel:DWORD
	v_and_b32_sdwa v48, v16, v59 dst_sel:DWORD dst_unused:UNUSED_PAD src0_sel:WORD_1 src1_sel:DWORD
	v_and_b32_sdwa v49, v17, v59 dst_sel:DWORD dst_unused:UNUSED_PAD src0_sel:WORD_1 src1_sel:DWORD
	v_and_b32_sdwa v50, v18, v59 dst_sel:DWORD dst_unused:UNUSED_PAD src0_sel:WORD_1 src1_sel:DWORD
	v_and_b32_sdwa v51, v19, v59 dst_sel:DWORD dst_unused:UNUSED_PAD src0_sel:WORD_1 src1_sel:DWORD
	v_and_b32_sdwa v52, v20, v59 dst_sel:DWORD dst_unused:UNUSED_PAD src0_sel:WORD_1 src1_sel:DWORD
	v_and_b32_sdwa v53, v21, v59 dst_sel:DWORD dst_unused:UNUSED_PAD src0_sel:WORD_1 src1_sel:DWORD
	v_add3_u32 v14, v14, v46, s24
	v_add3_u32 v15, v15, v47, s24
	v_add3_u32 v16, v16, v48, s24
	v_add3_u32 v17, v17, v49, s24
	v_add3_u32 v18, v18, v50, s24
	v_add3_u32 v19, v19, v51, s24
	v_add3_u32 v20, v20, v52, s24
	v_add3_u32 v21, v21, v53, s24
	v_and_b32_e32 v15, 0xffff0000, v15
	v_and_b32_e32 v17, 0xffff0000, v17
	v_and_b32_e32 v19, 0xffff0000, v19
	v_and_b32_e32 v21, 0xffff0000, v21
	v_or_b32_sdwa v60, v15, v14 dst_sel:DWORD dst_unused:UNUSED_PAD src0_sel:DWORD src1_sel:WORD_1
	v_or_b32_sdwa v61, v17, v16 dst_sel:DWORD dst_unused:UNUSED_PAD src0_sel:DWORD src1_sel:WORD_1
	v_or_b32_sdwa v62, v19, v18 dst_sel:DWORD dst_unused:UNUSED_PAD src0_sel:DWORD src1_sel:WORD_1
	v_or_b32_sdwa v63, v21, v20 dst_sel:DWORD dst_unused:UNUSED_PAD src0_sel:DWORD src1_sel:WORD_1
	global_store_dwordx4 v57, v[60:63], s[56:57]
	v_add_u32_e32 v55, 0xc180, v237
	ds_read2_b32 v[30:31], v55 offset0:0 offset1:1
	ds_read2_b32 v[32:33], v55 offset0:2 offset1:3
	ds_read2_b32 v[34:35], v55 offset0:4 offset1:5
	ds_read2_b32 v[36:37], v55 offset0:6 offset1:7
	v_add_u32_e32 v56, 0xe1c0, v237
	ds_read2_b32 v[38:39], v56 offset0:0 offset1:1
	ds_read2_b32 v[40:41], v56 offset0:2 offset1:3
	ds_read2_b32 v[42:43], v56 offset0:4 offset1:5
	ds_read2_b32 v[44:45], v56 offset0:6 offset1:7
	s_waitcnt vmcnt(7) lgkmcnt(8)
	v_fmamk_f32 v54, v10, 0x3a800000, v13
	v_rsq_f32_e32 v54, v54
	v_add_u32_e32 v58, 0xa0000, v4
	v_mul_f32_e32 v22, v22, v54
	v_mul_f32_e32 v23, v23, v54
	v_mul_f32_e32 v24, v24, v54
	v_mul_f32_e32 v25, v25, v54
	v_mul_f32_e32 v26, v26, v54
	v_mul_f32_e32 v27, v27, v54
	v_mul_f32_e32 v28, v28, v54
	v_mul_f32_e32 v29, v29, v54
	v_max_f32_e32 v22, 0, v22
	v_max_f32_e32 v23, 0, v23
	v_max_f32_e32 v24, 0, v24
	v_max_f32_e32 v25, 0, v25
	v_max_f32_e32 v26, 0, v26
	v_max_f32_e32 v27, 0, v27
	v_max_f32_e32 v28, 0, v28
	v_max_f32_e32 v29, 0, v29
	v_pk_mul_f32 v[22:23], v[22:23], v[22:23]
	v_pk_mul_f32 v[24:25], v[24:25], v[24:25]
	v_pk_mul_f32 v[26:27], v[26:27], v[26:27]
	v_pk_mul_f32 v[28:29], v[28:29], v[28:29]
	v_and_b32_sdwa v46, v22, v59 dst_sel:DWORD dst_unused:UNUSED_PAD src0_sel:WORD_1 src1_sel:DWORD
	v_and_b32_sdwa v47, v23, v59 dst_sel:DWORD dst_unused:UNUSED_PAD src0_sel:WORD_1 src1_sel:DWORD
	v_and_b32_sdwa v48, v24, v59 dst_sel:DWORD dst_unused:UNUSED_PAD src0_sel:WORD_1 src1_sel:DWORD
	v_and_b32_sdwa v49, v25, v59 dst_sel:DWORD dst_unused:UNUSED_PAD src0_sel:WORD_1 src1_sel:DWORD
	v_and_b32_sdwa v50, v26, v59 dst_sel:DWORD dst_unused:UNUSED_PAD src0_sel:WORD_1 src1_sel:DWORD
	v_and_b32_sdwa v51, v27, v59 dst_sel:DWORD dst_unused:UNUSED_PAD src0_sel:WORD_1 src1_sel:DWORD
	v_and_b32_sdwa v52, v28, v59 dst_sel:DWORD dst_unused:UNUSED_PAD src0_sel:WORD_1 src1_sel:DWORD
	v_and_b32_sdwa v53, v29, v59 dst_sel:DWORD dst_unused:UNUSED_PAD src0_sel:WORD_1 src1_sel:DWORD
	v_add3_u32 v22, v22, v46, s24
	v_add3_u32 v23, v23, v47, s24
	v_add3_u32 v24, v24, v48, s24
	v_add3_u32 v25, v25, v49, s24
	v_add3_u32 v26, v26, v50, s24
	v_add3_u32 v27, v27, v51, s24
	v_add3_u32 v28, v28, v52, s24
	v_add3_u32 v29, v29, v53, s24
	v_and_b32_e32 v23, 0xffff0000, v23
	v_and_b32_e32 v25, 0xffff0000, v25
	v_and_b32_e32 v27, 0xffff0000, v27
	v_and_b32_e32 v29, 0xffff0000, v29
	v_or_b32_sdwa v76, v23, v22 dst_sel:DWORD dst_unused:UNUSED_PAD src0_sel:DWORD src1_sel:WORD_1
	v_or_b32_sdwa v77, v25, v24 dst_sel:DWORD dst_unused:UNUSED_PAD src0_sel:DWORD src1_sel:WORD_1
	v_or_b32_sdwa v78, v27, v26 dst_sel:DWORD dst_unused:UNUSED_PAD src0_sel:DWORD src1_sel:WORD_1
	v_or_b32_sdwa v79, v29, v28 dst_sel:DWORD dst_unused:UNUSED_PAD src0_sel:DWORD src1_sel:WORD_1
	global_store_dwordx4 v58, v[76:79], s[56:57]
	s_waitcnt vmcnt(7) lgkmcnt(4)
	v_fmamk_f32 v54, v11, 0x3a800000, v13
	v_rsq_f32_e32 v54, v54
	v_add_u32_e32 v57, 0xc0000, v4
	v_mul_f32_e32 v30, v30, v54
	v_mul_f32_e32 v31, v31, v54
	v_mul_f32_e32 v32, v32, v54
	v_mul_f32_e32 v33, v33, v54
	v_mul_f32_e32 v34, v34, v54
	v_mul_f32_e32 v35, v35, v54
	v_mul_f32_e32 v36, v36, v54
	v_mul_f32_e32 v37, v37, v54
	v_max_f32_e32 v30, 0, v30
	v_max_f32_e32 v31, 0, v31
	v_max_f32_e32 v32, 0, v32
	v_max_f32_e32 v33, 0, v33
	v_max_f32_e32 v34, 0, v34
	v_max_f32_e32 v35, 0, v35
	v_max_f32_e32 v36, 0, v36
	v_max_f32_e32 v37, 0, v37
	v_pk_mul_f32 v[30:31], v[30:31], v[30:31]
	v_pk_mul_f32 v[32:33], v[32:33], v[32:33]
	v_pk_mul_f32 v[34:35], v[34:35], v[34:35]
	v_pk_mul_f32 v[36:37], v[36:37], v[36:37]
	v_and_b32_sdwa v46, v30, v59 dst_sel:DWORD dst_unused:UNUSED_PAD src0_sel:WORD_1 src1_sel:DWORD
	v_and_b32_sdwa v47, v31, v59 dst_sel:DWORD dst_unused:UNUSED_PAD src0_sel:WORD_1 src1_sel:DWORD
	v_and_b32_sdwa v48, v32, v59 dst_sel:DWORD dst_unused:UNUSED_PAD src0_sel:WORD_1 src1_sel:DWORD
	v_and_b32_sdwa v49, v33, v59 dst_sel:DWORD dst_unused:UNUSED_PAD src0_sel:WORD_1 src1_sel:DWORD
	v_and_b32_sdwa v50, v34, v59 dst_sel:DWORD dst_unused:UNUSED_PAD src0_sel:WORD_1 src1_sel:DWORD
	v_and_b32_sdwa v51, v35, v59 dst_sel:DWORD dst_unused:UNUSED_PAD src0_sel:WORD_1 src1_sel:DWORD
	v_and_b32_sdwa v52, v36, v59 dst_sel:DWORD dst_unused:UNUSED_PAD src0_sel:WORD_1 src1_sel:DWORD
	v_and_b32_sdwa v53, v37, v59 dst_sel:DWORD dst_unused:UNUSED_PAD src0_sel:WORD_1 src1_sel:DWORD
	v_add3_u32 v30, v30, v46, s24
	v_add3_u32 v31, v31, v47, s24
	v_add3_u32 v32, v32, v48, s24
	v_add3_u32 v33, v33, v49, s24
	v_add3_u32 v34, v34, v50, s24
	v_add3_u32 v35, v35, v51, s24
	v_add3_u32 v36, v36, v52, s24
	v_add3_u32 v37, v37, v53, s24
	v_and_b32_e32 v31, 0xffff0000, v31
	v_and_b32_e32 v33, 0xffff0000, v33
	v_and_b32_e32 v35, 0xffff0000, v35
	v_and_b32_e32 v37, 0xffff0000, v37
	v_or_b32_sdwa v60, v31, v30 dst_sel:DWORD dst_unused:UNUSED_PAD src0_sel:DWORD src1_sel:WORD_1
	v_or_b32_sdwa v61, v33, v32 dst_sel:DWORD dst_unused:UNUSED_PAD src0_sel:DWORD src1_sel:WORD_1
	v_or_b32_sdwa v62, v35, v34 dst_sel:DWORD dst_unused:UNUSED_PAD src0_sel:DWORD src1_sel:WORD_1
	v_or_b32_sdwa v63, v37, v36 dst_sel:DWORD dst_unused:UNUSED_PAD src0_sel:DWORD src1_sel:WORD_1
	global_store_dwordx4 v57, v[60:63], s[56:57]
	s_waitcnt vmcnt(7) lgkmcnt(0)
	v_fmamk_f32 v54, v12, 0x3a800000, v13
	v_rsq_f32_e32 v54, v54
	v_add_u32_e32 v58, 0xe0000, v4
	v_mul_f32_e32 v38, v38, v54
	v_mul_f32_e32 v39, v39, v54
	v_mul_f32_e32 v40, v40, v54
	v_mul_f32_e32 v41, v41, v54
	v_mul_f32_e32 v42, v42, v54
	v_mul_f32_e32 v43, v43, v54
	v_mul_f32_e32 v44, v44, v54
	v_mul_f32_e32 v45, v45, v54
	v_max_f32_e32 v38, 0, v38
	v_max_f32_e32 v39, 0, v39
	v_max_f32_e32 v40, 0, v40
	v_max_f32_e32 v41, 0, v41
	v_max_f32_e32 v42, 0, v42
	v_max_f32_e32 v43, 0, v43
	v_max_f32_e32 v44, 0, v44
	v_max_f32_e32 v45, 0, v45
	v_pk_mul_f32 v[38:39], v[38:39], v[38:39]
	v_pk_mul_f32 v[40:41], v[40:41], v[40:41]
	v_pk_mul_f32 v[42:43], v[42:43], v[42:43]
	v_pk_mul_f32 v[44:45], v[44:45], v[44:45]
	v_and_b32_sdwa v46, v38, v59 dst_sel:DWORD dst_unused:UNUSED_PAD src0_sel:WORD_1 src1_sel:DWORD
	v_and_b32_sdwa v47, v39, v59 dst_sel:DWORD dst_unused:UNUSED_PAD src0_sel:WORD_1 src1_sel:DWORD
	v_and_b32_sdwa v48, v40, v59 dst_sel:DWORD dst_unused:UNUSED_PAD src0_sel:WORD_1 src1_sel:DWORD
	v_and_b32_sdwa v49, v41, v59 dst_sel:DWORD dst_unused:UNUSED_PAD src0_sel:WORD_1 src1_sel:DWORD
	v_and_b32_sdwa v50, v42, v59 dst_sel:DWORD dst_unused:UNUSED_PAD src0_sel:WORD_1 src1_sel:DWORD
	v_and_b32_sdwa v51, v43, v59 dst_sel:DWORD dst_unused:UNUSED_PAD src0_sel:WORD_1 src1_sel:DWORD
	v_and_b32_sdwa v52, v44, v59 dst_sel:DWORD dst_unused:UNUSED_PAD src0_sel:WORD_1 src1_sel:DWORD
	v_and_b32_sdwa v53, v45, v59 dst_sel:DWORD dst_unused:UNUSED_PAD src0_sel:WORD_1 src1_sel:DWORD
	v_add3_u32 v38, v38, v46, s24
	v_add3_u32 v39, v39, v47, s24
	v_add3_u32 v40, v40, v48, s24
	v_add3_u32 v41, v41, v49, s24
	v_add3_u32 v42, v42, v50, s24
	v_add3_u32 v43, v43, v51, s24
	v_add3_u32 v44, v44, v52, s24
	v_add3_u32 v45, v45, v53, s24
	v_and_b32_e32 v39, 0xffff0000, v39
	v_and_b32_e32 v41, 0xffff0000, v41
	v_and_b32_e32 v43, 0xffff0000, v43
	v_and_b32_e32 v45, 0xffff0000, v45
	v_or_b32_sdwa v76, v39, v38 dst_sel:DWORD dst_unused:UNUSED_PAD src0_sel:DWORD src1_sel:WORD_1
	v_or_b32_sdwa v77, v41, v40 dst_sel:DWORD dst_unused:UNUSED_PAD src0_sel:DWORD src1_sel:WORD_1
	v_or_b32_sdwa v78, v43, v42 dst_sel:DWORD dst_unused:UNUSED_PAD src0_sel:DWORD src1_sel:WORD_1
	v_or_b32_sdwa v79, v45, v44 dst_sel:DWORD dst_unused:UNUSED_PAD src0_sel:DWORD src1_sel:WORD_1
	global_store_dwordx4 v58, v[76:79], s[56:57]
	s_cmpk_lt_u32 s13, 0x400
	s_barrier
	s_cbranch_scc1 .LBB0_338

.LBB0_590:
	s_lshr_b32 s8, s12, 2
	s_and_b32 s10, s16, 56
	s_and_b32 s8, s8, 0x1ffffc0
	s_or_b32 s10, s10, s3
	s_or_b32 s8, s10, s8
	s_lshl_b32 s8, s8, 7
	s_lshl_b64 s[24:25], s[8:9], 11
	v_lshl_add_u64 v[78:79], v[70:71], 0, s[24:25]
	v_add_co_u32_e32 v80, vcc, s18, v78
	s_and_b32 s10, s14, 0xf80
	s_nop 0
	v_addc_co_u32_e32 v81, vcc, 0, v79, vcc
	s_lshl_b32 s26, s10, 11
	s_mov_b32 s27, s9
	v_add_co_u32_e32 v82, vcc, s19, v78
	v_lshl_add_u64 v[76:77], v[72:73], 0, s[26:27]
	s_nop 0
	v_addc_co_u32_e32 v83, vcc, 0, v79, vcc
	v_add_co_u32_e32 v84, vcc, s18, v76
	global_load_dwordx4 v[2:5], v[78:79], off
	global_load_dwordx4 v[6:9], v[80:81], off
	v_addc_co_u32_e32 v85, vcc, 0, v77, vcc
	v_add_co_u32_e32 v86, vcc, s19, v76
	global_load_dwordx4 v[10:13], v[82:83], off
	global_load_dwordx4 v[14:17], v[76:77], off
	v_addc_co_u32_e32 v87, vcc, 0, v77, vcc
	global_load_dwordx4 v[18:21], v[84:85], off
	global_load_dwordx4 v[22:25], v[86:87], off
	v_add_co_u32_e32 v88, vcc, s20, v76
	s_nop 1
	v_addc_co_u32_e32 v89, vcc, 0, v77, vcc
	global_load_dwordx4 v[26:29], v[88:89], off
	v_add_co_u32_e32 v90, vcc, s20, v78
	s_nop 1
	v_addc_co_u32_e32 v91, vcc, 0, v79, vcc
	global_load_dwordx4 v[30:33], v[90:91], off
	global_load_dwordx4 v[148:151], v[76:77], off offset:128
	global_load_dwordx4 v[152:155], v[84:85], off offset:128
	global_load_dwordx4 v[156:159], v[86:87], off offset:128
	global_load_dwordx4 v[160:163], v[88:89], off offset:128
	global_load_dwordx4 v[164:167], v[78:79], off offset:128
	global_load_dwordx4 v[168:171], v[80:81], off offset:128
	global_load_dwordx4 v[172:175], v[82:83], off offset:128
	global_load_dwordx4 v[176:179], v[90:91], off offset:128
	s_waitcnt vmcnt(12)
	ds_write_b128 v1, v[14:17] offset:36864
	s_waitcnt vmcnt(11)
	ds_write_b128 v1, v[18:21] offset:41472
	s_waitcnt vmcnt(10)
	ds_write_b128 v1, v[22:25] offset:46080
	s_waitcnt vmcnt(9)
	ds_write_b128 v1, v[26:29] offset:50688
	ds_write_b128 v1, v[2:5]
	ds_write_b128 v1, v[6:9] offset:4608
	ds_write_b128 v1, v[10:13] offset:9216
	s_waitcnt vmcnt(8)
	ds_write_b128 v1, v[30:33] offset:13824
	s_waitcnt lgkmcnt(0)
	s_barrier
	global_load_dwordx4 v[180:183], v[80:81], off offset:256
	global_load_dwordx4 v[184:187], v[82:83], off offset:256
	global_load_dwordx4 v[188:191], v[78:79], off offset:256
	global_load_dwordx4 v[192:195], v[76:77], off offset:256
	global_load_dwordx4 v[196:199], v[90:91], off offset:256
	global_load_dwordx4 v[200:203], v[84:85], off offset:256
	global_load_dwordx4 v[204:207], v[86:87], off offset:256
	global_load_dwordx4 v[208:211], v[88:89], off offset:256
	ds_read_b128 v[18:21], v66
	ds_read_b128 v[34:37], v67 offset:36864
	ds_read_b128 v[212:215], v66 offset:32
	ds_read_b128 v[216:219], v67 offset:36896
	ds_read_b128 v[50:53], v67 offset:41472
	ds_read_b128 v[220:223], v67 offset:41504
	ds_read_b128 v[54:57], v66 offset:4608
	ds_read_b128 v[224:227], v66 offset:4640
	s_waitcnt lgkmcnt(6)
	v_mfma_f32_32x32x16_bf16 v[2:17], v[18:21], v[34:37], 0
	s_waitcnt lgkmcnt(3)
	v_mfma_f32_32x32x16_bf16 v[18:33], v[18:21], v[50:53], 0
	s_waitcnt lgkmcnt(1)
	v_mfma_f32_32x32x16_bf16 v[34:49], v[54:57], v[34:37], 0
	v_mfma_f32_32x32x16_bf16 v[50:65], v[54:57], v[50:53], 0
	v_mfma_f32_32x32x16_bf16 v[2:17], v[212:215], v[216:219], v[2:17]
	v_mfma_f32_32x32x16_bf16 v[18:33], v[212:215], v[220:223], v[18:33]
	s_waitcnt lgkmcnt(0)
	v_mfma_f32_32x32x16_bf16 v[34:49], v[224:227], v[216:219], v[34:49]
	v_mfma_f32_32x32x16_bf16 v[50:65], v[224:227], v[220:223], v[50:65]
	ds_read_b128 v[212:215], v66 offset:64
	ds_read_b128 v[216:219], v67 offset:36928
	ds_read_b128 v[220:223], v66 offset:96
	ds_read_b128 v[224:227], v67 offset:36960
	ds_read_b128 v[228:231], v67 offset:41536
	ds_read_b128 v[232:235], v67 offset:41568
	s_waitcnt lgkmcnt(4)
	v_mfma_f32_32x32x16_bf16 v[2:17], v[212:215], v[216:219], v[2:17]
	s_waitcnt lgkmcnt(1)
	v_mfma_f32_32x32x16_bf16 v[18:33], v[212:215], v[228:231], v[18:33]
	ds_read_b128 v[212:215], v66 offset:4672
	ds_read_b128 v[236:239], v66 offset:4704
	s_waitcnt vmcnt(11)
	ds_write_b128 v1, v[164:167] offset:18432
	s_waitcnt vmcnt(10)
	ds_write_b128 v1, v[168:171] offset:23040
	s_waitcnt vmcnt(9)
	ds_write_b128 v1, v[172:175] offset:27648
	s_waitcnt vmcnt(8)
	ds_write_b128 v1, v[176:179] offset:32256
	ds_write_b128 v1, v[148:151] offset:55296
	ds_write_b128 v1, v[152:155] offset:59904
	ds_write_b128 v1, v[156:159] offset:64512
	ds_write_b128 v92, v[160:163] offset:32256
	global_load_dwordx4 v[148:151], v[80:81], off offset:384
	global_load_dwordx4 v[152:155], v[82:83], off offset:384
	global_load_dwordx4 v[156:159], v[78:79], off offset:384
	global_load_dwordx4 v[160:163], v[76:77], off offset:384
	global_load_dwordx4 v[164:167], v[90:91], off offset:384
	global_load_dwordx4 v[168:171], v[84:85], off offset:384
	global_load_dwordx4 v[172:175], v[86:87], off offset:384
	global_load_dwordx4 v[176:179], v[88:89], off offset:384
	s_waitcnt lgkmcnt(0)
	s_barrier
	v_mfma_f32_32x32x16_bf16 v[34:49], v[212:215], v[216:219], v[34:49]
	v_mfma_f32_32x32x16_bf16 v[50:65], v[212:215], v[228:231], v[50:65]
	v_mfma_f32_32x32x16_bf16 v[2:17], v[220:223], v[224:227], v[2:17]
	v_mfma_f32_32x32x16_bf16 v[18:33], v[220:223], v[232:235], v[18:33]
	v_mfma_f32_32x32x16_bf16 v[34:49], v[236:239], v[224:227], v[34:49]
	v_mfma_f32_32x32x16_bf16 v[50:65], v[236:239], v[232:235], v[50:65]
	ds_read_b128 v[212:215], v66 offset:18432
	ds_read_b128 v[216:219], v67 offset:55296
	ds_read_b128 v[220:223], v66 offset:18464
	ds_read_b128 v[224:227], v67 offset:55328
	ds_read_b128 v[228:231], v67 offset:59904
	ds_read_b128 v[232:235], v67 offset:59936
	s_waitcnt lgkmcnt(4)
	v_mfma_f32_32x32x16_bf16 v[2:17], v[212:215], v[216:219], v[2:17]
	s_waitcnt lgkmcnt(1)
	v_mfma_f32_32x32x16_bf16 v[18:33], v[212:215], v[228:231], v[18:33]
	ds_read_b128 v[212:215], v66 offset:23040
	ds_read_b128 v[236:239], v66 offset:23072
	s_waitcnt lgkmcnt(1)
	v_mfma_f32_32x32x16_bf16 v[34:49], v[212:215], v[216:219], v[34:49]
	v_mfma_f32_32x32x16_bf16 v[50:65], v[212:215], v[228:231], v[50:65]
	v_mfma_f32_32x32x16_bf16 v[2:17], v[220:223], v[224:227], v[2:17]
	v_mfma_f32_32x32x16_bf16 v[18:33], v[220:223], v[232:235], v[18:33]
	s_waitcnt lgkmcnt(0)
	v_mfma_f32_32x32x16_bf16 v[34:49], v[236:239], v[224:227], v[34:49]
	ds_read_b128 v[212:215], v66 offset:18496
	ds_read_b128 v[216:219], v67 offset:55360
	ds_read_b128 v[220:223], v66 offset:18528
	ds_read_b128 v[224:227], v67 offset:55392
	v_mfma_f32_32x32x16_bf16 v[50:65], v[236:239], v[232:235], v[50:65]
	ds_read_b128 v[228:231], v67 offset:59968
	ds_read_b128 v[232:235], v67 offset:60000
	s_waitcnt lgkmcnt(4)
	v_mfma_f32_32x32x16_bf16 v[2:17], v[212:215], v[216:219], v[2:17]
	s_waitcnt lgkmcnt(1)
	v_mfma_f32_32x32x16_bf16 v[18:33], v[212:215], v[228:231], v[18:33]
	ds_read_b128 v[212:215], v66 offset:23104
	ds_read_b128 v[236:239], v66 offset:23136
	s_waitcnt vmcnt(13)
	ds_write_b128 v1, v[188:191]
	ds_write_b128 v1, v[180:183] offset:4608
	ds_write_b128 v1, v[184:187] offset:9216
	s_waitcnt vmcnt(11)
	ds_write_b128 v1, v[196:199] offset:13824
	ds_write_b128 v1, v[192:195] offset:36864
	s_waitcnt vmcnt(10)
	ds_write_b128 v1, v[200:203] offset:41472
	s_waitcnt vmcnt(9)
	ds_write_b128 v1, v[204:207] offset:46080
	s_waitcnt vmcnt(8)
	ds_write_b128 v1, v[208:211] offset:50688
	global_load_dwordx4 v[180:183], v[80:81], off offset:512
	global_load_dwordx4 v[184:187], v[82:83], off offset:512
	global_load_dwordx4 v[188:191], v[78:79], off offset:512
	global_load_dwordx4 v[192:195], v[76:77], off offset:512
	global_load_dwordx4 v[196:199], v[90:91], off offset:512
	global_load_dwordx4 v[200:203], v[84:85], off offset:512
	global_load_dwordx4 v[204:207], v[86:87], off offset:512
	global_load_dwordx4 v[208:211], v[88:89], off offset:512
	s_waitcnt lgkmcnt(0)
	s_barrier
	v_mfma_f32_32x32x16_bf16 v[34:49], v[212:215], v[216:219], v[34:49]
	v_mfma_f32_32x32x16_bf16 v[50:65], v[212:215], v[228:231], v[50:65]
	v_mfma_f32_32x32x16_bf16 v[2:17], v[220:223], v[224:227], v[2:17]
	v_mfma_f32_32x32x16_bf16 v[18:33], v[220:223], v[232:235], v[18:33]
	v_mfma_f32_32x32x16_bf16 v[34:49], v[236:239], v[224:227], v[34:49]
	v_mfma_f32_32x32x16_bf16 v[50:65], v[236:239], v[232:235], v[50:65]
	ds_read_b128 v[212:215], v66
	ds_read_b128 v[216:219], v67 offset:36864
	ds_read_b128 v[220:223], v66 offset:32
	ds_read_b128 v[224:227], v67 offset:36896
	ds_read_b128 v[228:231], v67 offset:41472
	ds_read_b128 v[232:235], v67 offset:41504
	s_waitcnt lgkmcnt(4)
	v_mfma_f32_32x32x16_bf16 v[2:17], v[212:215], v[216:219], v[2:17]
	s_waitcnt lgkmcnt(1)
	v_mfma_f32_32x32x16_bf16 v[18:33], v[212:215], v[228:231], v[18:33]
	ds_read_b128 v[212:215], v66 offset:4608
	ds_read_b128 v[236:239], v66 offset:4640
	s_waitcnt lgkmcnt(1)
	v_mfma_f32_32x32x16_bf16 v[34:49], v[212:215], v[216:219], v[34:49]
	v_mfma_f32_32x32x16_bf16 v[50:65], v[212:215], v[228:231], v[50:65]
	v_mfma_f32_32x32x16_bf16 v[2:17], v[220:223], v[224:227], v[2:17]
	v_mfma_f32_32x32x16_bf16 v[18:33], v[220:223], v[232:235], v[18:33]
	s_waitcnt lgkmcnt(0)
	v_mfma_f32_32x32x16_bf16 v[34:49], v[236:239], v[224:227], v[34:49]
	ds_read_b128 v[212:215], v66 offset:64
	ds_read_b128 v[216:219], v67 offset:36928
	ds_read_b128 v[220:223], v66 offset:96
	ds_read_b128 v[224:227], v67 offset:36960
	v_mfma_f32_32x32x16_bf16 v[50:65], v[236:239], v[232:235], v[50:65]
	ds_read_b128 v[228:231], v67 offset:41536
	ds_read_b128 v[232:235], v67 offset:41568
	s_waitcnt lgkmcnt(4)
	v_mfma_f32_32x32x16_bf16 v[2:17], v[212:215], v[216:219], v[2:17]
	s_waitcnt lgkmcnt(1)
	v_mfma_f32_32x32x16_bf16 v[18:33], v[212:215], v[228:231], v[18:33]
	ds_read_b128 v[212:215], v66 offset:4672
	ds_read_b128 v[236:239], v66 offset:4704
	s_waitcnt vmcnt(13)
	ds_write_b128 v1, v[156:159] offset:18432
	ds_write_b128 v1, v[148:151] offset:23040
	ds_write_b128 v1, v[152:155] offset:27648
	s_waitcnt vmcnt(11)
	ds_write_b128 v1, v[164:167] offset:32256
	ds_write_b128 v1, v[160:163] offset:55296
	s_waitcnt vmcnt(10)
	ds_write_b128 v1, v[168:171] offset:59904
	s_waitcnt vmcnt(9)
	ds_write_b128 v1, v[172:175] offset:64512
	s_waitcnt vmcnt(8)
	ds_write_b128 v92, v[176:179] offset:32256
	global_load_dwordx4 v[148:151], v[80:81], off offset:640
	global_load_dwordx4 v[152:155], v[82:83], off offset:640
	global_load_dwordx4 v[156:159], v[78:79], off offset:640
	global_load_dwordx4 v[160:163], v[76:77], off offset:640
	global_load_dwordx4 v[164:167], v[90:91], off offset:640
	global_load_dwordx4 v[168:171], v[84:85], off offset:640
	global_load_dwordx4 v[172:175], v[86:87], off offset:640
	global_load_dwordx4 v[176:179], v[88:89], off offset:640
	s_waitcnt lgkmcnt(0)
	s_barrier
	v_mfma_f32_32x32x16_bf16 v[34:49], v[212:215], v[216:219], v[34:49]
	v_mfma_f32_32x32x16_bf16 v[50:65], v[212:215], v[228:231], v[50:65]
	v_mfma_f32_32x32x16_bf16 v[2:17], v[220:223], v[224:227], v[2:17]
	v_mfma_f32_32x32x16_bf16 v[18:33], v[220:223], v[232:235], v[18:33]
	v_mfma_f32_32x32x16_bf16 v[34:49], v[236:239], v[224:227], v[34:49]
	v_mfma_f32_32x32x16_bf16 v[50:65], v[236:239], v[232:235], v[50:65]
	ds_read_b128 v[212:215], v66 offset:18432
	ds_read_b128 v[216:219], v67 offset:55296
	ds_read_b128 v[220:223], v66 offset:18464
	ds_read_b128 v[224:227], v67 offset:55328
	ds_read_b128 v[228:231], v67 offset:59904
	ds_read_b128 v[232:235], v67 offset:59936
	s_waitcnt lgkmcnt(4)
	v_mfma_f32_32x32x16_bf16 v[2:17], v[212:215], v[216:219], v[2:17]
	s_waitcnt lgkmcnt(1)
	v_mfma_f32_32x32x16_bf16 v[18:33], v[212:215], v[228:231], v[18:33]
	ds_read_b128 v[212:215], v66 offset:23040
	ds_read_b128 v[236:239], v66 offset:23072
	s_waitcnt lgkmcnt(1)
	v_mfma_f32_32x32x16_bf16 v[34:49], v[212:215], v[216:219], v[34:49]
	v_mfma_f32_32x32x16_bf16 v[50:65], v[212:215], v[228:231], v[50:65]
	v_mfma_f32_32x32x16_bf16 v[2:17], v[220:223], v[224:227], v[2:17]
	v_mfma_f32_32x32x16_bf16 v[18:33], v[220:223], v[232:235], v[18:33]
	s_waitcnt lgkmcnt(0)
	v_mfma_f32_32x32x16_bf16 v[34:49], v[236:239], v[224:227], v[34:49]
	ds_read_b128 v[212:215], v66 offset:18496
	ds_read_b128 v[216:219], v67 offset:55360
	ds_read_b128 v[220:223], v66 offset:18528
	ds_read_b128 v[224:227], v67 offset:55392
	v_mfma_f32_32x32x16_bf16 v[50:65], v[236:239], v[232:235], v[50:65]
	ds_read_b128 v[228:231], v67 offset:59968
	ds_read_b128 v[232:235], v67 offset:60000
	s_waitcnt lgkmcnt(4)
	v_mfma_f32_32x32x16_bf16 v[2:17], v[212:215], v[216:219], v[2:17]
	s_waitcnt lgkmcnt(1)
	v_mfma_f32_32x32x16_bf16 v[18:33], v[212:215], v[228:231], v[18:33]
	ds_read_b128 v[212:215], v66 offset:23104
	ds_read_b128 v[236:239], v66 offset:23136
	s_waitcnt vmcnt(13)
	ds_write_b128 v1, v[188:191]
	ds_write_b128 v1, v[180:183] offset:4608
	ds_write_b128 v1, v[184:187] offset:9216
	s_waitcnt vmcnt(11)
	ds_write_b128 v1, v[196:199] offset:13824
	ds_write_b128 v1, v[192:195] offset:36864
	s_waitcnt vmcnt(10)
	ds_write_b128 v1, v[200:203] offset:41472
	s_waitcnt vmcnt(9)
	ds_write_b128 v1, v[204:207] offset:46080
	s_waitcnt vmcnt(8)
	ds_write_b128 v1, v[208:211] offset:50688
	global_load_dwordx4 v[180:183], v[80:81], off offset:768
	global_load_dwordx4 v[184:187], v[82:83], off offset:768
	global_load_dwordx4 v[188:191], v[78:79], off offset:768
	global_load_dwordx4 v[192:195], v[76:77], off offset:768
	global_load_dwordx4 v[196:199], v[90:91], off offset:768
	global_load_dwordx4 v[200:203], v[84:85], off offset:768
	global_load_dwordx4 v[204:207], v[86:87], off offset:768
	global_load_dwordx4 v[208:211], v[88:89], off offset:768
	s_waitcnt lgkmcnt(0)
	s_barrier
	v_mfma_f32_32x32x16_bf16 v[34:49], v[212:215], v[216:219], v[34:49]
	v_mfma_f32_32x32x16_bf16 v[50:65], v[212:215], v[228:231], v[50:65]
	v_mfma_f32_32x32x16_bf16 v[2:17], v[220:223], v[224:227], v[2:17]
	v_mfma_f32_32x32x16_bf16 v[18:33], v[220:223], v[232:235], v[18:33]
	v_mfma_f32_32x32x16_bf16 v[34:49], v[236:239], v[224:227], v[34:49]
	v_mfma_f32_32x32x16_bf16 v[50:65], v[236:239], v[232:235], v[50:65]
	ds_read_b128 v[212:215], v66
	ds_read_b128 v[216:219], v67 offset:36864
	ds_read_b128 v[220:223], v66 offset:32
	ds_read_b128 v[224:227], v67 offset:36896
	ds_read_b128 v[228:231], v67 offset:41472
	ds_read_b128 v[232:235], v67 offset:41504
	s_waitcnt lgkmcnt(4)
	v_mfma_f32_32x32x16_bf16 v[2:17], v[212:215], v[216:219], v[2:17]
	s_waitcnt lgkmcnt(1)
	v_mfma_f32_32x32x16_bf16 v[18:33], v[212:215], v[228:231], v[18:33]
	ds_read_b128 v[212:215], v66 offset:4608
	ds_read_b128 v[236:239], v66 offset:4640
	s_waitcnt lgkmcnt(1)
	v_mfma_f32_32x32x16_bf16 v[34:49], v[212:215], v[216:219], v[34:49]
	v_mfma_f32_32x32x16_bf16 v[50:65], v[212:215], v[228:231], v[50:65]
	v_mfma_f32_32x32x16_bf16 v[2:17], v[220:223], v[224:227], v[2:17]
	v_mfma_f32_32x32x16_bf16 v[18:33], v[220:223], v[232:235], v[18:33]
	s_waitcnt lgkmcnt(0)
	v_mfma_f32_32x32x16_bf16 v[34:49], v[236:239], v[224:227], v[34:49]
	ds_read_b128 v[212:215], v66 offset:64
	ds_read_b128 v[216:219], v67 offset:36928
	ds_read_b128 v[220:223], v66 offset:96
	ds_read_b128 v[224:227], v67 offset:36960
	v_mfma_f32_32x32x16_bf16 v[50:65], v[236:239], v[232:235], v[50:65]
	ds_read_b128 v[228:231], v67 offset:41536
	ds_read_b128 v[232:235], v67 offset:41568
	s_waitcnt lgkmcnt(4)
	v_mfma_f32_32x32x16_bf16 v[2:17], v[212:215], v[216:219], v[2:17]
	s_waitcnt lgkmcnt(1)
	v_mfma_f32_32x32x16_bf16 v[18:33], v[212:215], v[228:231], v[18:33]
	ds_read_b128 v[212:215], v66 offset:4672
	ds_read_b128 v[236:239], v66 offset:4704
	s_waitcnt vmcnt(13)
	ds_write_b128 v1, v[156:159] offset:18432
	ds_write_b128 v1, v[148:151] offset:23040
	ds_write_b128 v1, v[152:155] offset:27648
	s_waitcnt vmcnt(11)
	ds_write_b128 v1, v[164:167] offset:32256
	ds_write_b128 v1, v[160:163] offset:55296
	s_waitcnt vmcnt(10)
	ds_write_b128 v1, v[168:171] offset:59904
	s_waitcnt vmcnt(9)
	ds_write_b128 v1, v[172:175] offset:64512
	s_waitcnt vmcnt(8)
	ds_write_b128 v92, v[176:179] offset:32256
	global_load_dwordx4 v[148:151], v[80:81], off offset:896
	global_load_dwordx4 v[152:155], v[82:83], off offset:896
	global_load_dwordx4 v[156:159], v[78:79], off offset:896
	global_load_dwordx4 v[160:163], v[76:77], off offset:896
	global_load_dwordx4 v[164:167], v[90:91], off offset:896
	global_load_dwordx4 v[168:171], v[84:85], off offset:896
	global_load_dwordx4 v[172:175], v[86:87], off offset:896
	global_load_dwordx4 v[176:179], v[88:89], off offset:896
	s_waitcnt lgkmcnt(0)
	s_barrier
	v_mfma_f32_32x32x16_bf16 v[34:49], v[212:215], v[216:219], v[34:49]
	v_mfma_f32_32x32x16_bf16 v[50:65], v[212:215], v[228:231], v[50:65]
	v_mfma_f32_32x32x16_bf16 v[2:17], v[220:223], v[224:227], v[2:17]
	v_mfma_f32_32x32x16_bf16 v[18:33], v[220:223], v[232:235], v[18:33]
	v_mfma_f32_32x32x16_bf16 v[34:49], v[236:239], v[224:227], v[34:49]
	v_mfma_f32_32x32x16_bf16 v[50:65], v[236:239], v[232:235], v[50:65]
	ds_read_b128 v[212:215], v66 offset:18432
	ds_read_b128 v[216:219], v67 offset:55296
	ds_read_b128 v[220:223], v66 offset:18464
	ds_read_b128 v[224:227], v67 offset:55328
	ds_read_b128 v[228:231], v67 offset:59904
	ds_read_b128 v[232:235], v67 offset:59936
	s_waitcnt lgkmcnt(4)
	v_mfma_f32_32x32x16_bf16 v[2:17], v[212:215], v[216:219], v[2:17]
	s_waitcnt lgkmcnt(1)
	v_mfma_f32_32x32x16_bf16 v[18:33], v[212:215], v[228:231], v[18:33]
	ds_read_b128 v[212:215], v66 offset:23040
	ds_read_b128 v[236:239], v66 offset:23072
	s_waitcnt lgkmcnt(1)
	v_mfma_f32_32x32x16_bf16 v[34:49], v[212:215], v[216:219], v[34:49]
	v_mfma_f32_32x32x16_bf16 v[50:65], v[212:215], v[228:231], v[50:65]
	v_mfma_f32_32x32x16_bf16 v[2:17], v[220:223], v[224:227], v[2:17]
	v_mfma_f32_32x32x16_bf16 v[18:33], v[220:223], v[232:235], v[18:33]
	s_waitcnt lgkmcnt(0)
	v_mfma_f32_32x32x16_bf16 v[34:49], v[236:239], v[224:227], v[34:49]
	ds_read_b128 v[212:215], v66 offset:18496
	ds_read_b128 v[216:219], v67 offset:55360
	ds_read_b128 v[220:223], v66 offset:18528
	ds_read_b128 v[224:227], v67 offset:55392
	v_mfma_f32_32x32x16_bf16 v[50:65], v[236:239], v[232:235], v[50:65]
	ds_read_b128 v[228:231], v67 offset:59968
	ds_read_b128 v[232:235], v67 offset:60000
	s_waitcnt lgkmcnt(4)
	v_mfma_f32_32x32x16_bf16 v[2:17], v[212:215], v[216:219], v[2:17]
	s_waitcnt lgkmcnt(1)
	v_mfma_f32_32x32x16_bf16 v[18:33], v[212:215], v[228:231], v[18:33]
	ds_read_b128 v[212:215], v66 offset:23104
	ds_read_b128 v[236:239], v66 offset:23136
	s_waitcnt vmcnt(13)
	ds_write_b128 v1, v[188:191]
	ds_write_b128 v1, v[180:183] offset:4608
	ds_write_b128 v1, v[184:187] offset:9216
	s_waitcnt vmcnt(11)
	ds_write_b128 v1, v[196:199] offset:13824
	ds_write_b128 v1, v[192:195] offset:36864
	s_waitcnt vmcnt(10)
	ds_write_b128 v1, v[200:203] offset:41472
	s_waitcnt vmcnt(9)
	ds_write_b128 v1, v[204:207] offset:46080
	s_waitcnt vmcnt(8)
	ds_write_b128 v1, v[208:211] offset:50688
	global_load_dwordx4 v[180:183], v[80:81], off offset:1024
	global_load_dwordx4 v[184:187], v[82:83], off offset:1024
	global_load_dwordx4 v[188:191], v[78:79], off offset:1024
	global_load_dwordx4 v[192:195], v[76:77], off offset:1024
	global_load_dwordx4 v[196:199], v[90:91], off offset:1024
	global_load_dwordx4 v[200:203], v[84:85], off offset:1024
	global_load_dwordx4 v[204:207], v[86:87], off offset:1024
	global_load_dwordx4 v[208:211], v[88:89], off offset:1024
	s_waitcnt lgkmcnt(0)
	s_barrier
	v_mfma_f32_32x32x16_bf16 v[34:49], v[212:215], v[216:219], v[34:49]
	v_mfma_f32_32x32x16_bf16 v[50:65], v[212:215], v[228:231], v[50:65]
	v_mfma_f32_32x32x16_bf16 v[2:17], v[220:223], v[224:227], v[2:17]
	v_mfma_f32_32x32x16_bf16 v[18:33], v[220:223], v[232:235], v[18:33]
	v_mfma_f32_32x32x16_bf16 v[34:49], v[236:239], v[224:227], v[34:49]
	v_mfma_f32_32x32x16_bf16 v[50:65], v[236:239], v[232:235], v[50:65]
	ds_read_b128 v[212:215], v66
	ds_read_b128 v[216:219], v67 offset:36864
	ds_read_b128 v[220:223], v66 offset:32
	ds_read_b128 v[224:227], v67 offset:36896
	ds_read_b128 v[228:231], v67 offset:41472
	ds_read_b128 v[232:235], v67 offset:41504
	s_waitcnt lgkmcnt(4)
	v_mfma_f32_32x32x16_bf16 v[2:17], v[212:215], v[216:219], v[2:17]
	s_waitcnt lgkmcnt(1)
	v_mfma_f32_32x32x16_bf16 v[18:33], v[212:215], v[228:231], v[18:33]
	ds_read_b128 v[212:215], v66 offset:4608
	ds_read_b128 v[236:239], v66 offset:4640
	s_waitcnt lgkmcnt(1)
	v_mfma_f32_32x32x16_bf16 v[34:49], v[212:215], v[216:219], v[34:49]
	v_mfma_f32_32x32x16_bf16 v[50:65], v[212:215], v[228:231], v[50:65]
	v_mfma_f32_32x32x16_bf16 v[2:17], v[220:223], v[224:227], v[2:17]
	v_mfma_f32_32x32x16_bf16 v[18:33], v[220:223], v[232:235], v[18:33]
	s_waitcnt lgkmcnt(0)
	v_mfma_f32_32x32x16_bf16 v[34:49], v[236:239], v[224:227], v[34:49]
	ds_read_b128 v[212:215], v66 offset:64
	ds_read_b128 v[216:219], v67 offset:36928
	ds_read_b128 v[220:223], v66 offset:96
	ds_read_b128 v[224:227], v67 offset:36960
	v_mfma_f32_32x32x16_bf16 v[50:65], v[236:239], v[232:235], v[50:65]
	ds_read_b128 v[228:231], v67 offset:41536
	ds_read_b128 v[232:235], v67 offset:41568
	s_waitcnt lgkmcnt(4)
	v_mfma_f32_32x32x16_bf16 v[2:17], v[212:215], v[216:219], v[2:17]
	s_waitcnt lgkmcnt(1)
	v_mfma_f32_32x32x16_bf16 v[18:33], v[212:215], v[228:231], v[18:33]
	ds_read_b128 v[212:215], v66 offset:4672
	ds_read_b128 v[236:239], v66 offset:4704
	s_waitcnt vmcnt(13)
	ds_write_b128 v1, v[156:159] offset:18432
	ds_write_b128 v1, v[148:151] offset:23040
	ds_write_b128 v1, v[152:155] offset:27648
	s_waitcnt vmcnt(11)
	ds_write_b128 v1, v[164:167] offset:32256
	ds_write_b128 v1, v[160:163] offset:55296
	s_waitcnt vmcnt(10)
	ds_write_b128 v1, v[168:171] offset:59904
	s_waitcnt vmcnt(9)
	ds_write_b128 v1, v[172:175] offset:64512
	s_waitcnt vmcnt(8)
	ds_write_b128 v92, v[176:179] offset:32256
	global_load_dwordx4 v[148:151], v[80:81], off offset:1152
	global_load_dwordx4 v[152:155], v[82:83], off offset:1152
	global_load_dwordx4 v[156:159], v[78:79], off offset:1152
	global_load_dwordx4 v[160:163], v[76:77], off offset:1152
	global_load_dwordx4 v[164:167], v[90:91], off offset:1152
	global_load_dwordx4 v[168:171], v[84:85], off offset:1152
	global_load_dwordx4 v[172:175], v[86:87], off offset:1152
	global_load_dwordx4 v[176:179], v[88:89], off offset:1152
	s_waitcnt lgkmcnt(0)
	s_barrier
	v_mfma_f32_32x32x16_bf16 v[34:49], v[212:215], v[216:219], v[34:49]
	v_mfma_f32_32x32x16_bf16 v[50:65], v[212:215], v[228:231], v[50:65]
	v_mfma_f32_32x32x16_bf16 v[2:17], v[220:223], v[224:227], v[2:17]
	v_mfma_f32_32x32x16_bf16 v[18:33], v[220:223], v[232:235], v[18:33]
	v_mfma_f32_32x32x16_bf16 v[34:49], v[236:239], v[224:227], v[34:49]
	v_mfma_f32_32x32x16_bf16 v[50:65], v[236:239], v[232:235], v[50:65]
	ds_read_b128 v[212:215], v66 offset:18432
	ds_read_b128 v[216:219], v67 offset:55296
	ds_read_b128 v[220:223], v66 offset:18464
	ds_read_b128 v[224:227], v67 offset:55328
	ds_read_b128 v[228:231], v67 offset:59904
	ds_read_b128 v[232:235], v67 offset:59936
	s_waitcnt lgkmcnt(4)
	v_mfma_f32_32x32x16_bf16 v[2:17], v[212:215], v[216:219], v[2:17]
	s_waitcnt lgkmcnt(1)
	v_mfma_f32_32x32x16_bf16 v[18:33], v[212:215], v[228:231], v[18:33]
	ds_read_b128 v[212:215], v66 offset:23040
	ds_read_b128 v[236:239], v66 offset:23072
	s_waitcnt lgkmcnt(1)
	v_mfma_f32_32x32x16_bf16 v[34:49], v[212:215], v[216:219], v[34:49]
	v_mfma_f32_32x32x16_bf16 v[50:65], v[212:215], v[228:231], v[50:65]
	v_mfma_f32_32x32x16_bf16 v[2:17], v[220:223], v[224:227], v[2:17]
	v_mfma_f32_32x32x16_bf16 v[18:33], v[220:223], v[232:235], v[18:33]
	s_waitcnt lgkmcnt(0)
	v_mfma_f32_32x32x16_bf16 v[34:49], v[236:239], v[224:227], v[34:49]
	ds_read_b128 v[212:215], v66 offset:18496
	ds_read_b128 v[216:219], v67 offset:55360
	ds_read_b128 v[220:223], v66 offset:18528
	ds_read_b128 v[224:227], v67 offset:55392
	v_mfma_f32_32x32x16_bf16 v[50:65], v[236:239], v[232:235], v[50:65]
	ds_read_b128 v[228:231], v67 offset:59968
	ds_read_b128 v[232:235], v67 offset:60000
	s_waitcnt lgkmcnt(4)
	v_mfma_f32_32x32x16_bf16 v[2:17], v[212:215], v[216:219], v[2:17]
	s_waitcnt lgkmcnt(1)
	v_mfma_f32_32x32x16_bf16 v[18:33], v[212:215], v[228:231], v[18:33]
	ds_read_b128 v[212:215], v66 offset:23104
	ds_read_b128 v[236:239], v66 offset:23136
	s_waitcnt vmcnt(13)
	ds_write_b128 v1, v[188:191]
	ds_write_b128 v1, v[180:183] offset:4608
	ds_write_b128 v1, v[184:187] offset:9216
	s_waitcnt vmcnt(11)
	ds_write_b128 v1, v[196:199] offset:13824
	ds_write_b128 v1, v[192:195] offset:36864
	s_waitcnt vmcnt(10)
	ds_write_b128 v1, v[200:203] offset:41472
	s_waitcnt vmcnt(9)
	ds_write_b128 v1, v[204:207] offset:46080
	s_waitcnt vmcnt(8)
	ds_write_b128 v1, v[208:211] offset:50688
	global_load_dwordx4 v[180:183], v[80:81], off offset:1280
	global_load_dwordx4 v[184:187], v[82:83], off offset:1280
	global_load_dwordx4 v[188:191], v[78:79], off offset:1280
	global_load_dwordx4 v[192:195], v[76:77], off offset:1280
	global_load_dwordx4 v[196:199], v[90:91], off offset:1280
	global_load_dwordx4 v[200:203], v[84:85], off offset:1280
	global_load_dwordx4 v[204:207], v[86:87], off offset:1280
	global_load_dwordx4 v[208:211], v[88:89], off offset:1280
	s_waitcnt lgkmcnt(0)
	s_barrier
	v_mfma_f32_32x32x16_bf16 v[34:49], v[212:215], v[216:219], v[34:49]
	v_mfma_f32_32x32x16_bf16 v[50:65], v[212:215], v[228:231], v[50:65]
	v_mfma_f32_32x32x16_bf16 v[2:17], v[220:223], v[224:227], v[2:17]
	v_mfma_f32_32x32x16_bf16 v[18:33], v[220:223], v[232:235], v[18:33]
	v_mfma_f32_32x32x16_bf16 v[34:49], v[236:239], v[224:227], v[34:49]
	v_mfma_f32_32x32x16_bf16 v[50:65], v[236:239], v[232:235], v[50:65]
	ds_read_b128 v[212:215], v66
	ds_read_b128 v[216:219], v67 offset:36864
	ds_read_b128 v[220:223], v66 offset:32
	ds_read_b128 v[224:227], v67 offset:36896
	ds_read_b128 v[228:231], v67 offset:41472
	ds_read_b128 v[232:235], v67 offset:41504
	s_waitcnt lgkmcnt(4)
	v_mfma_f32_32x32x16_bf16 v[2:17], v[212:215], v[216:219], v[2:17]
	s_waitcnt lgkmcnt(1)
	v_mfma_f32_32x32x16_bf16 v[18:33], v[212:215], v[228:231], v[18:33]
	ds_read_b128 v[212:215], v66 offset:4608
	ds_read_b128 v[236:239], v66 offset:4640
	s_waitcnt lgkmcnt(1)
	v_mfma_f32_32x32x16_bf16 v[34:49], v[212:215], v[216:219], v[34:49]
	v_mfma_f32_32x32x16_bf16 v[50:65], v[212:215], v[228:231], v[50:65]
	v_mfma_f32_32x32x16_bf16 v[2:17], v[220:223], v[224:227], v[2:17]
	v_mfma_f32_32x32x16_bf16 v[18:33], v[220:223], v[232:235], v[18:33]
	s_waitcnt lgkmcnt(0)
	v_mfma_f32_32x32x16_bf16 v[34:49], v[236:239], v[224:227], v[34:49]
	ds_read_b128 v[212:215], v66 offset:64
	ds_read_b128 v[216:219], v67 offset:36928
	ds_read_b128 v[220:223], v66 offset:96
	ds_read_b128 v[224:227], v67 offset:36960
	v_mfma_f32_32x32x16_bf16 v[50:65], v[236:239], v[232:235], v[50:65]
	ds_read_b128 v[228:231], v67 offset:41536
	ds_read_b128 v[232:235], v67 offset:41568
	s_waitcnt lgkmcnt(4)
	v_mfma_f32_32x32x16_bf16 v[2:17], v[212:215], v[216:219], v[2:17]
	s_waitcnt lgkmcnt(1)
	v_mfma_f32_32x32x16_bf16 v[18:33], v[212:215], v[228:231], v[18:33]
	ds_read_b128 v[212:215], v66 offset:4672
	ds_read_b128 v[236:239], v66 offset:4704
	s_waitcnt vmcnt(13)
	ds_write_b128 v1, v[156:159] offset:18432
	ds_write_b128 v1, v[148:151] offset:23040
	ds_write_b128 v1, v[152:155] offset:27648
	s_waitcnt vmcnt(11)
	ds_write_b128 v1, v[164:167] offset:32256
	ds_write_b128 v1, v[160:163] offset:55296
	s_waitcnt vmcnt(10)
	ds_write_b128 v1, v[168:171] offset:59904
	s_waitcnt vmcnt(9)
	ds_write_b128 v1, v[172:175] offset:64512
	s_waitcnt vmcnt(8)
	ds_write_b128 v92, v[176:179] offset:32256
	global_load_dwordx4 v[148:151], v[80:81], off offset:1408
	global_load_dwordx4 v[152:155], v[82:83], off offset:1408
	global_load_dwordx4 v[156:159], v[78:79], off offset:1408
	global_load_dwordx4 v[160:163], v[76:77], off offset:1408
	global_load_dwordx4 v[164:167], v[90:91], off offset:1408
	global_load_dwordx4 v[168:171], v[84:85], off offset:1408
	global_load_dwordx4 v[172:175], v[86:87], off offset:1408
	global_load_dwordx4 v[176:179], v[88:89], off offset:1408
	s_waitcnt lgkmcnt(0)
	s_barrier
	v_mfma_f32_32x32x16_bf16 v[34:49], v[212:215], v[216:219], v[34:49]
	v_mfma_f32_32x32x16_bf16 v[50:65], v[212:215], v[228:231], v[50:65]
	v_mfma_f32_32x32x16_bf16 v[2:17], v[220:223], v[224:227], v[2:17]
	v_mfma_f32_32x32x16_bf16 v[18:33], v[220:223], v[232:235], v[18:33]
	v_mfma_f32_32x32x16_bf16 v[34:49], v[236:239], v[224:227], v[34:49]
	v_mfma_f32_32x32x16_bf16 v[50:65], v[236:239], v[232:235], v[50:65]
	ds_read_b128 v[212:215], v66 offset:18432
	ds_read_b128 v[216:219], v67 offset:55296
	ds_read_b128 v[220:223], v66 offset:18464
	ds_read_b128 v[224:227], v67 offset:55328
	ds_read_b128 v[228:231], v67 offset:59904
	ds_read_b128 v[232:235], v67 offset:59936
	s_waitcnt lgkmcnt(4)
	v_mfma_f32_32x32x16_bf16 v[2:17], v[212:215], v[216:219], v[2:17]
	s_waitcnt lgkmcnt(1)
	v_mfma_f32_32x32x16_bf16 v[18:33], v[212:215], v[228:231], v[18:33]
	ds_read_b128 v[212:215], v66 offset:23040
	ds_read_b128 v[236:239], v66 offset:23072
	s_waitcnt lgkmcnt(1)
	v_mfma_f32_32x32x16_bf16 v[34:49], v[212:215], v[216:219], v[34:49]
	v_mfma_f32_32x32x16_bf16 v[50:65], v[212:215], v[228:231], v[50:65]
	v_mfma_f32_32x32x16_bf16 v[2:17], v[220:223], v[224:227], v[2:17]
	v_mfma_f32_32x32x16_bf16 v[18:33], v[220:223], v[232:235], v[18:33]
	s_waitcnt lgkmcnt(0)
	v_mfma_f32_32x32x16_bf16 v[34:49], v[236:239], v[224:227], v[34:49]
	ds_read_b128 v[212:215], v66 offset:18496
	ds_read_b128 v[216:219], v67 offset:55360
	ds_read_b128 v[220:223], v66 offset:18528
	ds_read_b128 v[224:227], v67 offset:55392
	v_mfma_f32_32x32x16_bf16 v[50:65], v[236:239], v[232:235], v[50:65]
	ds_read_b128 v[228:231], v67 offset:59968
	ds_read_b128 v[232:235], v67 offset:60000
	s_waitcnt lgkmcnt(4)
	v_mfma_f32_32x32x16_bf16 v[2:17], v[212:215], v[216:219], v[2:17]
	s_waitcnt lgkmcnt(1)
	v_mfma_f32_32x32x16_bf16 v[18:33], v[212:215], v[228:231], v[18:33]
	ds_read_b128 v[212:215], v66 offset:23104
	ds_read_b128 v[236:239], v66 offset:23136
	s_waitcnt vmcnt(13)
	ds_write_b128 v1, v[188:191]
	ds_write_b128 v1, v[180:183] offset:4608
	ds_write_b128 v1, v[184:187] offset:9216
	s_waitcnt vmcnt(11)
	ds_write_b128 v1, v[196:199] offset:13824
	ds_write_b128 v1, v[192:195] offset:36864
	s_waitcnt vmcnt(10)
	ds_write_b128 v1, v[200:203] offset:41472
	s_waitcnt vmcnt(9)
	ds_write_b128 v1, v[204:207] offset:46080
	s_waitcnt vmcnt(8)
	ds_write_b128 v1, v[208:211] offset:50688
	global_load_dwordx4 v[180:183], v[80:81], off offset:1536
	global_load_dwordx4 v[184:187], v[82:83], off offset:1536
	global_load_dwordx4 v[188:191], v[78:79], off offset:1536
	global_load_dwordx4 v[192:195], v[76:77], off offset:1536
	global_load_dwordx4 v[196:199], v[90:91], off offset:1536
	global_load_dwordx4 v[200:203], v[84:85], off offset:1536
	global_load_dwordx4 v[204:207], v[86:87], off offset:1536
	global_load_dwordx4 v[208:211], v[88:89], off offset:1536
	s_waitcnt lgkmcnt(0)
	s_barrier
	v_mfma_f32_32x32x16_bf16 v[34:49], v[212:215], v[216:219], v[34:49]
	v_mfma_f32_32x32x16_bf16 v[50:65], v[212:215], v[228:231], v[50:65]
	v_mfma_f32_32x32x16_bf16 v[2:17], v[220:223], v[224:227], v[2:17]
	v_mfma_f32_32x32x16_bf16 v[18:33], v[220:223], v[232:235], v[18:33]
	v_mfma_f32_32x32x16_bf16 v[34:49], v[236:239], v[224:227], v[34:49]
	v_mfma_f32_32x32x16_bf16 v[50:65], v[236:239], v[232:235], v[50:65]
	ds_read_b128 v[212:215], v66
	ds_read_b128 v[216:219], v67 offset:36864
	ds_read_b128 v[220:223], v66 offset:32
	ds_read_b128 v[224:227], v67 offset:36896
	ds_read_b128 v[228:231], v67 offset:41472
	ds_read_b128 v[232:235], v67 offset:41504
	s_waitcnt lgkmcnt(4)
	v_mfma_f32_32x32x16_bf16 v[2:17], v[212:215], v[216:219], v[2:17]
	s_waitcnt lgkmcnt(1)
	v_mfma_f32_32x32x16_bf16 v[18:33], v[212:215], v[228:231], v[18:33]
	ds_read_b128 v[212:215], v66 offset:4608
	ds_read_b128 v[236:239], v66 offset:4640
	s_waitcnt lgkmcnt(1)
	v_mfma_f32_32x32x16_bf16 v[34:49], v[212:215], v[216:219], v[34:49]
	v_mfma_f32_32x32x16_bf16 v[50:65], v[212:215], v[228:231], v[50:65]
	v_mfma_f32_32x32x16_bf16 v[2:17], v[220:223], v[224:227], v[2:17]
	v_mfma_f32_32x32x16_bf16 v[18:33], v[220:223], v[232:235], v[18:33]
	s_waitcnt lgkmcnt(0)
	v_mfma_f32_32x32x16_bf16 v[34:49], v[236:239], v[224:227], v[34:49]
	ds_read_b128 v[212:215], v66 offset:64
	ds_read_b128 v[216:219], v67 offset:36928
	ds_read_b128 v[220:223], v66 offset:96
	ds_read_b128 v[224:227], v67 offset:36960
	v_mfma_f32_32x32x16_bf16 v[50:65], v[236:239], v[232:235], v[50:65]
	ds_read_b128 v[228:231], v67 offset:41536
	ds_read_b128 v[232:235], v67 offset:41568
	s_waitcnt lgkmcnt(4)
	v_mfma_f32_32x32x16_bf16 v[2:17], v[212:215], v[216:219], v[2:17]
	s_waitcnt lgkmcnt(1)
	v_mfma_f32_32x32x16_bf16 v[18:33], v[212:215], v[228:231], v[18:33]
	ds_read_b128 v[212:215], v66 offset:4672
	ds_read_b128 v[236:239], v66 offset:4704
	s_waitcnt vmcnt(13)
	ds_write_b128 v1, v[156:159] offset:18432
	ds_write_b128 v1, v[148:151] offset:23040
	ds_write_b128 v1, v[152:155] offset:27648
	s_waitcnt vmcnt(11)
	ds_write_b128 v1, v[164:167] offset:32256
	ds_write_b128 v1, v[160:163] offset:55296
	s_waitcnt vmcnt(10)
	ds_write_b128 v1, v[168:171] offset:59904
	s_waitcnt vmcnt(9)
	ds_write_b128 v1, v[172:175] offset:64512
	s_waitcnt vmcnt(8)
	ds_write_b128 v92, v[176:179] offset:32256
	global_load_dwordx4 v[148:151], v[80:81], off offset:1664
	global_load_dwordx4 v[152:155], v[82:83], off offset:1664
	global_load_dwordx4 v[156:159], v[78:79], off offset:1664
	global_load_dwordx4 v[160:163], v[76:77], off offset:1664
	global_load_dwordx4 v[164:167], v[90:91], off offset:1664
	global_load_dwordx4 v[168:171], v[84:85], off offset:1664
	global_load_dwordx4 v[172:175], v[86:87], off offset:1664
	global_load_dwordx4 v[176:179], v[88:89], off offset:1664
	s_waitcnt lgkmcnt(0)
	s_barrier
	v_mfma_f32_32x32x16_bf16 v[34:49], v[212:215], v[216:219], v[34:49]
	v_mfma_f32_32x32x16_bf16 v[50:65], v[212:215], v[228:231], v[50:65]
	v_mfma_f32_32x32x16_bf16 v[2:17], v[220:223], v[224:227], v[2:17]
	v_mfma_f32_32x32x16_bf16 v[18:33], v[220:223], v[232:235], v[18:33]
	v_mfma_f32_32x32x16_bf16 v[34:49], v[236:239], v[224:227], v[34:49]
	v_mfma_f32_32x32x16_bf16 v[50:65], v[236:239], v[232:235], v[50:65]
	ds_read_b128 v[212:215], v66 offset:18432
	ds_read_b128 v[216:219], v67 offset:55296
	ds_read_b128 v[220:223], v66 offset:18464
	ds_read_b128 v[224:227], v67 offset:55328
	ds_read_b128 v[228:231], v67 offset:59904
	ds_read_b128 v[232:235], v67 offset:59936
	s_waitcnt lgkmcnt(4)
	v_mfma_f32_32x32x16_bf16 v[2:17], v[212:215], v[216:219], v[2:17]
	s_waitcnt lgkmcnt(1)
	v_mfma_f32_32x32x16_bf16 v[18:33], v[212:215], v[228:231], v[18:33]
	ds_read_b128 v[212:215], v66 offset:23040
	ds_read_b128 v[236:239], v66 offset:23072
	s_waitcnt lgkmcnt(1)
	v_mfma_f32_32x32x16_bf16 v[34:49], v[212:215], v[216:219], v[34:49]
	v_mfma_f32_32x32x16_bf16 v[50:65], v[212:215], v[228:231], v[50:65]
	v_mfma_f32_32x32x16_bf16 v[2:17], v[220:223], v[224:227], v[2:17]
	v_mfma_f32_32x32x16_bf16 v[18:33], v[220:223], v[232:235], v[18:33]
	s_waitcnt lgkmcnt(0)
	v_mfma_f32_32x32x16_bf16 v[34:49], v[236:239], v[224:227], v[34:49]
	ds_read_b128 v[212:215], v66 offset:18496
	ds_read_b128 v[216:219], v67 offset:55360
	ds_read_b128 v[220:223], v66 offset:18528
	ds_read_b128 v[224:227], v67 offset:55392
	v_mfma_f32_32x32x16_bf16 v[50:65], v[236:239], v[232:235], v[50:65]
	ds_read_b128 v[228:231], v67 offset:59968
	ds_read_b128 v[232:235], v67 offset:60000
	s_waitcnt lgkmcnt(4)
	v_mfma_f32_32x32x16_bf16 v[2:17], v[212:215], v[216:219], v[2:17]
	s_waitcnt lgkmcnt(1)
	v_mfma_f32_32x32x16_bf16 v[18:33], v[212:215], v[228:231], v[18:33]
	ds_read_b128 v[212:215], v66 offset:23104
	ds_read_b128 v[236:239], v66 offset:23136
	s_waitcnt vmcnt(13)
	ds_write_b128 v1, v[188:191]
	ds_write_b128 v1, v[180:183] offset:4608
	ds_write_b128 v1, v[184:187] offset:9216
	s_waitcnt vmcnt(11)
	ds_write_b128 v1, v[196:199] offset:13824
	ds_write_b128 v1, v[192:195] offset:36864
	s_waitcnt vmcnt(10)
	ds_write_b128 v1, v[200:203] offset:41472
	s_waitcnt vmcnt(9)
	ds_write_b128 v1, v[204:207] offset:46080
	s_waitcnt vmcnt(8)
	ds_write_b128 v1, v[208:211] offset:50688
	global_load_dwordx4 v[180:183], v[80:81], off offset:1792
	global_load_dwordx4 v[184:187], v[82:83], off offset:1792
	global_load_dwordx4 v[188:191], v[78:79], off offset:1792
	global_load_dwordx4 v[192:195], v[76:77], off offset:1792
	global_load_dwordx4 v[196:199], v[90:91], off offset:1792
	global_load_dwordx4 v[200:203], v[84:85], off offset:1792
	global_load_dwordx4 v[204:207], v[86:87], off offset:1792
	global_load_dwordx4 v[208:211], v[88:89], off offset:1792
	s_waitcnt lgkmcnt(0)
	s_barrier
	v_mfma_f32_32x32x16_bf16 v[34:49], v[212:215], v[216:219], v[34:49]
	v_mfma_f32_32x32x16_bf16 v[50:65], v[212:215], v[228:231], v[50:65]
	v_mfma_f32_32x32x16_bf16 v[2:17], v[220:223], v[224:227], v[2:17]
	v_mfma_f32_32x32x16_bf16 v[18:33], v[220:223], v[232:235], v[18:33]
	v_mfma_f32_32x32x16_bf16 v[34:49], v[236:239], v[224:227], v[34:49]
	v_mfma_f32_32x32x16_bf16 v[50:65], v[236:239], v[232:235], v[50:65]
	ds_read_b128 v[212:215], v66
	ds_read_b128 v[216:219], v67 offset:36864
	ds_read_b128 v[220:223], v66 offset:32
	ds_read_b128 v[224:227], v67 offset:36896
	ds_read_b128 v[228:231], v67 offset:41472
	ds_read_b128 v[232:235], v67 offset:41504
	s_waitcnt lgkmcnt(4)
	v_mfma_f32_32x32x16_bf16 v[2:17], v[212:215], v[216:219], v[2:17]
	s_waitcnt lgkmcnt(1)
	v_mfma_f32_32x32x16_bf16 v[18:33], v[212:215], v[228:231], v[18:33]
	ds_read_b128 v[212:215], v66 offset:4608
	ds_read_b128 v[236:239], v66 offset:4640
	s_waitcnt lgkmcnt(1)
	v_mfma_f32_32x32x16_bf16 v[34:49], v[212:215], v[216:219], v[34:49]
	v_mfma_f32_32x32x16_bf16 v[50:65], v[212:215], v[228:231], v[50:65]
	v_mfma_f32_32x32x16_bf16 v[2:17], v[220:223], v[224:227], v[2:17]
	v_mfma_f32_32x32x16_bf16 v[18:33], v[220:223], v[232:235], v[18:33]
	s_waitcnt lgkmcnt(0)
	v_mfma_f32_32x32x16_bf16 v[34:49], v[236:239], v[224:227], v[34:49]
	ds_read_b128 v[212:215], v66 offset:64
	ds_read_b128 v[216:219], v67 offset:36928
	ds_read_b128 v[220:223], v66 offset:96
	ds_read_b128 v[224:227], v67 offset:36960
	v_mfma_f32_32x32x16_bf16 v[50:65], v[236:239], v[232:235], v[50:65]
	ds_read_b128 v[228:231], v67 offset:41536
	ds_read_b128 v[232:235], v67 offset:41568
	s_waitcnt lgkmcnt(4)
	v_mfma_f32_32x32x16_bf16 v[2:17], v[212:215], v[216:219], v[2:17]
	s_waitcnt lgkmcnt(1)
	v_mfma_f32_32x32x16_bf16 v[18:33], v[212:215], v[228:231], v[18:33]
	ds_read_b128 v[212:215], v66 offset:4672
	ds_read_b128 v[236:239], v66 offset:4704
	s_waitcnt vmcnt(13)
	ds_write_b128 v1, v[156:159] offset:18432
	ds_write_b128 v1, v[148:151] offset:23040
	ds_write_b128 v1, v[152:155] offset:27648
	s_waitcnt vmcnt(11)
	ds_write_b128 v1, v[164:167] offset:32256
	ds_write_b128 v1, v[160:163] offset:55296
	s_waitcnt vmcnt(10)
	ds_write_b128 v1, v[168:171] offset:59904
	s_waitcnt vmcnt(9)
	ds_write_b128 v1, v[172:175] offset:64512
	s_waitcnt vmcnt(8)
	ds_write_b128 v92, v[176:179] offset:32256
	s_waitcnt lgkmcnt(0)
	s_barrier
	global_load_dwordx4 v[148:151], v[80:81], off offset:1920
	s_nop 0
	global_load_dwordx4 v[80:83], v[82:83], off offset:1920
	s_nop 0
	global_load_dwordx4 v[152:155], v[78:79], off offset:1920
	s_nop 0
	global_load_dwordx4 v[76:79], v[76:77], off offset:1920
	s_nop 0
	global_load_dwordx4 v[156:159], v[90:91], off offset:1920
	global_load_dwordx4 v[160:163], v[84:85], off offset:1920
	s_nop 0
	global_load_dwordx4 v[84:87], v[86:87], off offset:1920
	s_nop 0
	global_load_dwordx4 v[88:91], v[88:89], off offset:1920
	v_mfma_f32_32x32x16_bf16 v[34:49], v[212:215], v[216:219], v[34:49]
	v_mfma_f32_32x32x16_bf16 v[50:65], v[212:215], v[228:231], v[50:65]
	v_mfma_f32_32x32x16_bf16 v[2:17], v[220:223], v[224:227], v[2:17]
	v_mfma_f32_32x32x16_bf16 v[18:33], v[220:223], v[232:235], v[18:33]
	v_mfma_f32_32x32x16_bf16 v[34:49], v[236:239], v[224:227], v[34:49]
	v_mfma_f32_32x32x16_bf16 v[50:65], v[236:239], v[232:235], v[50:65]
	ds_read_b128 v[164:167], v66 offset:18432
	ds_read_b128 v[168:171], v67 offset:55296
	ds_read_b128 v[172:175], v66 offset:18464
	ds_read_b128 v[176:179], v67 offset:55328
	ds_read_b128 v[212:215], v67 offset:59904
	ds_read_b128 v[216:219], v67 offset:59936
	s_waitcnt lgkmcnt(4)
	v_mfma_f32_32x32x16_bf16 v[2:17], v[164:167], v[168:171], v[2:17]
	s_waitcnt lgkmcnt(1)
	v_mfma_f32_32x32x16_bf16 v[18:33], v[164:167], v[212:215], v[18:33]
	ds_read_b128 v[164:167], v66 offset:23040
	ds_read_b128 v[220:223], v66 offset:23072
	s_waitcnt lgkmcnt(1)
	v_mfma_f32_32x32x16_bf16 v[34:49], v[164:167], v[168:171], v[34:49]
	v_mfma_f32_32x32x16_bf16 v[50:65], v[164:167], v[212:215], v[50:65]
	v_mfma_f32_32x32x16_bf16 v[2:17], v[172:175], v[176:179], v[2:17]
	v_mfma_f32_32x32x16_bf16 v[18:33], v[172:175], v[216:219], v[18:33]
	s_waitcnt lgkmcnt(0)
	v_mfma_f32_32x32x16_bf16 v[34:49], v[220:223], v[176:179], v[34:49]
	ds_read_b128 v[164:167], v66 offset:18496
	ds_read_b128 v[168:171], v67 offset:55360
	ds_read_b128 v[172:175], v66 offset:18528
	ds_read_b128 v[176:179], v67 offset:55392
	v_mfma_f32_32x32x16_bf16 v[50:65], v[220:223], v[216:219], v[50:65]
	ds_read_b128 v[212:215], v67 offset:59968
	ds_read_b128 v[216:219], v67 offset:60000
	s_waitcnt lgkmcnt(4)
	v_mfma_f32_32x32x16_bf16 v[2:17], v[164:167], v[168:171], v[2:17]
	s_waitcnt lgkmcnt(1)
	v_mfma_f32_32x32x16_bf16 v[18:33], v[164:167], v[212:215], v[18:33]
	ds_read_b128 v[164:167], v66 offset:23104
	ds_read_b128 v[220:223], v66 offset:23136
	s_waitcnt vmcnt(13)
	ds_write_b128 v1, v[188:191]
	ds_write_b128 v1, v[180:183] offset:4608
	ds_write_b128 v1, v[184:187] offset:9216
	s_waitcnt vmcnt(11)
	ds_write_b128 v1, v[196:199] offset:13824
	ds_write_b128 v1, v[192:195] offset:36864
	s_waitcnt vmcnt(10)
	ds_write_b128 v1, v[200:203] offset:41472
	s_waitcnt vmcnt(9)
	ds_write_b128 v1, v[204:207] offset:46080
	s_waitcnt vmcnt(8)
	ds_write_b128 v1, v[208:211] offset:50688
	s_waitcnt lgkmcnt(0)
	s_barrier
	v_mfma_f32_32x32x16_bf16 v[34:49], v[164:167], v[168:171], v[34:49]
	v_mfma_f32_32x32x16_bf16 v[50:65], v[164:167], v[212:215], v[50:65]
	v_mfma_f32_32x32x16_bf16 v[2:17], v[172:175], v[176:179], v[2:17]
	v_mfma_f32_32x32x16_bf16 v[18:33], v[172:175], v[216:219], v[18:33]
	v_mfma_f32_32x32x16_bf16 v[34:49], v[220:223], v[176:179], v[34:49]
	v_mfma_f32_32x32x16_bf16 v[50:65], v[220:223], v[216:219], v[50:65]
	ds_read_b128 v[164:167], v66
	ds_read_b128 v[168:171], v67 offset:36864
	ds_read_b128 v[172:175], v66 offset:32
	ds_read_b128 v[176:179], v67 offset:36896
	ds_read_b128 v[180:183], v67 offset:41472
	ds_read_b128 v[184:187], v67 offset:41504
	s_waitcnt lgkmcnt(4)
	v_mfma_f32_32x32x16_bf16 v[2:17], v[164:167], v[168:171], v[2:17]
	s_waitcnt lgkmcnt(1)
	v_mfma_f32_32x32x16_bf16 v[18:33], v[164:167], v[180:183], v[18:33]
	ds_read_b128 v[164:167], v66 offset:4608
	ds_read_b128 v[188:191], v66 offset:4640
	s_waitcnt lgkmcnt(1)
	v_mfma_f32_32x32x16_bf16 v[34:49], v[164:167], v[168:171], v[34:49]
	v_mfma_f32_32x32x16_bf16 v[50:65], v[164:167], v[180:183], v[50:65]
	v_mfma_f32_32x32x16_bf16 v[2:17], v[172:175], v[176:179], v[2:17]
	v_mfma_f32_32x32x16_bf16 v[18:33], v[172:175], v[184:187], v[18:33]
	s_waitcnt lgkmcnt(0)
	v_mfma_f32_32x32x16_bf16 v[34:49], v[188:191], v[176:179], v[34:49]
	ds_read_b128 v[164:167], v66 offset:64
	ds_read_b128 v[168:171], v67 offset:36928
	ds_read_b128 v[172:175], v66 offset:96
	ds_read_b128 v[176:179], v67 offset:36960
	v_mfma_f32_32x32x16_bf16 v[50:65], v[188:191], v[184:187], v[50:65]
	ds_read_b128 v[180:183], v67 offset:41536
	ds_read_b128 v[184:187], v67 offset:41568
	s_waitcnt lgkmcnt(4)
	v_mfma_f32_32x32x16_bf16 v[2:17], v[164:167], v[168:171], v[2:17]
	s_waitcnt lgkmcnt(1)
	v_mfma_f32_32x32x16_bf16 v[18:33], v[164:167], v[180:183], v[18:33]
	ds_read_b128 v[164:167], v66 offset:4672
	ds_read_b128 v[188:191], v66 offset:4704
	s_waitcnt vmcnt(5)
	ds_write_b128 v1, v[152:155] offset:18432
	ds_write_b128 v1, v[148:151] offset:23040
	ds_write_b128 v1, v[80:83] offset:27648
	s_waitcnt vmcnt(3)
	ds_write_b128 v1, v[156:159] offset:32256
	ds_write_b128 v1, v[76:79] offset:55296
	s_waitcnt vmcnt(2)
	ds_write_b128 v1, v[160:163] offset:59904
	s_waitcnt vmcnt(1)
	ds_write_b128 v1, v[84:87] offset:64512
	s_waitcnt vmcnt(0)
	ds_write_b128 v92, v[88:91] offset:32256
	s_waitcnt lgkmcnt(0)
	s_barrier
	v_mfma_f32_32x32x16_bf16 v[34:49], v[164:167], v[168:171], v[34:49]
	v_mfma_f32_32x32x16_bf16 v[50:65], v[164:167], v[180:183], v[50:65]
	v_mfma_f32_32x32x16_bf16 v[2:17], v[172:175], v[176:179], v[2:17]
	v_mfma_f32_32x32x16_bf16 v[18:33], v[172:175], v[184:187], v[18:33]
	v_mfma_f32_32x32x16_bf16 v[34:49], v[188:191], v[176:179], v[34:49]
	v_mfma_f32_32x32x16_bf16 v[50:65], v[188:191], v[184:187], v[50:65]
	ds_read_b128 v[76:79], v66 offset:18432
	ds_read_b128 v[80:83], v67 offset:55296
	ds_read_b128 v[84:87], v66 offset:18464
	ds_read_b128 v[88:91], v67 offset:55328
	ds_read_b128 v[148:151], v67 offset:59904
	ds_read_b128 v[152:155], v67 offset:59936
	v_or_b32_e32 v68, s8, v94
	s_waitcnt lgkmcnt(4)
	v_mfma_f32_32x32x16_bf16 v[2:17], v[76:79], v[80:83], v[2:17]
	s_lshl_b32 s10, s10, 1
	s_mov_b32 s11, s9
	s_add_i32 s12, s12, s13
	s_add_i32 s14, s14, s15
	s_add_i32 s16, s16, s17
	s_cmpk_lt_u32 s12, 0x400
	s_waitcnt lgkmcnt(1)
	v_mfma_f32_32x32x16_bf16 v[18:33], v[76:79], v[148:151], v[18:33]
	ds_read_b128 v[76:79], v66 offset:23040
	ds_read_b128 v[156:159], v66 offset:23072
	s_waitcnt lgkmcnt(1)
	v_mfma_f32_32x32x16_bf16 v[34:49], v[76:79], v[80:83], v[34:49]
	v_mfma_f32_32x32x16_bf16 v[50:65], v[76:79], v[148:151], v[50:65]
	v_mfma_f32_32x32x16_bf16 v[2:17], v[84:87], v[88:91], v[2:17]
	v_mfma_f32_32x32x16_bf16 v[18:33], v[84:87], v[152:155], v[18:33]
	s_waitcnt lgkmcnt(0)
	v_mfma_f32_32x32x16_bf16 v[34:49], v[156:159], v[88:91], v[34:49]
	ds_read_b128 v[76:79], v66 offset:18496
	ds_read_b128 v[80:83], v67 offset:55360
	ds_read_b128 v[84:87], v66 offset:18528
	ds_read_b128 v[88:91], v67 offset:55392
	v_mfma_f32_32x32x16_bf16 v[50:65], v[156:159], v[152:155], v[50:65]
	ds_read_b128 v[148:151], v67 offset:59968
	ds_read_b128 v[152:155], v67 offset:60000
	s_waitcnt lgkmcnt(4)
	v_mfma_f32_32x32x16_bf16 v[2:17], v[76:79], v[80:83], v[2:17]
	s_waitcnt lgkmcnt(1)
	v_mfma_f32_32x32x16_bf16 v[18:33], v[76:79], v[148:151], v[18:33]
	ds_read_b128 v[76:79], v66 offset:23104
	ds_read_b128 v[156:159], v66 offset:23136
	s_waitcnt lgkmcnt(0)
	s_barrier
	v_mfma_f32_32x32x16_bf16 v[34:49], v[76:79], v[80:83], v[34:49]
	v_mfma_f32_32x32x16_bf16 v[50:65], v[76:79], v[148:151], v[50:65]
	v_mfma_f32_32x32x16_bf16 v[2:17], v[84:87], v[88:91], v[2:17]
	v_mfma_f32_32x32x16_bf16 v[18:33], v[84:87], v[152:155], v[18:33]
	v_mfma_f32_32x32x16_bf16 v[34:49], v[156:159], v[88:91], v[34:49]
	s_nop 10
	ds_write2_b32 v93, v2, v18 offset1:32
	v_mfma_f32_32x32x16_bf16 v[50:65], v[156:159], v[152:155], v[50:65]
	s_nop 11
	ds_write2_b32 v132, v34, v50 offset0:32 offset1:64
	ds_write2_b32 v93, v3, v19 offset0:129 offset1:161
	ds_write2_b32 v132, v35, v51 offset0:161 offset1:193
	ds_write2_b32 v133, v4, v20 offset0:2 offset1:34
	ds_write2_b32 v134, v36, v52 offset0:34 offset1:66
	ds_write2_b32 v133, v5, v21 offset0:131 offset1:163
	ds_write2_b32 v134, v37, v53 offset0:163 offset1:195
	ds_write2_b32 v135, v6, v22 offset0:8 offset1:40
	ds_write2_b32 v136, v38, v54 offset0:40 offset1:72
	ds_write2_b32 v135, v7, v23 offset0:137 offset1:169
	ds_write2_b32 v136, v39, v55 offset0:169 offset1:201
	ds_write2_b32 v137, v8, v24 offset0:10 offset1:42
	ds_write2_b32 v138, v40, v56 offset0:42 offset1:74
	ds_write2_b32 v137, v9, v25 offset0:139 offset1:171
	ds_write2_b32 v138, v41, v57 offset0:171 offset1:203
	ds_write2_b32 v139, v10, v26 offset0:16 offset1:48
	ds_write2_b32 v140, v42, v58 offset0:48 offset1:80
	ds_write2_b32 v139, v11, v27 offset0:145 offset1:177
	ds_write2_b32 v140, v43, v59 offset0:177 offset1:209
	ds_write2_b32 v141, v12, v28 offset0:18 offset1:50
	ds_write2_b32 v142, v44, v60 offset0:50 offset1:82
	ds_write2_b32 v141, v13, v29 offset0:147 offset1:179
	ds_write2_b32 v142, v45, v61 offset0:179 offset1:211
	ds_write2_b32 v143, v14, v30 offset0:24 offset1:56
	ds_write2_b32 v144, v46, v62 offset0:56 offset1:88
	ds_write2_b32 v143, v15, v31 offset0:153 offset1:185
	ds_write2_b32 v144, v47, v63 offset0:185 offset1:217
	ds_write2_b32 v145, v16, v32 offset0:26 offset1:58
	ds_write2_b32 v146, v48, v64 offset0:58 offset1:90
	ds_write2_b32 v145, v17, v33 offset0:155 offset1:187
	ds_write2_b32 v146, v49, v65 offset0:187 offset1:219
	v_lshl_add_u64 v[2:3], v[68:69], 2, s[6:7]
	s_waitcnt lgkmcnt(0)
	s_barrier
	v_and_b32_e32 v230, 0x3ff, v0
	v_and_b32_e32 v231, 63, v230
	v_lshrrev_b32_e32 v232, 6, v230
	v_and_b32_e32 v233, 7, v231
	v_and_b32_e32 v234, 1, v232
	v_lshl_add_u32 v233, v234, 3, v233
	v_lshrrev_b32_e32 v235, 3, v231
	v_lshrrev_b32_e32 v234, 1, v232
	v_lshl_add_u32 v235, v234, 3, v235
	v_lshrrev_b32_e32 v234, 4, v230
	v_sub_u32_e32 v236, v68, v234
	v_add_u32_e32 v236, v236, v233
	v_mul_u32_u24_e32 v237, 0x204, v233
	v_lshl_add_u32 v237, v235, 5, v237
	v_lshlrev_b32_e32 v238, 4, v235
	v_mov_b32_e32 v2, v236
	v_lshlrev_b32_e32 v3, 2, v2
	global_load_dword v5, v3, s[6:7]
	global_load_dword v6, v3, s[6:7] offset:64
	global_load_dword v7, v3, s[6:7] offset:128
	global_load_dword v8, v3, s[6:7] offset:192
	global_load_dword v9, v3, s[6:7] offset:256
	global_load_dword v10, v3, s[6:7] offset:320
	global_load_dword v11, v3, s[6:7] offset:384
	global_load_dword v12, v3, s[6:7] offset:448
	v_lshlrev_b32_e32 v4, 13, v2
	v_add3_u32 v4, v4, v238, s10
	s_movk_i32 s24, 0x7fff
	v_mov_b32_e32 v59, 1
	v_mov_b32_e32 v13, 0x358637bd
	ds_read2_b32 v[14:15], v237 offset0:0 offset1:1
	ds_read2_b32 v[16:17], v237 offset0:2 offset1:3
	ds_read2_b32 v[18:19], v237 offset0:4 offset1:5
	ds_read2_b32 v[20:21], v237 offset0:6 offset1:7
	v_add_u32_e32 v56, 0x2040, v237
	ds_read2_b32 v[22:23], v56 offset0:0 offset1:1
	ds_read2_b32 v[24:25], v56 offset0:2 offset1:3
	ds_read2_b32 v[26:27], v56 offset0:4 offset1:5
	ds_read2_b32 v[28:29], v56 offset0:6 offset1:7
	s_waitcnt vmcnt(7) lgkmcnt(4)
	v_fmamk_f32 v54, v5, 0x3a800000, v13
	v_rsq_f32_e32 v54, v54
	s_nop 0
	v_mul_f32_e32 v14, v14, v54
	v_mul_f32_e32 v15, v15, v54
	v_mul_f32_e32 v16, v16, v54
	v_mul_f32_e32 v17, v17, v54
	v_mul_f32_e32 v18, v18, v54
	v_mul_f32_e32 v19, v19, v54
	v_mul_f32_e32 v20, v20, v54
	v_mul_f32_e32 v21, v21, v54
	v_max_f32_e32 v14, 0, v14
	v_max_f32_e32 v15, 0, v15
	v_max_f32_e32 v16, 0, v16
	v_max_f32_e32 v17, 0, v17
	v_max_f32_e32 v18, 0, v18
	v_max_f32_e32 v19, 0, v19
	v_max_f32_e32 v20, 0, v20
	v_max_f32_e32 v21, 0, v21
	v_pk_mul_f32 v[14:15], v[14:15], v[14:15]
	v_pk_mul_f32 v[16:17], v[16:17], v[16:17]
	v_pk_mul_f32 v[18:19], v[18:19], v[18:19]
	v_pk_mul_f32 v[20:21], v[20:21], v[20:21]
	v_and_b32_sdwa v46, v14, v59 dst_sel:DWORD dst_unused:UNUSED_PAD src0_sel:WORD_1 src1_sel:DWORD
	v_and_b32_sdwa v47, v15, v59 dst_sel:DWORD dst_unused:UNUSED_PAD src0_sel:WORD_1 src1_sel:DWORD
	v_and_b32_sdwa v48, v16, v59 dst_sel:DWORD dst_unused:UNUSED_PAD src0_sel:WORD_1 src1_sel:DWORD
	v_and_b32_sdwa v49, v17, v59 dst_sel:DWORD dst_unused:UNUSED_PAD src0_sel:WORD_1 src1_sel:DWORD
	v_and_b32_sdwa v50, v18, v59 dst_sel:DWORD dst_unused:UNUSED_PAD src0_sel:WORD_1 src1_sel:DWORD
	v_and_b32_sdwa v51, v19, v59 dst_sel:DWORD dst_unused:UNUSED_PAD src0_sel:WORD_1 src1_sel:DWORD
	v_and_b32_sdwa v52, v20, v59 dst_sel:DWORD dst_unused:UNUSED_PAD src0_sel:WORD_1 src1_sel:DWORD
	v_and_b32_sdwa v53, v21, v59 dst_sel:DWORD dst_unused:UNUSED_PAD src0_sel:WORD_1 src1_sel:DWORD
	v_add3_u32 v14, v14, v46, s24
	v_add3_u32 v15, v15, v47, s24
	v_add3_u32 v16, v16, v48, s24
	v_add3_u32 v17, v17, v49, s24
	v_add3_u32 v18, v18, v50, s24
	v_add3_u32 v19, v19, v51, s24
	v_add3_u32 v20, v20, v52, s24
	v_add3_u32 v21, v21, v53, s24
	v_and_b32_e32 v15, 0xffff0000, v15
	v_and_b32_e32 v17, 0xffff0000, v17
	v_and_b32_e32 v19, 0xffff0000, v19
	v_and_b32_e32 v21, 0xffff0000, v21
	v_or_b32_sdwa v60, v15, v14 dst_sel:DWORD dst_unused:UNUSED_PAD src0_sel:DWORD src1_sel:WORD_1
	v_or_b32_sdwa v61, v17, v16 dst_sel:DWORD dst_unused:UNUSED_PAD src0_sel:DWORD src1_sel:WORD_1
	v_or_b32_sdwa v62, v19, v18 dst_sel:DWORD dst_unused:UNUSED_PAD src0_sel:DWORD src1_sel:WORD_1
	v_or_b32_sdwa v63, v21, v20 dst_sel:DWORD dst_unused:UNUSED_PAD src0_sel:DWORD src1_sel:WORD_1
	global_store_dwordx4 v4, v[60:63], s[56:57]
	v_add_u32_e32 v55, 0x4080, v237
	ds_read2_b32 v[30:31], v55 offset0:0 offset1:1
	ds_read2_b32 v[32:33], v55 offset0:2 offset1:3
	ds_read2_b32 v[34:35], v55 offset0:4 offset1:5
	ds_read2_b32 v[36:37], v55 offset0:6 offset1:7
	v_add_u32_e32 v56, 0x60c0, v237
	ds_read2_b32 v[38:39], v56 offset0:0 offset1:1
	ds_read2_b32 v[40:41], v56 offset0:2 offset1:3
	ds_read2_b32 v[42:43], v56 offset0:4 offset1:5
	ds_read2_b32 v[44:45], v56 offset0:6 offset1:7
	s_waitcnt vmcnt(7) lgkmcnt(8)
	v_fmamk_f32 v54, v6, 0x3a800000, v13
	v_rsq_f32_e32 v54, v54
	v_add_u32_e32 v58, 0x20000, v4
	v_mul_f32_e32 v22, v22, v54
	v_mul_f32_e32 v23, v23, v54
	v_mul_f32_e32 v24, v24, v54
	v_mul_f32_e32 v25, v25, v54
	v_mul_f32_e32 v26, v26, v54
	v_mul_f32_e32 v27, v27, v54
	v_mul_f32_e32 v28, v28, v54
	v_mul_f32_e32 v29, v29, v54
	v_max_f32_e32 v22, 0, v22
	v_max_f32_e32 v23, 0, v23
	v_max_f32_e32 v24, 0, v24
	v_max_f32_e32 v25, 0, v25
	v_max_f32_e32 v26, 0, v26
	v_max_f32_e32 v27, 0, v27
	v_max_f32_e32 v28, 0, v28
	v_max_f32_e32 v29, 0, v29
	v_pk_mul_f32 v[22:23], v[22:23], v[22:23]
	v_pk_mul_f32 v[24:25], v[24:25], v[24:25]
	v_pk_mul_f32 v[26:27], v[26:27], v[26:27]
	v_pk_mul_f32 v[28:29], v[28:29], v[28:29]
	v_and_b32_sdwa v46, v22, v59 dst_sel:DWORD dst_unused:UNUSED_PAD src0_sel:WORD_1 src1_sel:DWORD
	v_and_b32_sdwa v47, v23, v59 dst_sel:DWORD dst_unused:UNUSED_PAD src0_sel:WORD_1 src1_sel:DWORD
	v_and_b32_sdwa v48, v24, v59 dst_sel:DWORD dst_unused:UNUSED_PAD src0_sel:WORD_1 src1_sel:DWORD
	v_and_b32_sdwa v49, v25, v59 dst_sel:DWORD dst_unused:UNUSED_PAD src0_sel:WORD_1 src1_sel:DWORD
	v_and_b32_sdwa v50, v26, v59 dst_sel:DWORD dst_unused:UNUSED_PAD src0_sel:WORD_1 src1_sel:DWORD
	v_and_b32_sdwa v51, v27, v59 dst_sel:DWORD dst_unused:UNUSED_PAD src0_sel:WORD_1 src1_sel:DWORD
	v_and_b32_sdwa v52, v28, v59 dst_sel:DWORD dst_unused:UNUSED_PAD src0_sel:WORD_1 src1_sel:DWORD
	v_and_b32_sdwa v53, v29, v59 dst_sel:DWORD dst_unused:UNUSED_PAD src0_sel:WORD_1 src1_sel:DWORD
	v_add3_u32 v22, v22, v46, s24
	v_add3_u32 v23, v23, v47, s24
	v_add3_u32 v24, v24, v48, s24
	v_add3_u32 v25, v25, v49, s24
	v_add3_u32 v26, v26, v50, s24
	v_add3_u32 v27, v27, v51, s24
	v_add3_u32 v28, v28, v52, s24
	v_add3_u32 v29, v29, v53, s24
	v_and_b32_e32 v23, 0xffff0000, v23
	v_and_b32_e32 v25, 0xffff0000, v25
	v_and_b32_e32 v27, 0xffff0000, v27
	v_and_b32_e32 v29, 0xffff0000, v29
	v_or_b32_sdwa v76, v23, v22 dst_sel:DWORD dst_unused:UNUSED_PAD src0_sel:DWORD src1_sel:WORD_1
	v_or_b32_sdwa v77, v25, v24 dst_sel:DWORD dst_unused:UNUSED_PAD src0_sel:DWORD src1_sel:WORD_1
	v_or_b32_sdwa v78, v27, v26 dst_sel:DWORD dst_unused:UNUSED_PAD src0_sel:DWORD src1_sel:WORD_1
	v_or_b32_sdwa v79, v29, v28 dst_sel:DWORD dst_unused:UNUSED_PAD src0_sel:DWORD src1_sel:WORD_1
	global_store_dwordx4 v58, v[76:79], s[56:57]
	s_waitcnt vmcnt(7) lgkmcnt(4)
	v_fmamk_f32 v54, v7, 0x3a800000, v13
	v_rsq_f32_e32 v54, v54
	v_add_u32_e32 v57, 0x40000, v4
	v_mul_f32_e32 v30, v30, v54
	v_mul_f32_e32 v31, v31, v54
	v_mul_f32_e32 v32, v32, v54
	v_mul_f32_e32 v33, v33, v54
	v_mul_f32_e32 v34, v34, v54
	v_mul_f32_e32 v35, v35, v54
	v_mul_f32_e32 v36, v36, v54
	v_mul_f32_e32 v37, v37, v54
	v_max_f32_e32 v30, 0, v30
	v_max_f32_e32 v31, 0, v31
	v_max_f32_e32 v32, 0, v32
	v_max_f32_e32 v33, 0, v33
	v_max_f32_e32 v34, 0, v34
	v_max_f32_e32 v35, 0, v35
	v_max_f32_e32 v36, 0, v36
	v_max_f32_e32 v37, 0, v37
	v_pk_mul_f32 v[30:31], v[30:31], v[30:31]
	v_pk_mul_f32 v[32:33], v[32:33], v[32:33]
	v_pk_mul_f32 v[34:35], v[34:35], v[34:35]
	v_pk_mul_f32 v[36:37], v[36:37], v[36:37]
	v_and_b32_sdwa v46, v30, v59 dst_sel:DWORD dst_unused:UNUSED_PAD src0_sel:WORD_1 src1_sel:DWORD
	v_and_b32_sdwa v47, v31, v59 dst_sel:DWORD dst_unused:UNUSED_PAD src0_sel:WORD_1 src1_sel:DWORD
	v_and_b32_sdwa v48, v32, v59 dst_sel:DWORD dst_unused:UNUSED_PAD src0_sel:WORD_1 src1_sel:DWORD
	v_and_b32_sdwa v49, v33, v59 dst_sel:DWORD dst_unused:UNUSED_PAD src0_sel:WORD_1 src1_sel:DWORD
	v_and_b32_sdwa v50, v34, v59 dst_sel:DWORD dst_unused:UNUSED_PAD src0_sel:WORD_1 src1_sel:DWORD
	v_and_b32_sdwa v51, v35, v59 dst_sel:DWORD dst_unused:UNUSED_PAD src0_sel:WORD_1 src1_sel:DWORD
	v_and_b32_sdwa v52, v36, v59 dst_sel:DWORD dst_unused:UNUSED_PAD src0_sel:WORD_1 src1_sel:DWORD
	v_and_b32_sdwa v53, v37, v59 dst_sel:DWORD dst_unused:UNUSED_PAD src0_sel:WORD_1 src1_sel:DWORD
	v_add3_u32 v30, v30, v46, s24
	v_add3_u32 v31, v31, v47, s24
	v_add3_u32 v32, v32, v48, s24
	v_add3_u32 v33, v33, v49, s24
	v_add3_u32 v34, v34, v50, s24
	v_add3_u32 v35, v35, v51, s24
	v_add3_u32 v36, v36, v52, s24
	v_add3_u32 v37, v37, v53, s24
	v_and_b32_e32 v31, 0xffff0000, v31
	v_and_b32_e32 v33, 0xffff0000, v33
	v_and_b32_e32 v35, 0xffff0000, v35
	v_and_b32_e32 v37, 0xffff0000, v37
	v_or_b32_sdwa v60, v31, v30 dst_sel:DWORD dst_unused:UNUSED_PAD src0_sel:DWORD src1_sel:WORD_1
	v_or_b32_sdwa v61, v33, v32 dst_sel:DWORD dst_unused:UNUSED_PAD src0_sel:DWORD src1_sel:WORD_1
	v_or_b32_sdwa v62, v35, v34 dst_sel:DWORD dst_unused:UNUSED_PAD src0_sel:DWORD src1_sel:WORD_1
	v_or_b32_sdwa v63, v37, v36 dst_sel:DWORD dst_unused:UNUSED_PAD src0_sel:DWORD src1_sel:WORD_1
	global_store_dwordx4 v57, v[60:63], s[56:57]
	v_add_u32_e32 v55, 0x8100, v237
	ds_read2_b32 v[14:15], v55 offset0:0 offset1:1
	ds_read2_b32 v[16:17], v55 offset0:2 offset1:3
	ds_read2_b32 v[18:19], v55 offset0:4 offset1:5
	ds_read2_b32 v[20:21], v55 offset0:6 offset1:7
	v_add_u32_e32 v56, 0xa140, v237
	ds_read2_b32 v[22:23], v56 offset0:0 offset1:1
	ds_read2_b32 v[24:25], v56 offset0:2 offset1:3
	ds_read2_b32 v[26:27], v56 offset0:4 offset1:5
	ds_read2_b32 v[28:29], v56 offset0:6 offset1:7
	s_waitcnt vmcnt(7) lgkmcnt(8)
	v_fmamk_f32 v54, v8, 0x3a800000, v13
	v_rsq_f32_e32 v54, v54
	v_add_u32_e32 v58, 0x60000, v4
	v_mul_f32_e32 v38, v38, v54
	v_mul_f32_e32 v39, v39, v54
	v_mul_f32_e32 v40, v40, v54
	v_mul_f32_e32 v41, v41, v54
	v_mul_f32_e32 v42, v42, v54
	v_mul_f32_e32 v43, v43, v54
	v_mul_f32_e32 v44, v44, v54
	v_mul_f32_e32 v45, v45, v54
	v_max_f32_e32 v38, 0, v38
	v_max_f32_e32 v39, 0, v39
	v_max_f32_e32 v40, 0, v40
	v_max_f32_e32 v41, 0, v41
	v_max_f32_e32 v42, 0, v42
	v_max_f32_e32 v43, 0, v43
	v_max_f32_e32 v44, 0, v44
	v_max_f32_e32 v45, 0, v45
	v_pk_mul_f32 v[38:39], v[38:39], v[38:39]
	v_pk_mul_f32 v[40:41], v[40:41], v[40:41]
	v_pk_mul_f32 v[42:43], v[42:43], v[42:43]
	v_pk_mul_f32 v[44:45], v[44:45], v[44:45]
	v_and_b32_sdwa v46, v38, v59 dst_sel:DWORD dst_unused:UNUSED_PAD src0_sel:WORD_1 src1_sel:DWORD
	v_and_b32_sdwa v47, v39, v59 dst_sel:DWORD dst_unused:UNUSED_PAD src0_sel:WORD_1 src1_sel:DWORD
	v_and_b32_sdwa v48, v40, v59 dst_sel:DWORD dst_unused:UNUSED_PAD src0_sel:WORD_1 src1_sel:DWORD
	v_and_b32_sdwa v49, v41, v59 dst_sel:DWORD dst_unused:UNUSED_PAD src0_sel:WORD_1 src1_sel:DWORD
	v_and_b32_sdwa v50, v42, v59 dst_sel:DWORD dst_unused:UNUSED_PAD src0_sel:WORD_1 src1_sel:DWORD
	v_and_b32_sdwa v51, v43, v59 dst_sel:DWORD dst_unused:UNUSED_PAD src0_sel:WORD_1 src1_sel:DWORD
	v_and_b32_sdwa v52, v44, v59 dst_sel:DWORD dst_unused:UNUSED_PAD src0_sel:WORD_1 src1_sel:DWORD
	v_and_b32_sdwa v53, v45, v59 dst_sel:DWORD dst_unused:UNUSED_PAD src0_sel:WORD_1 src1_sel:DWORD
	v_add3_u32 v38, v38, v46, s24
	v_add3_u32 v39, v39, v47, s24
	v_add3_u32 v40, v40, v48, s24
	v_add3_u32 v41, v41, v49, s24
	v_add3_u32 v42, v42, v50, s24
	v_add3_u32 v43, v43, v51, s24
	v_add3_u32 v44, v44, v52, s24
	v_add3_u32 v45, v45, v53, s24
	v_and_b32_e32 v39, 0xffff0000, v39
	v_and_b32_e32 v41, 0xffff0000, v41
	v_and_b32_e32 v43, 0xffff0000, v43
	v_and_b32_e32 v45, 0xffff0000, v45
	v_or_b32_sdwa v76, v39, v38 dst_sel:DWORD dst_unused:UNUSED_PAD src0_sel:DWORD src1_sel:WORD_1
	v_or_b32_sdwa v77, v41, v40 dst_sel:DWORD dst_unused:UNUSED_PAD src0_sel:DWORD src1_sel:WORD_1
	v_or_b32_sdwa v78, v43, v42 dst_sel:DWORD dst_unused:UNUSED_PAD src0_sel:DWORD src1_sel:WORD_1
	v_or_b32_sdwa v79, v45, v44 dst_sel:DWORD dst_unused:UNUSED_PAD src0_sel:DWORD src1_sel:WORD_1
	global_store_dwordx4 v58, v[76:79], s[56:57]
	s_waitcnt vmcnt(7) lgkmcnt(4)
	v_fmamk_f32 v54, v9, 0x3a800000, v13
	v_rsq_f32_e32 v54, v54
	v_add_u32_e32 v57, 0x80000, v4
	v_mul_f32_e32 v14, v14, v54
	v_mul_f32_e32 v15, v15, v54
	v_mul_f32_e32 v16, v16, v54
	v_mul_f32_e32 v17, v17, v54
	v_mul_f32_e32 v18, v18, v54
	v_mul_f32_e32 v19, v19, v54
	v_mul_f32_e32 v20, v20, v54
	v_mul_f32_e32 v21, v21, v54
	v_max_f32_e32 v14, 0, v14
	v_max_f32_e32 v15, 0, v15
	v_max_f32_e32 v16, 0, v16
	v_max_f32_e32 v17, 0, v17
	v_max_f32_e32 v18, 0, v18
	v_max_f32_e32 v19, 0, v19
	v_max_f32_e32 v20, 0, v20
	v_max_f32_e32 v21, 0, v21
	v_pk_mul_f32 v[14:15], v[14:15], v[14:15]
	v_pk_mul_f32 v[16:17], v[16:17], v[16:17]
	v_pk_mul_f32 v[18:19], v[18:19], v[18:19]
	v_pk_mul_f32 v[20:21], v[20:21], v[20:21]
	v_and_b32_sdwa v46, v14, v59 dst_sel:DWORD dst_unused:UNUSED_PAD src0_sel:WORD_1 src1_sel:DWORD
	v_and_b32_sdwa v47, v15, v59 dst_sel:DWORD dst_unused:UNUSED_PAD src0_sel:WORD_1 src1_sel:DWORD
	v_and_b32_sdwa v48, v16, v59 dst_sel:DWORD dst_unused:UNUSED_PAD src0_sel:WORD_1 src1_sel:DWORD
	v_and_b32_sdwa v49, v17, v59 dst_sel:DWORD dst_unused:UNUSED_PAD src0_sel:WORD_1 src1_sel:DWORD
	v_and_b32_sdwa v50, v18, v59 dst_sel:DWORD dst_unused:UNUSED_PAD src0_sel:WORD_1 src1_sel:DWORD
	v_and_b32_sdwa v51, v19, v59 dst_sel:DWORD dst_unused:UNUSED_PAD src0_sel:WORD_1 src1_sel:DWORD
	v_and_b32_sdwa v52, v20, v59 dst_sel:DWORD dst_unused:UNUSED_PAD src0_sel:WORD_1 src1_sel:DWORD
	v_and_b32_sdwa v53, v21, v59 dst_sel:DWORD dst_unused:UNUSED_PAD src0_sel:WORD_1 src1_sel:DWORD
	v_add3_u32 v14, v14, v46, s24
	v_add3_u32 v15, v15, v47, s24
	v_add3_u32 v16, v16, v48, s24
	v_add3_u32 v17, v17, v49, s24
	v_add3_u32 v18, v18, v50, s24
	v_add3_u32 v19, v19, v51, s24
	v_add3_u32 v20, v20, v52, s24
	v_add3_u32 v21, v21, v53, s24
	v_and_b32_e32 v15, 0xffff0000, v15
	v_and_b32_e32 v17, 0xffff0000, v17
	v_and_b32_e32 v19, 0xffff0000, v19
	v_and_b32_e32 v21, 0xffff0000, v21
	v_or_b32_sdwa v60, v15, v14 dst_sel:DWORD dst_unused:UNUSED_PAD src0_sel:DWORD src1_sel:WORD_1
	v_or_b32_sdwa v61, v17, v16 dst_sel:DWORD dst_unused:UNUSED_PAD src0_sel:DWORD src1_sel:WORD_1
	v_or_b32_sdwa v62, v19, v18 dst_sel:DWORD dst_unused:UNUSED_PAD src0_sel:DWORD src1_sel:WORD_1
	v_or_b32_sdwa v63, v21, v20 dst_sel:DWORD dst_unused:UNUSED_PAD src0_sel:DWORD src1_sel:WORD_1
	global_store_dwordx4 v57, v[60:63], s[56:57]
	v_add_u32_e32 v55, 0xc180, v237
	ds_read2_b32 v[30:31], v55 offset0:0 offset1:1
	ds_read2_b32 v[32:33], v55 offset0:2 offset1:3
	ds_read2_b32 v[34:35], v55 offset0:4 offset1:5
	ds_read2_b32 v[36:37], v55 offset0:6 offset1:7
	v_add_u32_e32 v56, 0xe1c0, v237
	ds_read2_b32 v[38:39], v56 offset0:0 offset1:1
	ds_read2_b32 v[40:41], v56 offset0:2 offset1:3
	ds_read2_b32 v[42:43], v56 offset0:4 offset1:5
	ds_read2_b32 v[44:45], v56 offset0:6 offset1:7
	s_waitcnt vmcnt(7) lgkmcnt(8)
	v_fmamk_f32 v54, v10, 0x3a800000, v13
	v_rsq_f32_e32 v54, v54
	v_add_u32_e32 v58, 0xa0000, v4
	v_mul_f32_e32 v22, v22, v54
	v_mul_f32_e32 v23, v23, v54
	v_mul_f32_e32 v24, v24, v54
	v_mul_f32_e32 v25, v25, v54
	v_mul_f32_e32 v26, v26, v54
	v_mul_f32_e32 v27, v27, v54
	v_mul_f32_e32 v28, v28, v54
	v_mul_f32_e32 v29, v29, v54
	v_max_f32_e32 v22, 0, v22
	v_max_f32_e32 v23, 0, v23
	v_max_f32_e32 v24, 0, v24
	v_max_f32_e32 v25, 0, v25
	v_max_f32_e32 v26, 0, v26
	v_max_f32_e32 v27, 0, v27
	v_max_f32_e32 v28, 0, v28
	v_max_f32_e32 v29, 0, v29
	v_pk_mul_f32 v[22:23], v[22:23], v[22:23]
	v_pk_mul_f32 v[24:25], v[24:25], v[24:25]
	v_pk_mul_f32 v[26:27], v[26:27], v[26:27]
	v_pk_mul_f32 v[28:29], v[28:29], v[28:29]
	v_and_b32_sdwa v46, v22, v59 dst_sel:DWORD dst_unused:UNUSED_PAD src0_sel:WORD_1 src1_sel:DWORD
	v_and_b32_sdwa v47, v23, v59 dst_sel:DWORD dst_unused:UNUSED_PAD src0_sel:WORD_1 src1_sel:DWORD
	v_and_b32_sdwa v48, v24, v59 dst_sel:DWORD dst_unused:UNUSED_PAD src0_sel:WORD_1 src1_sel:DWORD
	v_and_b32_sdwa v49, v25, v59 dst_sel:DWORD dst_unused:UNUSED_PAD src0_sel:WORD_1 src1_sel:DWORD
	v_and_b32_sdwa v50, v26, v59 dst_sel:DWORD dst_unused:UNUSED_PAD src0_sel:WORD_1 src1_sel:DWORD
	v_and_b32_sdwa v51, v27, v59 dst_sel:DWORD dst_unused:UNUSED_PAD src0_sel:WORD_1 src1_sel:DWORD
	v_and_b32_sdwa v52, v28, v59 dst_sel:DWORD dst_unused:UNUSED_PAD src0_sel:WORD_1 src1_sel:DWORD
	v_and_b32_sdwa v53, v29, v59 dst_sel:DWORD dst_unused:UNUSED_PAD src0_sel:WORD_1 src1_sel:DWORD
	v_add3_u32 v22, v22, v46, s24
	v_add3_u32 v23, v23, v47, s24
	v_add3_u32 v24, v24, v48, s24
	v_add3_u32 v25, v25, v49, s24
	v_add3_u32 v26, v26, v50, s24
	v_add3_u32 v27, v27, v51, s24
	v_add3_u32 v28, v28, v52, s24
	v_add3_u32 v29, v29, v53, s24
	v_and_b32_e32 v23, 0xffff0000, v23
	v_and_b32_e32 v25, 0xffff0000, v25
	v_and_b32_e32 v27, 0xffff0000, v27
	v_and_b32_e32 v29, 0xffff0000, v29
	v_or_b32_sdwa v76, v23, v22 dst_sel:DWORD dst_unused:UNUSED_PAD src0_sel:DWORD src1_sel:WORD_1
	v_or_b32_sdwa v77, v25, v24 dst_sel:DWORD dst_unused:UNUSED_PAD src0_sel:DWORD src1_sel:WORD_1
	v_or_b32_sdwa v78, v27, v26 dst_sel:DWORD dst_unused:UNUSED_PAD src0_sel:DWORD src1_sel:WORD_1
	v_or_b32_sdwa v79, v29, v28 dst_sel:DWORD dst_unused:UNUSED_PAD src0_sel:DWORD src1_sel:WORD_1
	global_store_dwordx4 v58, v[76:79], s[56:57]
	s_waitcnt vmcnt(7) lgkmcnt(4)
	v_fmamk_f32 v54, v11, 0x3a800000, v13
	v_rsq_f32_e32 v54, v54
	v_add_u32_e32 v57, 0xc0000, v4
	v_mul_f32_e32 v30, v30, v54
	v_mul_f32_e32 v31, v31, v54
	v_mul_f32_e32 v32, v32, v54
	v_mul_f32_e32 v33, v33, v54
	v_mul_f32_e32 v34, v34, v54
	v_mul_f32_e32 v35, v35, v54
	v_mul_f32_e32 v36, v36, v54
	v_mul_f32_e32 v37, v37, v54
	v_max_f32_e32 v30, 0, v30
	v_max_f32_e32 v31, 0, v31
	v_max_f32_e32 v32, 0, v32
	v_max_f32_e32 v33, 0, v33
	v_max_f32_e32 v34, 0, v34
	v_max_f32_e32 v35, 0, v35
	v_max_f32_e32 v36, 0, v36
	v_max_f32_e32 v37, 0, v37
	v_pk_mul_f32 v[30:31], v[30:31], v[30:31]
	v_pk_mul_f32 v[32:33], v[32:33], v[32:33]
	v_pk_mul_f32 v[34:35], v[34:35], v[34:35]
	v_pk_mul_f32 v[36:37], v[36:37], v[36:37]
	v_and_b32_sdwa v46, v30, v59 dst_sel:DWORD dst_unused:UNUSED_PAD src0_sel:WORD_1 src1_sel:DWORD
	v_and_b32_sdwa v47, v31, v59 dst_sel:DWORD dst_unused:UNUSED_PAD src0_sel:WORD_1 src1_sel:DWORD
	v_and_b32_sdwa v48, v32, v59 dst_sel:DWORD dst_unused:UNUSED_PAD src0_sel:WORD_1 src1_sel:DWORD
	v_and_b32_sdwa v49, v33, v59 dst_sel:DWORD dst_unused:UNUSED_PAD src0_sel:WORD_1 src1_sel:DWORD
	v_and_b32_sdwa v50, v34, v59 dst_sel:DWORD dst_unused:UNUSED_PAD src0_sel:WORD_1 src1_sel:DWORD
	v_and_b32_sdwa v51, v35, v59 dst_sel:DWORD dst_unused:UNUSED_PAD src0_sel:WORD_1 src1_sel:DWORD
	v_and_b32_sdwa v52, v36, v59 dst_sel:DWORD dst_unused:UNUSED_PAD src0_sel:WORD_1 src1_sel:DWORD
	v_and_b32_sdwa v53, v37, v59 dst_sel:DWORD dst_unused:UNUSED_PAD src0_sel:WORD_1 src1_sel:DWORD
	v_add3_u32 v30, v30, v46, s24
	v_add3_u32 v31, v31, v47, s24
	v_add3_u32 v32, v32, v48, s24
	v_add3_u32 v33, v33, v49, s24
	v_add3_u32 v34, v34, v50, s24
	v_add3_u32 v35, v35, v51, s24
	v_add3_u32 v36, v36, v52, s24
	v_add3_u32 v37, v37, v53, s24
	v_and_b32_e32 v31, 0xffff0000, v31
	v_and_b32_e32 v33, 0xffff0000, v33
	v_and_b32_e32 v35, 0xffff0000, v35
	v_and_b32_e32 v37, 0xffff0000, v37
	v_or_b32_sdwa v60, v31, v30 dst_sel:DWORD dst_unused:UNUSED_PAD src0_sel:DWORD src1_sel:WORD_1
	v_or_b32_sdwa v61, v33, v32 dst_sel:DWORD dst_unused:UNUSED_PAD src0_sel:DWORD src1_sel:WORD_1
	v_or_b32_sdwa v62, v35, v34 dst_sel:DWORD dst_unused:UNUSED_PAD src0_sel:DWORD src1_sel:WORD_1
	v_or_b32_sdwa v63, v37, v36 dst_sel:DWORD dst_unused:UNUSED_PAD src0_sel:DWORD src1_sel:WORD_1
	global_store_dwordx4 v57, v[60:63], s[56:57]
	s_waitcnt vmcnt(7) lgkmcnt(0)
	v_fmamk_f32 v54, v12, 0x3a800000, v13
	v_rsq_f32_e32 v54, v54
	v_add_u32_e32 v58, 0xe0000, v4
	v_mul_f32_e32 v38, v38, v54
	v_mul_f32_e32 v39, v39, v54
	v_mul_f32_e32 v40, v40, v54
	v_mul_f32_e32 v41, v41, v54
	v_mul_f32_e32 v42, v42, v54
	v_mul_f32_e32 v43, v43, v54
	v_mul_f32_e32 v44, v44, v54
	v_mul_f32_e32 v45, v45, v54
	v_max_f32_e32 v38, 0, v38
	v_max_f32_e32 v39, 0, v39
	v_max_f32_e32 v40, 0, v40
	v_max_f32_e32 v41, 0, v41
	v_max_f32_e32 v42, 0, v42
	v_max_f32_e32 v43, 0, v43
	v_max_f32_e32 v44, 0, v44
	v_max_f32_e32 v45, 0, v45
	v_pk_mul_f32 v[38:39], v[38:39], v[38:39]
	v_pk_mul_f32 v[40:41], v[40:41], v[40:41]
	v_pk_mul_f32 v[42:43], v[42:43], v[42:43]
	v_pk_mul_f32 v[44:45], v[44:45], v[44:45]
	v_and_b32_sdwa v46, v38, v59 dst_sel:DWORD dst_unused:UNUSED_PAD src0_sel:WORD_1 src1_sel:DWORD
	v_and_b32_sdwa v47, v39, v59 dst_sel:DWORD dst_unused:UNUSED_PAD src0_sel:WORD_1 src1_sel:DWORD
	v_and_b32_sdwa v48, v40, v59 dst_sel:DWORD dst_unused:UNUSED_PAD src0_sel:WORD_1 src1_sel:DWORD
	v_and_b32_sdwa v49, v41, v59 dst_sel:DWORD dst_unused:UNUSED_PAD src0_sel:WORD_1 src1_sel:DWORD
	v_and_b32_sdwa v50, v42, v59 dst_sel:DWORD dst_unused:UNUSED_PAD src0_sel:WORD_1 src1_sel:DWORD
	v_and_b32_sdwa v51, v43, v59 dst_sel:DWORD dst_unused:UNUSED_PAD src0_sel:WORD_1 src1_sel:DWORD
	v_and_b32_sdwa v52, v44, v59 dst_sel:DWORD dst_unused:UNUSED_PAD src0_sel:WORD_1 src1_sel:DWORD
	v_and_b32_sdwa v53, v45, v59 dst_sel:DWORD dst_unused:UNUSED_PAD src0_sel:WORD_1 src1_sel:DWORD
	v_add3_u32 v38, v38, v46, s24
	v_add3_u32 v39, v39, v47, s24
	v_add3_u32 v40, v40, v48, s24
	v_add3_u32 v41, v41, v49, s24
	v_add3_u32 v42, v42, v50, s24
	v_add3_u32 v43, v43, v51, s24
	v_add3_u32 v44, v44, v52, s24
	v_add3_u32 v45, v45, v53, s24
	v_and_b32_e32 v39, 0xffff0000, v39
	v_and_b32_e32 v41, 0xffff0000, v41
	v_and_b32_e32 v43, 0xffff0000, v43
	v_and_b32_e32 v45, 0xffff0000, v45
	v_or_b32_sdwa v76, v39, v38 dst_sel:DWORD dst_unused:UNUSED_PAD src0_sel:DWORD src1_sel:WORD_1
	v_or_b32_sdwa v77, v41, v40 dst_sel:DWORD dst_unused:UNUSED_PAD src0_sel:DWORD src1_sel:WORD_1
	v_or_b32_sdwa v78, v43, v42 dst_sel:DWORD dst_unused:UNUSED_PAD src0_sel:DWORD src1_sel:WORD_1
	v_or_b32_sdwa v79, v45, v44 dst_sel:DWORD dst_unused:UNUSED_PAD src0_sel:DWORD src1_sel:WORD_1
	global_store_dwordx4 v58, v[76:79], s[56:57]
	s_cmpk_lt_u32 s12, 0x400
	s_barrier
	s_cbranch_scc1 .LBB0_590
